# GEMM K loops: the second s_waitcnt lgkmcnt(0) at the head of each MFMA segment (already drained before the barrier) removed
# baseline (speedup 1.0000x reference)
.LBB0_179:
	s_add_u32 s29, s56, 0xfffc0080
	s_addc_u32 s30, s57, -1
	s_add_i32 s31, 0, 0x10000
	s_cmp_eq_u32 s28, 12
	s_cselect_b32 s61, s6, s30
	s_cselect_b32 s60, s7, s29
	s_cselect_b32 s59, s24, s27
	s_cselect_b32 s58, s25, s26
	s_add_i32 s29, 0, 0x14000
	v_add_u32_e32 v156, s31, v145
	v_add_u32_e32 v162, s29, v145
	ds_read_b128 v[140:143], v156
	ds_read_b128 v[148:151], v156 offset:1024
	ds_read_b128 v[152:155], v156 offset:2048
	ds_read_b128 v[156:159], v156 offset:3072
	ds_read_b128 v[178:181], v162
	ds_read_b128 v[182:185], v162 offset:1024
	ds_read_b128 v[186:189], v162 offset:2048
	ds_read_b128 v[190:193], v162 offset:3072
	v_lshl_add_u64 v[174:175], s[56:57], 0, v[136:137]
	s_add_i32 m0, s65, 0xc000
	ds_read_b128 v[194:197], v147
	ds_read_b128 v[198:201], v147 offset:1024
	ds_read_b128 v[202:205], v147 offset:2048
	ds_read_b128 v[220:223], v147 offset:3072
	ds_read_b128 v[228:231], v147 offset:4096
	ds_read_b128 v[232:235], v147 offset:5120
	ds_read_b128 v[236:239], v147 offset:6144
	ds_read_b128 v[240:243], v147 offset:7168
	global_load_lds_dwordx4 v[174:175], off
	v_lshl_add_u64 v[174:175], s[56:57], 0, v[138:139]
	s_add_i32 m0, s65, 0xe000
	s_nop 0
	global_load_lds_dwordx4 v[174:175], off
	s_waitcnt vmcnt(8)
	s_waitcnt lgkmcnt(0)
	s_barrier
	s_setprio 1
	v_mfma_f32_16x16x32_bf16 v[124:127], v[140:143], v[194:197], v[124:127]
	v_mfma_f32_16x16x32_bf16 v[120:123], v[152:155], v[194:197], v[120:123]
	v_mfma_f32_16x16x32_bf16 v[108:111], v[140:143], v[202:205], v[108:111]
	v_mfma_f32_16x16x32_bf16 v[104:107], v[152:155], v[202:205], v[104:107]
	v_mfma_f32_16x16x32_bf16 v[92:95], v[140:143], v[228:231], v[92:95]
	v_mfma_f32_16x16x32_bf16 v[88:91], v[152:155], v[228:231], v[88:91]
	v_mfma_f32_16x16x32_bf16 v[76:79], v[140:143], v[236:239], v[76:79]
	v_mfma_f32_16x16x32_bf16 v[72:75], v[152:155], v[236:239], v[72:75]
	v_mfma_f32_16x16x32_bf16 v[124:127], v[148:151], v[198:201], v[124:127]
	v_mfma_f32_16x16x32_bf16 v[120:123], v[156:159], v[198:201], v[120:123]
	v_mfma_f32_16x16x32_bf16 v[108:111], v[148:151], v[220:223], v[108:111]
	v_mfma_f32_16x16x32_bf16 v[104:107], v[156:159], v[220:223], v[104:107]
	v_mfma_f32_16x16x32_bf16 v[92:95], v[148:151], v[232:235], v[92:95]
	v_mfma_f32_16x16x32_bf16 v[88:91], v[156:159], v[232:235], v[88:91]
	v_mfma_f32_16x16x32_bf16 v[76:79], v[148:151], v[240:243], v[76:79]
	v_mfma_f32_16x16x32_bf16 v[72:75], v[156:159], v[240:243], v[72:75]
	s_setprio 0
	s_setprio 1
	v_mfma_f32_16x16x32_bf16 v[116:119], v[178:181], v[194:197], v[116:119]
	v_mfma_f32_16x16x32_bf16 v[112:115], v[186:189], v[194:197], v[112:115]
	v_mfma_f32_16x16x32_bf16 v[100:103], v[178:181], v[202:205], v[100:103]
	v_mfma_f32_16x16x32_bf16 v[96:99], v[186:189], v[202:205], v[96:99]
	v_mfma_f32_16x16x32_bf16 v[84:87], v[178:181], v[228:231], v[84:87]
	v_mfma_f32_16x16x32_bf16 v[80:83], v[186:189], v[228:231], v[80:83]
	v_mfma_f32_16x16x32_bf16 v[68:71], v[178:181], v[236:239], v[68:71]
	v_mfma_f32_16x16x32_bf16 v[64:67], v[186:189], v[236:239], v[64:67]
	v_mfma_f32_16x16x32_bf16 v[116:119], v[182:185], v[198:201], v[116:119]
	v_mfma_f32_16x16x32_bf16 v[112:115], v[190:193], v[198:201], v[112:115]
	v_mfma_f32_16x16x32_bf16 v[100:103], v[182:185], v[220:223], v[100:103]
	v_mfma_f32_16x16x32_bf16 v[96:99], v[190:193], v[220:223], v[96:99]
	v_mfma_f32_16x16x32_bf16 v[84:87], v[182:185], v[232:235], v[84:87]
	v_mfma_f32_16x16x32_bf16 v[80:83], v[190:193], v[232:235], v[80:83]
	v_mfma_f32_16x16x32_bf16 v[68:71], v[182:185], v[240:243], v[68:71]
	v_mfma_f32_16x16x32_bf16 v[64:67], v[190:193], v[240:243], v[64:67]
	s_setprio 0
	s_barrier
	s_add_i32 s30, s31, s64
	v_lshl_add_u64 v[174:175], s[58:59], 0, v[132:133]
	s_mov_b32 m0, s30
	ds_read_b128 v[194:197], v147 offset:16384
	ds_read_b128 v[198:201], v147 offset:17408
	ds_read_b128 v[202:205], v147 offset:18432
	ds_read_b128 v[220:223], v147 offset:19456
	ds_read_b128 v[228:231], v147 offset:20480
	ds_read_b128 v[232:235], v147 offset:21504
	ds_read_b128 v[236:239], v147 offset:22528
	ds_read_b128 v[240:243], v147 offset:23552
	global_load_lds_dwordx4 v[174:175], off
	s_add_i32 m0, s30, 0x2000
	s_add_u32 s30, s58, 0x40000
	v_lshl_add_u64 v[176:177], s[58:59], 0, v[128:129]
	s_addc_u32 s31, s59, 0
	s_add_i32 s29, s29, s64
	global_load_lds_dwordx4 v[176:177], off
	v_lshl_add_u64 v[244:245], s[30:31], 0, v[132:133]
	s_mov_b32 m0, s29
	v_lshl_add_u64 v[246:247], s[60:61], 0, v[130:131]
	global_load_lds_dwordx4 v[244:245], off
	v_lshl_add_u64 v[244:245], s[30:31], 0, v[128:129]
	s_add_i32 m0, s29, 0x2000
	s_nop 0
	global_load_lds_dwordx4 v[244:245], off
	v_lshl_add_u64 v[244:245], s[60:61], 0, v[134:135]
	s_mov_b32 m0, s65
	s_nop 0
	global_load_lds_dwordx4 v[244:245], off
	s_mov_b32 m0, s66
	s_nop 0
	global_load_lds_dwordx4 v[246:247], off
	s_waitcnt vmcnt(8)
	s_waitcnt lgkmcnt(0)
	s_barrier
	s_setprio 1
	v_mfma_f32_16x16x32_bf16 v[60:63], v[140:143], v[194:197], v[60:63]
	v_mfma_f32_16x16x32_bf16 v[56:59], v[152:155], v[194:197], v[56:59]
	v_mfma_f32_16x16x32_bf16 v[44:47], v[140:143], v[202:205], v[44:47]
	v_mfma_f32_16x16x32_bf16 v[40:43], v[152:155], v[202:205], v[40:43]
	v_mfma_f32_16x16x32_bf16 v[28:31], v[140:143], v[228:231], v[28:31]
	v_mfma_f32_16x16x32_bf16 v[24:27], v[152:155], v[228:231], v[24:27]
	v_mfma_f32_16x16x32_bf16 v[12:15], v[140:143], v[236:239], v[12:15]
	v_mfma_f32_16x16x32_bf16 v[8:11], v[152:155], v[236:239], v[8:11]
	v_mfma_f32_16x16x32_bf16 v[60:63], v[148:151], v[198:201], v[60:63]
	v_mfma_f32_16x16x32_bf16 v[56:59], v[156:159], v[198:201], v[56:59]
	v_mfma_f32_16x16x32_bf16 v[44:47], v[148:151], v[220:223], v[44:47]
	v_mfma_f32_16x16x32_bf16 v[40:43], v[156:159], v[220:223], v[40:43]
	v_mfma_f32_16x16x32_bf16 v[28:31], v[148:151], v[232:235], v[28:31]
	v_mfma_f32_16x16x32_bf16 v[24:27], v[156:159], v[232:235], v[24:27]
	v_mfma_f32_16x16x32_bf16 v[12:15], v[148:151], v[240:243], v[12:15]
	v_mfma_f32_16x16x32_bf16 v[8:11], v[156:159], v[240:243], v[8:11]
	s_setprio 0
	s_setprio 1
	v_mfma_f32_16x16x32_bf16 v[52:55], v[178:181], v[194:197], v[52:55]
	v_mfma_f32_16x16x32_bf16 v[48:51], v[186:189], v[194:197], v[48:51]
	v_mfma_f32_16x16x32_bf16 v[36:39], v[178:181], v[202:205], v[36:39]
	v_mfma_f32_16x16x32_bf16 v[32:35], v[186:189], v[202:205], v[32:35]
	v_mfma_f32_16x16x32_bf16 v[20:23], v[178:181], v[228:231], v[20:23]
	v_mfma_f32_16x16x32_bf16 v[16:19], v[186:189], v[228:231], v[16:19]
	v_mfma_f32_16x16x32_bf16 v[4:7], v[178:181], v[236:239], v[4:7]
	v_mfma_f32_16x16x32_bf16 v[0:3], v[186:189], v[236:239], v[0:3]
	v_mfma_f32_16x16x32_bf16 v[52:55], v[182:185], v[198:201], v[52:55]
	v_mfma_f32_16x16x32_bf16 v[48:51], v[190:193], v[198:201], v[48:51]
	v_mfma_f32_16x16x32_bf16 v[36:39], v[182:185], v[220:223], v[36:39]
	v_mfma_f32_16x16x32_bf16 v[32:35], v[190:193], v[220:223], v[32:35]
	v_mfma_f32_16x16x32_bf16 v[20:23], v[182:185], v[232:235], v[20:23]
	v_mfma_f32_16x16x32_bf16 v[16:19], v[190:193], v[232:235], v[16:19]
	v_mfma_f32_16x16x32_bf16 v[4:7], v[182:185], v[240:243], v[4:7]
	v_mfma_f32_16x16x32_bf16 v[0:3], v[190:193], v[240:243], v[0:3]
	s_setprio 0
	s_barrier
	s_add_i32 s29, 0, 0x18000
	s_add_i32 s49, 0, 0x1c000
	v_add_u32_e32 v156, s29, v145
	v_add_u32_e32 v162, s49, v145
	ds_read_b128 v[140:143], v156
	ds_read_b128 v[148:151], v156 offset:1024
	ds_read_b128 v[152:155], v156 offset:2048
	ds_read_b128 v[156:159], v156 offset:3072
	ds_read_b128 v[178:181], v162
	ds_read_b128 v[182:185], v162 offset:1024
	ds_read_b128 v[186:189], v162 offset:2048
	ds_read_b128 v[190:193], v162 offset:3072
	s_add_u32 s30, s60, 0x40000
	s_addc_u32 s31, s61, 0
	s_mov_b32 m0, s67
	v_lshl_add_u64 v[248:249], s[30:31], 0, v[134:135]
	ds_read_b128 v[194:197], v147 offset:32768
	ds_read_b128 v[198:201], v147 offset:33792
	ds_read_b128 v[202:205], v147 offset:34816
	ds_read_b128 v[220:223], v147 offset:35840
	ds_read_b128 v[228:231], v147 offset:36864
	ds_read_b128 v[232:235], v147 offset:37888
	ds_read_b128 v[236:239], v147 offset:38912
	ds_read_b128 v[240:243], v147 offset:39936
	global_load_lds_dwordx4 v[248:249], off
	v_lshl_add_u64 v[248:249], s[30:31], 0, v[130:131]
	s_mov_b32 m0, s68
	s_nop 0
	global_load_lds_dwordx4 v[248:249], off
	s_waitcnt vmcnt(8)
	s_waitcnt lgkmcnt(0)
	s_barrier
	s_setprio 1
	v_mfma_f32_16x16x32_bf16 v[124:127], v[140:143], v[194:197], v[124:127]
	v_mfma_f32_16x16x32_bf16 v[120:123], v[152:155], v[194:197], v[120:123]
	v_mfma_f32_16x16x32_bf16 v[108:111], v[140:143], v[202:205], v[108:111]
	v_mfma_f32_16x16x32_bf16 v[104:107], v[152:155], v[202:205], v[104:107]
	v_mfma_f32_16x16x32_bf16 v[92:95], v[140:143], v[228:231], v[92:95]
	v_mfma_f32_16x16x32_bf16 v[88:91], v[152:155], v[228:231], v[88:91]
	v_mfma_f32_16x16x32_bf16 v[76:79], v[140:143], v[236:239], v[76:79]
	v_mfma_f32_16x16x32_bf16 v[72:75], v[152:155], v[236:239], v[72:75]
	v_mfma_f32_16x16x32_bf16 v[124:127], v[148:151], v[198:201], v[124:127]
	v_mfma_f32_16x16x32_bf16 v[120:123], v[156:159], v[198:201], v[120:123]
	v_mfma_f32_16x16x32_bf16 v[108:111], v[148:151], v[220:223], v[108:111]
	v_mfma_f32_16x16x32_bf16 v[104:107], v[156:159], v[220:223], v[104:107]
	v_mfma_f32_16x16x32_bf16 v[92:95], v[148:151], v[232:235], v[92:95]
	v_mfma_f32_16x16x32_bf16 v[88:91], v[156:159], v[232:235], v[88:91]
	v_mfma_f32_16x16x32_bf16 v[76:79], v[148:151], v[240:243], v[76:79]
	v_mfma_f32_16x16x32_bf16 v[72:75], v[156:159], v[240:243], v[72:75]
	s_setprio 0
	s_setprio 1
	v_mfma_f32_16x16x32_bf16 v[116:119], v[178:181], v[194:197], v[116:119]
	v_mfma_f32_16x16x32_bf16 v[112:115], v[186:189], v[194:197], v[112:115]
	v_mfma_f32_16x16x32_bf16 v[100:103], v[178:181], v[202:205], v[100:103]
	v_mfma_f32_16x16x32_bf16 v[96:99], v[186:189], v[202:205], v[96:99]
	v_mfma_f32_16x16x32_bf16 v[84:87], v[178:181], v[228:231], v[84:87]
	v_mfma_f32_16x16x32_bf16 v[80:83], v[186:189], v[228:231], v[80:83]
	v_mfma_f32_16x16x32_bf16 v[68:71], v[178:181], v[236:239], v[68:71]
	v_mfma_f32_16x16x32_bf16 v[64:67], v[186:189], v[236:239], v[64:67]
	v_mfma_f32_16x16x32_bf16 v[116:119], v[182:185], v[198:201], v[116:119]
	v_mfma_f32_16x16x32_bf16 v[112:115], v[190:193], v[198:201], v[112:115]
	v_mfma_f32_16x16x32_bf16 v[100:103], v[182:185], v[220:223], v[100:103]
	v_mfma_f32_16x16x32_bf16 v[96:99], v[190:193], v[220:223], v[96:99]
	v_mfma_f32_16x16x32_bf16 v[84:87], v[182:185], v[232:235], v[84:87]
	v_mfma_f32_16x16x32_bf16 v[80:83], v[190:193], v[232:235], v[80:83]
	v_mfma_f32_16x16x32_bf16 v[68:71], v[182:185], v[240:243], v[68:71]
	v_mfma_f32_16x16x32_bf16 v[64:67], v[190:193], v[240:243], v[64:67]
	s_setprio 0
	s_barrier
	s_add_i32 s29, s29, s64
	v_lshl_add_u64 v[174:175], v[174:175], 0, s[4:5]
	s_mov_b32 m0, s29
	ds_read_b128 v[194:197], v147 offset:49152
	ds_read_b128 v[198:201], v147 offset:50176
	ds_read_b128 v[202:205], v147 offset:51200
	ds_read_b128 v[220:223], v147 offset:52224
	ds_read_b128 v[228:231], v147 offset:53248
	ds_read_b128 v[232:235], v147 offset:54272
	ds_read_b128 v[236:239], v147 offset:55296
	ds_read_b128 v[240:243], v147 offset:56320
	global_load_lds_dwordx4 v[174:175], off
	s_add_i32 m0, s29, 0x2000
	s_add_u32 s30, s58, 0x40080
	v_lshl_add_u64 v[174:175], v[176:177], 0, s[4:5]
	s_addc_u32 s31, s59, 0
	s_add_i32 s29, s49, s64
	global_load_lds_dwordx4 v[174:175], off
	v_lshl_add_u64 v[174:175], s[30:31], 0, v[132:133]
	s_mov_b32 m0, s29
	s_nop 0
	global_load_lds_dwordx4 v[174:175], off
	v_lshl_add_u64 v[174:175], s[30:31], 0, v[128:129]
	s_add_i32 m0, s29, 0x2000
	s_nop 0
	global_load_lds_dwordx4 v[174:175], off
	v_lshl_add_u64 v[174:175], v[244:245], 0, s[4:5]
	s_mov_b32 m0, s73
	s_nop 0
	global_load_lds_dwordx4 v[174:175], off
	v_lshl_add_u64 v[174:175], v[246:247], 0, s[4:5]
	s_mov_b32 m0, s74
	s_nop 0
	global_load_lds_dwordx4 v[174:175], off
	s_waitcnt vmcnt(8)
	s_waitcnt lgkmcnt(0)
	s_barrier
	s_setprio 1
	v_mfma_f32_16x16x32_bf16 v[60:63], v[140:143], v[194:197], v[60:63]
	v_mfma_f32_16x16x32_bf16 v[56:59], v[152:155], v[194:197], v[56:59]
	v_mfma_f32_16x16x32_bf16 v[44:47], v[140:143], v[202:205], v[44:47]
	v_mfma_f32_16x16x32_bf16 v[40:43], v[152:155], v[202:205], v[40:43]
	v_mfma_f32_16x16x32_bf16 v[28:31], v[140:143], v[228:231], v[28:31]
	v_mfma_f32_16x16x32_bf16 v[24:27], v[152:155], v[228:231], v[24:27]
	v_mfma_f32_16x16x32_bf16 v[12:15], v[140:143], v[236:239], v[12:15]
	v_mfma_f32_16x16x32_bf16 v[8:11], v[152:155], v[236:239], v[8:11]
	v_mfma_f32_16x16x32_bf16 v[60:63], v[148:151], v[198:201], v[60:63]
	v_mfma_f32_16x16x32_bf16 v[56:59], v[156:159], v[198:201], v[56:59]
	v_mfma_f32_16x16x32_bf16 v[44:47], v[148:151], v[220:223], v[44:47]
	v_mfma_f32_16x16x32_bf16 v[40:43], v[156:159], v[220:223], v[40:43]
	v_mfma_f32_16x16x32_bf16 v[28:31], v[148:151], v[232:235], v[28:31]
	v_mfma_f32_16x16x32_bf16 v[24:27], v[156:159], v[232:235], v[24:27]
	v_mfma_f32_16x16x32_bf16 v[12:15], v[148:151], v[240:243], v[12:15]
	v_mfma_f32_16x16x32_bf16 v[8:11], v[156:159], v[240:243], v[8:11]
	s_setprio 0
	s_setprio 1
	v_mfma_f32_16x16x32_bf16 v[52:55], v[178:181], v[194:197], v[52:55]
	v_mfma_f32_16x16x32_bf16 v[48:51], v[186:189], v[194:197], v[48:51]
	v_mfma_f32_16x16x32_bf16 v[36:39], v[178:181], v[202:205], v[36:39]
	v_mfma_f32_16x16x32_bf16 v[32:35], v[186:189], v[202:205], v[32:35]
	v_mfma_f32_16x16x32_bf16 v[20:23], v[178:181], v[228:231], v[20:23]
	v_mfma_f32_16x16x32_bf16 v[16:19], v[186:189], v[228:231], v[16:19]
	v_mfma_f32_16x16x32_bf16 v[4:7], v[178:181], v[236:239], v[4:7]
	v_mfma_f32_16x16x32_bf16 v[0:3], v[186:189], v[236:239], v[0:3]
	v_mfma_f32_16x16x32_bf16 v[52:55], v[182:185], v[198:201], v[52:55]
	v_mfma_f32_16x16x32_bf16 v[48:51], v[190:193], v[198:201], v[48:51]
	v_mfma_f32_16x16x32_bf16 v[36:39], v[182:185], v[220:223], v[36:39]
	v_mfma_f32_16x16x32_bf16 v[32:35], v[190:193], v[220:223], v[32:35]
	v_mfma_f32_16x16x32_bf16 v[20:23], v[182:185], v[232:235], v[20:23]
	v_mfma_f32_16x16x32_bf16 v[16:19], v[190:193], v[232:235], v[16:19]
	v_mfma_f32_16x16x32_bf16 v[4:7], v[182:185], v[240:243], v[4:7]
	v_mfma_f32_16x16x32_bf16 v[0:3], v[190:193], v[240:243], v[0:3]
	s_setprio 0
	s_barrier
	s_add_i32 s28, s28, 2
	s_add_u32 s56, s56, 0x100
	s_addc_u32 s57, s57, 0
	s_add_u32 s26, s26, 0x100
	s_addc_u32 s27, s27, 0
	s_cmp_gt_u32 s28, 13
	s_cbranch_scc0 .LBB0_179
	s_and_b64 vcc, exec, s[46:47]
	s_cbranch_vccz .LBB0_182
	s_barrier

.LBB0_204:
	s_add_u32 s28, s42, 0xfffc0080
	s_addc_u32 s29, s43, -1
	s_add_i32 s30, 0, 0x10000
	s_cmp_eq_u32 s27, 12
	s_cselect_b32 s63, s6, s29
	s_cselect_b32 s62, s7, s28
	s_cselect_b32 s61, s23, s26
	s_cselect_b32 s60, s24, s25
	s_add_i32 s31, 0, 0x14000
	v_add_u32_e32 v140, s30, v221
	v_add_u32_e32 v156, s31, v221
	ds_read_b128 v[128:131], v140
	ds_read_b128 v[132:135], v140 offset:1024
	ds_read_b128 v[136:139], v140 offset:2048
	ds_read_b128 v[140:143], v140 offset:3072
	ds_read_b128 v[144:147], v156
	ds_read_b128 v[148:151], v156 offset:1024
	ds_read_b128 v[152:155], v156 offset:2048
	ds_read_b128 v[156:159], v156 offset:3072
	v_lshl_add_u64 v[174:175], s[42:43], 0, v[184:185]
	s_add_i32 m0, s67, 0xc000
	ds_read_b128 v[188:191], v223
	ds_read_b128 v[192:195], v223 offset:1024
	ds_read_b128 v[196:199], v223 offset:2048
	ds_read_b128 v[200:203], v223 offset:3072
	ds_read_b128 v[228:231], v223 offset:4096
	ds_read_b128 v[232:235], v223 offset:5120
	ds_read_b128 v[236:239], v223 offset:6144
	ds_read_b128 v[240:243], v223 offset:7168
	global_load_lds_dwordx4 v[174:175], off
	v_lshl_add_u64 v[174:175], s[42:43], 0, v[186:187]
	s_add_i32 m0, s67, 0xe000
	s_nop 0
	global_load_lds_dwordx4 v[174:175], off
	s_waitcnt vmcnt(8)
	s_waitcnt lgkmcnt(0)
	s_barrier
	s_setprio 1
	v_mfma_f32_16x16x32_bf16 v[124:127], v[128:131], v[188:191], v[124:127]
	v_mfma_f32_16x16x32_bf16 v[120:123], v[136:139], v[188:191], v[120:123]
	v_mfma_f32_16x16x32_bf16 v[116:119], v[128:131], v[196:199], v[116:119]
	v_mfma_f32_16x16x32_bf16 v[108:111], v[136:139], v[196:199], v[108:111]
	v_mfma_f32_16x16x32_bf16 v[100:103], v[128:131], v[228:231], v[100:103]
	v_mfma_f32_16x16x32_bf16 v[92:95], v[136:139], v[228:231], v[92:95]
	v_mfma_f32_16x16x32_bf16 v[84:87], v[128:131], v[236:239], v[84:87]
	v_mfma_f32_16x16x32_bf16 v[76:79], v[136:139], v[236:239], v[76:79]
	v_mfma_f32_16x16x32_bf16 v[124:127], v[132:135], v[192:195], v[124:127]
	v_mfma_f32_16x16x32_bf16 v[120:123], v[140:143], v[192:195], v[120:123]
	v_mfma_f32_16x16x32_bf16 v[116:119], v[132:135], v[200:203], v[116:119]
	v_mfma_f32_16x16x32_bf16 v[108:111], v[140:143], v[200:203], v[108:111]
	v_mfma_f32_16x16x32_bf16 v[100:103], v[132:135], v[232:235], v[100:103]
	v_mfma_f32_16x16x32_bf16 v[92:95], v[140:143], v[232:235], v[92:95]
	v_mfma_f32_16x16x32_bf16 v[84:87], v[132:135], v[240:243], v[84:87]
	v_mfma_f32_16x16x32_bf16 v[76:79], v[140:143], v[240:243], v[76:79]
	s_setprio 0
	s_setprio 1
	v_mfma_f32_16x16x32_bf16 v[112:115], v[144:147], v[188:191], v[112:115]
	v_mfma_f32_16x16x32_bf16 v[104:107], v[152:155], v[188:191], v[104:107]
	v_mfma_f32_16x16x32_bf16 v[96:99], v[144:147], v[196:199], v[96:99]
	v_mfma_f32_16x16x32_bf16 v[88:91], v[152:155], v[196:199], v[88:91]
	v_mfma_f32_16x16x32_bf16 v[80:83], v[144:147], v[228:231], v[80:83]
	v_mfma_f32_16x16x32_bf16 v[72:75], v[152:155], v[228:231], v[72:75]
	v_mfma_f32_16x16x32_bf16 v[68:71], v[144:147], v[236:239], v[68:71]
	v_mfma_f32_16x16x32_bf16 v[64:67], v[152:155], v[236:239], v[64:67]
	v_mfma_f32_16x16x32_bf16 v[112:115], v[148:151], v[192:195], v[112:115]
	v_mfma_f32_16x16x32_bf16 v[104:107], v[156:159], v[192:195], v[104:107]
	v_mfma_f32_16x16x32_bf16 v[96:99], v[148:151], v[200:203], v[96:99]
	v_mfma_f32_16x16x32_bf16 v[88:91], v[156:159], v[200:203], v[88:91]
	v_mfma_f32_16x16x32_bf16 v[80:83], v[148:151], v[232:235], v[80:83]
	v_mfma_f32_16x16x32_bf16 v[72:75], v[156:159], v[232:235], v[72:75]
	v_mfma_f32_16x16x32_bf16 v[68:71], v[148:151], v[240:243], v[68:71]
	v_mfma_f32_16x16x32_bf16 v[64:67], v[156:159], v[240:243], v[64:67]
	s_setprio 0
	s_barrier
	s_add_i32 s28, s30, s66
	v_lshl_add_u64 v[174:175], s[60:61], 0, v[162:163]
	s_mov_b32 m0, s28
	ds_read_b128 v[188:191], v223 offset:16384
	ds_read_b128 v[192:195], v223 offset:17408
	ds_read_b128 v[196:199], v223 offset:18432
	ds_read_b128 v[200:203], v223 offset:19456
	ds_read_b128 v[228:231], v223 offset:20480
	ds_read_b128 v[232:235], v223 offset:21504
	ds_read_b128 v[236:239], v223 offset:22528
	ds_read_b128 v[240:243], v223 offset:23552
	global_load_lds_dwordx4 v[174:175], off
	s_add_i32 m0, s28, 0x2000
	s_add_u32 s28, s60, 0x40000
	v_lshl_add_u64 v[176:177], s[60:61], 0, v[178:179]
	s_addc_u32 s29, s61, 0
	s_add_i32 s30, s31, s66
	global_load_lds_dwordx4 v[176:177], off
	v_lshl_add_u64 v[204:205], s[28:29], 0, v[162:163]
	s_mov_b32 m0, s30
	v_lshl_add_u64 v[244:245], s[62:63], 0, v[180:181]
	global_load_lds_dwordx4 v[204:205], off
	v_lshl_add_u64 v[204:205], s[28:29], 0, v[178:179]
	s_add_i32 m0, s30, 0x2000
	s_nop 0
	global_load_lds_dwordx4 v[204:205], off
	v_lshl_add_u64 v[204:205], s[62:63], 0, v[182:183]
	s_mov_b32 m0, s67
	s_nop 0
	global_load_lds_dwordx4 v[204:205], off
	s_mov_b32 m0, s68
	s_nop 0
	global_load_lds_dwordx4 v[244:245], off
	s_waitcnt vmcnt(8)
	s_waitcnt lgkmcnt(0)
	s_barrier
	s_setprio 1
	v_mfma_f32_16x16x32_bf16 v[60:63], v[128:131], v[188:191], v[60:63]
	v_mfma_f32_16x16x32_bf16 v[56:59], v[136:139], v[188:191], v[56:59]
	v_mfma_f32_16x16x32_bf16 v[52:55], v[128:131], v[196:199], v[52:55]
	v_mfma_f32_16x16x32_bf16 v[44:47], v[136:139], v[196:199], v[44:47]
	v_mfma_f32_16x16x32_bf16 v[36:39], v[128:131], v[228:231], v[36:39]
	v_mfma_f32_16x16x32_bf16 v[28:31], v[136:139], v[228:231], v[28:31]
	v_mfma_f32_16x16x32_bf16 v[20:23], v[128:131], v[236:239], v[20:23]
	v_mfma_f32_16x16x32_bf16 v[12:15], v[136:139], v[236:239], v[12:15]
	v_mfma_f32_16x16x32_bf16 v[60:63], v[132:135], v[192:195], v[60:63]
	v_mfma_f32_16x16x32_bf16 v[56:59], v[140:143], v[192:195], v[56:59]
	v_mfma_f32_16x16x32_bf16 v[52:55], v[132:135], v[200:203], v[52:55]
	v_mfma_f32_16x16x32_bf16 v[44:47], v[140:143], v[200:203], v[44:47]
	v_mfma_f32_16x16x32_bf16 v[36:39], v[132:135], v[232:235], v[36:39]
	v_mfma_f32_16x16x32_bf16 v[28:31], v[140:143], v[232:235], v[28:31]
	v_mfma_f32_16x16x32_bf16 v[20:23], v[132:135], v[240:243], v[20:23]
	v_mfma_f32_16x16x32_bf16 v[12:15], v[140:143], v[240:243], v[12:15]
	s_setprio 0
	s_setprio 1
	v_mfma_f32_16x16x32_bf16 v[48:51], v[144:147], v[188:191], v[48:51]
	v_mfma_f32_16x16x32_bf16 v[40:43], v[152:155], v[188:191], v[40:43]
	v_mfma_f32_16x16x32_bf16 v[32:35], v[144:147], v[196:199], v[32:35]
	v_mfma_f32_16x16x32_bf16 v[24:27], v[152:155], v[196:199], v[24:27]
	v_mfma_f32_16x16x32_bf16 v[16:19], v[144:147], v[228:231], v[16:19]
	v_mfma_f32_16x16x32_bf16 v[8:11], v[152:155], v[228:231], v[8:11]
	v_mfma_f32_16x16x32_bf16 v[4:7], v[144:147], v[236:239], v[4:7]
	v_mfma_f32_16x16x32_bf16 v[0:3], v[152:155], v[236:239], v[0:3]
	v_mfma_f32_16x16x32_bf16 v[48:51], v[148:151], v[192:195], v[48:51]
	v_mfma_f32_16x16x32_bf16 v[40:43], v[156:159], v[192:195], v[40:43]
	v_mfma_f32_16x16x32_bf16 v[32:35], v[148:151], v[200:203], v[32:35]
	v_mfma_f32_16x16x32_bf16 v[24:27], v[156:159], v[200:203], v[24:27]
	v_mfma_f32_16x16x32_bf16 v[16:19], v[148:151], v[232:235], v[16:19]
	v_mfma_f32_16x16x32_bf16 v[8:11], v[156:159], v[232:235], v[8:11]
	v_mfma_f32_16x16x32_bf16 v[4:7], v[148:151], v[240:243], v[4:7]
	v_mfma_f32_16x16x32_bf16 v[0:3], v[156:159], v[240:243], v[0:3]
	s_setprio 0
	s_barrier
	s_add_i32 s30, 0, 0x18000
	s_add_i32 s31, 0, 0x1c000
	v_add_u32_e32 v140, s30, v221
	v_add_u32_e32 v156, s31, v221
	ds_read_b128 v[128:131], v140
	ds_read_b128 v[132:135], v140 offset:1024
	ds_read_b128 v[136:139], v140 offset:2048
	ds_read_b128 v[140:143], v140 offset:3072
	ds_read_b128 v[144:147], v156
	ds_read_b128 v[148:151], v156 offset:1024
	ds_read_b128 v[152:155], v156 offset:2048
	ds_read_b128 v[156:159], v156 offset:3072
	s_add_u32 s28, s62, 0x40000
	s_addc_u32 s29, s63, 0
	s_mov_b32 m0, s69
	v_lshl_add_u64 v[246:247], s[28:29], 0, v[182:183]
	ds_read_b128 v[188:191], v223 offset:32768
	ds_read_b128 v[192:195], v223 offset:33792
	ds_read_b128 v[196:199], v223 offset:34816
	ds_read_b128 v[200:203], v223 offset:35840
	ds_read_b128 v[228:231], v223 offset:36864
	ds_read_b128 v[232:235], v223 offset:37888
	ds_read_b128 v[236:239], v223 offset:38912
	ds_read_b128 v[240:243], v223 offset:39936
	global_load_lds_dwordx4 v[246:247], off
	v_lshl_add_u64 v[246:247], s[28:29], 0, v[180:181]
	s_mov_b32 m0, s70
	s_nop 0
	global_load_lds_dwordx4 v[246:247], off
	s_waitcnt vmcnt(8)
	s_waitcnt lgkmcnt(0)
	s_barrier
	s_setprio 1
	v_mfma_f32_16x16x32_bf16 v[124:127], v[128:131], v[188:191], v[124:127]
	v_mfma_f32_16x16x32_bf16 v[120:123], v[136:139], v[188:191], v[120:123]
	v_mfma_f32_16x16x32_bf16 v[116:119], v[128:131], v[196:199], v[116:119]
	v_mfma_f32_16x16x32_bf16 v[108:111], v[136:139], v[196:199], v[108:111]
	v_mfma_f32_16x16x32_bf16 v[100:103], v[128:131], v[228:231], v[100:103]
	v_mfma_f32_16x16x32_bf16 v[92:95], v[136:139], v[228:231], v[92:95]
	v_mfma_f32_16x16x32_bf16 v[84:87], v[128:131], v[236:239], v[84:87]
	v_mfma_f32_16x16x32_bf16 v[76:79], v[136:139], v[236:239], v[76:79]
	v_mfma_f32_16x16x32_bf16 v[124:127], v[132:135], v[192:195], v[124:127]
	v_mfma_f32_16x16x32_bf16 v[120:123], v[140:143], v[192:195], v[120:123]
	v_mfma_f32_16x16x32_bf16 v[116:119], v[132:135], v[200:203], v[116:119]
	v_mfma_f32_16x16x32_bf16 v[108:111], v[140:143], v[200:203], v[108:111]
	v_mfma_f32_16x16x32_bf16 v[100:103], v[132:135], v[232:235], v[100:103]
	v_mfma_f32_16x16x32_bf16 v[92:95], v[140:143], v[232:235], v[92:95]
	v_mfma_f32_16x16x32_bf16 v[84:87], v[132:135], v[240:243], v[84:87]
	v_mfma_f32_16x16x32_bf16 v[76:79], v[140:143], v[240:243], v[76:79]
	s_setprio 0
	s_setprio 1
	v_mfma_f32_16x16x32_bf16 v[112:115], v[144:147], v[188:191], v[112:115]
	v_mfma_f32_16x16x32_bf16 v[104:107], v[152:155], v[188:191], v[104:107]
	v_mfma_f32_16x16x32_bf16 v[96:99], v[144:147], v[196:199], v[96:99]
	v_mfma_f32_16x16x32_bf16 v[88:91], v[152:155], v[196:199], v[88:91]
	v_mfma_f32_16x16x32_bf16 v[80:83], v[144:147], v[228:231], v[80:83]
	v_mfma_f32_16x16x32_bf16 v[72:75], v[152:155], v[228:231], v[72:75]
	v_mfma_f32_16x16x32_bf16 v[68:71], v[144:147], v[236:239], v[68:71]
	v_mfma_f32_16x16x32_bf16 v[64:67], v[152:155], v[236:239], v[64:67]
	v_mfma_f32_16x16x32_bf16 v[112:115], v[148:151], v[192:195], v[112:115]
	v_mfma_f32_16x16x32_bf16 v[104:107], v[156:159], v[192:195], v[104:107]
	v_mfma_f32_16x16x32_bf16 v[96:99], v[148:151], v[200:203], v[96:99]
	v_mfma_f32_16x16x32_bf16 v[88:91], v[156:159], v[200:203], v[88:91]
	v_mfma_f32_16x16x32_bf16 v[80:83], v[148:151], v[232:235], v[80:83]
	v_mfma_f32_16x16x32_bf16 v[72:75], v[156:159], v[232:235], v[72:75]
	v_mfma_f32_16x16x32_bf16 v[68:71], v[148:151], v[240:243], v[68:71]
	v_mfma_f32_16x16x32_bf16 v[64:67], v[156:159], v[240:243], v[64:67]
	s_setprio 0
	s_barrier
	s_add_i32 s28, s30, s66
	v_lshl_add_u64 v[174:175], v[174:175], 0, s[4:5]
	s_mov_b32 m0, s28
	ds_read_b128 v[188:191], v223 offset:49152
	ds_read_b128 v[192:195], v223 offset:50176
	ds_read_b128 v[196:199], v223 offset:51200
	ds_read_b128 v[200:203], v223 offset:52224
	ds_read_b128 v[228:231], v223 offset:53248
	ds_read_b128 v[232:235], v223 offset:54272
	ds_read_b128 v[236:239], v223 offset:55296
	ds_read_b128 v[240:243], v223 offset:56320
	global_load_lds_dwordx4 v[174:175], off
	s_add_i32 m0, s28, 0x2000
	s_add_u32 s28, s60, 0x40080
	v_lshl_add_u64 v[174:175], v[176:177], 0, s[4:5]
	s_addc_u32 s29, s61, 0
	s_add_i32 s30, s31, s66
	global_load_lds_dwordx4 v[174:175], off
	v_lshl_add_u64 v[174:175], s[28:29], 0, v[162:163]
	s_mov_b32 m0, s30
	s_nop 0
	global_load_lds_dwordx4 v[174:175], off
	v_lshl_add_u64 v[174:175], s[28:29], 0, v[178:179]
	s_add_i32 m0, s30, 0x2000
	s_nop 0
	global_load_lds_dwordx4 v[174:175], off
	v_lshl_add_u64 v[174:175], v[204:205], 0, s[4:5]
	s_mov_b32 m0, s71
	s_nop 0
	global_load_lds_dwordx4 v[174:175], off
	v_lshl_add_u64 v[174:175], v[244:245], 0, s[4:5]
	s_mov_b32 m0, s72
	s_nop 0
	global_load_lds_dwordx4 v[174:175], off
	s_waitcnt vmcnt(8)
	s_waitcnt lgkmcnt(0)
	s_barrier
	s_setprio 1
	v_mfma_f32_16x16x32_bf16 v[60:63], v[128:131], v[188:191], v[60:63]
	v_mfma_f32_16x16x32_bf16 v[56:59], v[136:139], v[188:191], v[56:59]
	v_mfma_f32_16x16x32_bf16 v[52:55], v[128:131], v[196:199], v[52:55]
	v_mfma_f32_16x16x32_bf16 v[44:47], v[136:139], v[196:199], v[44:47]
	v_mfma_f32_16x16x32_bf16 v[36:39], v[128:131], v[228:231], v[36:39]
	v_mfma_f32_16x16x32_bf16 v[28:31], v[136:139], v[228:231], v[28:31]
	v_mfma_f32_16x16x32_bf16 v[20:23], v[128:131], v[236:239], v[20:23]
	v_mfma_f32_16x16x32_bf16 v[12:15], v[136:139], v[236:239], v[12:15]
	v_mfma_f32_16x16x32_bf16 v[60:63], v[132:135], v[192:195], v[60:63]
	v_mfma_f32_16x16x32_bf16 v[56:59], v[140:143], v[192:195], v[56:59]
	v_mfma_f32_16x16x32_bf16 v[52:55], v[132:135], v[200:203], v[52:55]
	v_mfma_f32_16x16x32_bf16 v[44:47], v[140:143], v[200:203], v[44:47]
	v_mfma_f32_16x16x32_bf16 v[36:39], v[132:135], v[232:235], v[36:39]
	v_mfma_f32_16x16x32_bf16 v[28:31], v[140:143], v[232:235], v[28:31]
	v_mfma_f32_16x16x32_bf16 v[20:23], v[132:135], v[240:243], v[20:23]
	v_mfma_f32_16x16x32_bf16 v[12:15], v[140:143], v[240:243], v[12:15]
	s_setprio 0
	s_setprio 1
	v_mfma_f32_16x16x32_bf16 v[48:51], v[144:147], v[188:191], v[48:51]
	v_mfma_f32_16x16x32_bf16 v[40:43], v[152:155], v[188:191], v[40:43]
	v_mfma_f32_16x16x32_bf16 v[32:35], v[144:147], v[196:199], v[32:35]
	v_mfma_f32_16x16x32_bf16 v[24:27], v[152:155], v[196:199], v[24:27]
	v_mfma_f32_16x16x32_bf16 v[16:19], v[144:147], v[228:231], v[16:19]
	v_mfma_f32_16x16x32_bf16 v[8:11], v[152:155], v[228:231], v[8:11]
	v_mfma_f32_16x16x32_bf16 v[4:7], v[144:147], v[236:239], v[4:7]
	v_mfma_f32_16x16x32_bf16 v[0:3], v[152:155], v[236:239], v[0:3]
	v_mfma_f32_16x16x32_bf16 v[48:51], v[148:151], v[192:195], v[48:51]
	v_mfma_f32_16x16x32_bf16 v[40:43], v[156:159], v[192:195], v[40:43]
	v_mfma_f32_16x16x32_bf16 v[32:35], v[148:151], v[200:203], v[32:35]
	v_mfma_f32_16x16x32_bf16 v[24:27], v[156:159], v[200:203], v[24:27]
	v_mfma_f32_16x16x32_bf16 v[16:19], v[148:151], v[232:235], v[16:19]
	v_mfma_f32_16x16x32_bf16 v[8:11], v[156:159], v[232:235], v[8:11]
	v_mfma_f32_16x16x32_bf16 v[4:7], v[148:151], v[240:243], v[4:7]
	v_mfma_f32_16x16x32_bf16 v[0:3], v[156:159], v[240:243], v[0:3]
	s_setprio 0
	s_barrier
	s_add_i32 s27, s27, 2
	s_add_u32 s42, s42, 0x100
	s_addc_u32 s43, s43, 0
	s_add_u32 s25, s25, 0x100
	s_addc_u32 s26, s26, 0
	s_cmp_gt_u32 s27, 13
	s_cbranch_scc0 .LBB0_204
	s_and_b64 vcc, exec, s[50:51]
	s_cbranch_vccz .LBB0_207
	s_barrier

.LBB0_502:
	s_add_i32 s62, 0, 0x10000
	s_add_i32 s61, 0, 0x14000
	v_add_u32_e32 v19, s62, v16
	v_add_u32_e32 v20, s61, v16
	ds_read_b128 v[22:25], v19
	ds_read_b128 v[26:29], v19 offset:1024
	ds_read_b128 v[30:33], v19 offset:2048
	ds_read_b128 v[34:37], v19 offset:3072
	ds_read_b128 v[38:41], v20
	ds_read_b128 v[42:45], v20 offset:1024
	ds_read_b128 v[46:49], v20 offset:2048
	ds_read_b128 v[50:53], v20 offset:3072
	s_add_u32 s58, s50, 0x18080
	s_addc_u32 s59, s51, 0
	s_add_i32 s65, s26, 0xc000
	v_lshl_add_u64 v[78:79], s[58:59], 0, v[6:7]
	s_mov_b32 m0, s65
	s_add_i32 s57, s26, 0xe000
	ds_read_b128 v[8:11], v17
	ds_read_b128 v[12:15], v17 offset:1024
	ds_read_b128 v[54:57], v17 offset:2048
	ds_read_b128 v[58:61], v17 offset:3072
	ds_read_b128 v[62:65], v17 offset:4096
	ds_read_b128 v[66:69], v17 offset:5120
	ds_read_b128 v[70:73], v17 offset:6144
	ds_read_b128 v[74:77], v17 offset:7168
	global_load_lds_dwordx4 v[78:79], off
	v_lshl_add_u64 v[78:79], s[58:59], 0, v[2:3]
	s_mov_b32 m0, s57
	s_nop 0
	global_load_lds_dwordx4 v[78:79], off
	s_waitcnt vmcnt(8)
	s_waitcnt lgkmcnt(0)
	s_barrier
	s_setprio 1
	v_mfma_f32_16x16x32_bf16 v[78:81], v[22:25], v[8:11], 0
	v_mfma_f32_16x16x32_bf16 v[82:85], v[30:33], v[8:11], 0
	v_mfma_f32_16x16x32_bf16 v[86:89], v[22:25], v[54:57], 0
	v_mfma_f32_16x16x32_bf16 v[90:93], v[30:33], v[54:57], 0
	v_mfma_f32_16x16x32_bf16 v[94:97], v[22:25], v[62:65], 0
	v_mfma_f32_16x16x32_bf16 v[98:101], v[30:33], v[62:65], 0
	v_mfma_f32_16x16x32_bf16 v[102:105], v[22:25], v[70:73], 0
	v_mfma_f32_16x16x32_bf16 v[106:109], v[30:33], v[70:73], 0
	v_mfma_f32_16x16x32_bf16 v[78:81], v[26:29], v[12:15], v[78:81]
	v_mfma_f32_16x16x32_bf16 v[82:85], v[34:37], v[12:15], v[82:85]
	v_mfma_f32_16x16x32_bf16 v[86:89], v[26:29], v[58:61], v[86:89]
	v_mfma_f32_16x16x32_bf16 v[90:93], v[34:37], v[58:61], v[90:93]
	v_mfma_f32_16x16x32_bf16 v[94:97], v[26:29], v[66:69], v[94:97]
	v_mfma_f32_16x16x32_bf16 v[98:101], v[34:37], v[66:69], v[98:101]
	v_mfma_f32_16x16x32_bf16 v[102:105], v[26:29], v[74:77], v[102:105]
	v_mfma_f32_16x16x32_bf16 v[106:109], v[34:37], v[74:77], v[106:109]
	s_setprio 0
	s_setprio 1
	v_mfma_f32_16x16x32_bf16 v[110:113], v[38:41], v[8:11], 0
	v_mfma_f32_16x16x32_bf16 v[8:11], v[46:49], v[8:11], 0
	v_mfma_f32_16x16x32_bf16 v[114:117], v[50:53], v[12:15], v[8:11]
	v_mfma_f32_16x16x32_bf16 v[8:11], v[38:41], v[54:57], 0
	v_mfma_f32_16x16x32_bf16 v[118:121], v[42:45], v[58:61], v[8:11]
	v_mfma_f32_16x16x32_bf16 v[8:11], v[46:49], v[54:57], 0
	v_mfma_f32_16x16x32_bf16 v[54:57], v[50:53], v[58:61], v[8:11]
	v_mfma_f32_16x16x32_bf16 v[8:11], v[38:41], v[62:65], 0
	v_mfma_f32_16x16x32_bf16 v[58:61], v[42:45], v[66:69], v[8:11]
	v_mfma_f32_16x16x32_bf16 v[8:11], v[46:49], v[62:65], 0
	v_mfma_f32_16x16x32_bf16 v[62:65], v[50:53], v[66:69], v[8:11]
	v_mfma_f32_16x16x32_bf16 v[8:11], v[38:41], v[70:73], 0
	v_mfma_f32_16x16x32_bf16 v[66:69], v[42:45], v[74:77], v[8:11]
	v_mfma_f32_16x16x32_bf16 v[8:11], v[46:49], v[70:73], 0
	v_mfma_f32_16x16x32_bf16 v[110:113], v[42:45], v[12:15], v[110:113]
	v_mfma_f32_16x16x32_bf16 v[70:73], v[50:53], v[74:77], v[8:11]
	s_setprio 0
	s_barrier
	s_nop 3
	v_lshl_add_u64 v[8:9], s[52:53], 0, v[4:5]
	s_mov_b64 s[68:69], 0x100
	s_add_i32 s62, s62, s25
	v_lshl_add_u64 v[10:11], v[8:9], 0, s[68:69]
	s_mov_b32 m0, s62
	s_add_i32 s58, s62, 0x2000
	ds_read_b128 v[74:77], v17 offset:16384
	ds_read_b128 v[122:125], v17 offset:17408
	ds_read_b128 v[126:129], v17 offset:18432
	ds_read_b128 v[130:133], v17 offset:19456
	ds_read_b128 v[134:137], v17 offset:20480
	ds_read_b128 v[138:141], v17 offset:21504
	ds_read_b128 v[142:145], v17 offset:22528
	ds_read_b128 v[146:149], v17 offset:23552
	global_load_lds_dwordx4 v[10:11], off
	v_lshl_add_u64 v[10:11], s[52:53], 0, v[0:1]
	s_add_u32 s66, s52, 0x18100
	v_lshl_add_u64 v[12:13], v[10:11], 0, s[68:69]
	s_mov_b32 m0, s58
	s_addc_u32 s67, s53, 0
	s_add_i32 s59, s61, s25
	global_load_lds_dwordx4 v[12:13], off
	v_lshl_add_u64 v[12:13], s[66:67], 0, v[4:5]
	s_mov_b32 m0, s59
	s_add_i32 s61, s59, 0x2000
	global_load_lds_dwordx4 v[12:13], off
	v_lshl_add_u64 v[12:13], s[66:67], 0, v[0:1]
	s_mov_b32 m0, s61
	s_nop 0
	global_load_lds_dwordx4 v[12:13], off
	v_lshl_add_u64 v[12:13], s[50:51], 0, v[6:7]
	v_lshl_add_u64 v[14:15], v[12:13], 0, s[68:69]
	s_mov_b32 m0, s26
	s_nop 0
	global_load_lds_dwordx4 v[14:15], off
	v_lshl_add_u64 v[14:15], s[50:51], 0, v[2:3]
	v_lshl_add_u64 v[150:151], v[14:15], 0, s[68:69]
	s_mov_b32 m0, s27
	s_nop 0
	global_load_lds_dwordx4 v[150:151], off
	s_waitcnt vmcnt(8)
	s_waitcnt lgkmcnt(0)
	s_barrier
	s_setprio 1
	v_mfma_f32_16x16x32_bf16 v[150:153], v[22:25], v[74:77], 0
	v_mfma_f32_16x16x32_bf16 v[178:181], v[22:25], v[126:129], 0
	v_mfma_f32_16x16x32_bf16 v[186:189], v[22:25], v[134:137], 0
	v_mfma_f32_16x16x32_bf16 v[22:25], v[22:25], v[142:145], 0
	v_mfma_f32_16x16x32_bf16 v[150:153], v[26:29], v[122:125], v[150:153]
	v_mfma_f32_16x16x32_bf16 v[154:157], v[30:33], v[74:77], 0
	v_mfma_f32_16x16x32_bf16 v[178:181], v[26:29], v[130:133], v[178:181]
	v_mfma_f32_16x16x32_bf16 v[182:185], v[30:33], v[126:129], 0
	v_mfma_f32_16x16x32_bf16 v[186:189], v[26:29], v[138:141], v[186:189]
	v_mfma_f32_16x16x32_bf16 v[190:193], v[30:33], v[134:137], 0
	v_mfma_f32_16x16x32_bf16 v[24:27], v[26:29], v[146:149], v[22:25]
	v_mfma_f32_16x16x32_bf16 v[28:31], v[30:33], v[142:145], 0
	v_mfma_f32_16x16x32_bf16 v[154:157], v[34:37], v[122:125], v[154:157]
	v_mfma_f32_16x16x32_bf16 v[182:185], v[34:37], v[130:133], v[182:185]
	v_mfma_f32_16x16x32_bf16 v[190:193], v[34:37], v[138:141], v[190:193]
	v_mfma_f32_16x16x32_bf16 v[28:31], v[34:37], v[146:149], v[28:31]
	s_setprio 0
	s_setprio 1
	v_mfma_f32_16x16x32_bf16 v[32:35], v[38:41], v[74:77], 0
	v_mfma_f32_16x16x32_bf16 v[74:77], v[46:49], v[74:77], 0
	v_mfma_f32_16x16x32_bf16 v[32:35], v[42:45], v[122:125], v[32:35]
	v_mfma_f32_16x16x32_bf16 v[74:77], v[50:53], v[122:125], v[74:77]
	v_mfma_f32_16x16x32_bf16 v[122:125], v[38:41], v[126:129], 0
	v_mfma_f32_16x16x32_bf16 v[126:129], v[46:49], v[126:129], 0
	v_mfma_f32_16x16x32_bf16 v[122:125], v[42:45], v[130:133], v[122:125]
	v_mfma_f32_16x16x32_bf16 v[126:129], v[50:53], v[130:133], v[126:129]
	v_mfma_f32_16x16x32_bf16 v[130:133], v[38:41], v[134:137], 0
	v_mfma_f32_16x16x32_bf16 v[36:39], v[38:41], v[142:145], 0
	v_mfma_f32_16x16x32_bf16 v[130:133], v[42:45], v[138:141], v[130:133]
	v_mfma_f32_16x16x32_bf16 v[134:137], v[46:49], v[134:137], 0
	v_mfma_f32_16x16x32_bf16 v[36:39], v[42:45], v[146:149], v[36:39]
	v_mfma_f32_16x16x32_bf16 v[40:43], v[46:49], v[142:145], 0
	v_mfma_f32_16x16x32_bf16 v[134:137], v[50:53], v[138:141], v[134:137]
	v_mfma_f32_16x16x32_bf16 v[40:43], v[50:53], v[146:149], v[40:43]
	s_setprio 0
	s_barrier
	s_add_i32 s63, 0, 0x18000
	s_add_i32 s64, 0, 0x1c000
	v_add_u32_e32 v21, s63, v16
	v_add_u32_e32 v22, s64, v16
	ds_read_b128 v[44:47], v21
	ds_read_b128 v[48:51], v21 offset:1024
	ds_read_b128 v[138:141], v21 offset:2048
	ds_read_b128 v[142:145], v21 offset:3072
	ds_read_b128 v[146:149], v22
	ds_read_b128 v[194:197], v22 offset:1024
	ds_read_b128 v[198:201], v22 offset:2048
	ds_read_b128 v[202:205], v22 offset:3072
	s_add_u32 s66, s50, 0x18100
	s_addc_u32 s67, s51, 0
	s_mov_b32 m0, s28
	v_lshl_add_u64 v[52:53], s[66:67], 0, v[6:7]
	ds_read_b128 v[220:223], v17 offset:32768
	ds_read_b128 v[228:231], v17 offset:33792
	ds_read_b128 v[232:235], v17 offset:34816
	ds_read_b128 v[236:239], v17 offset:35840
	ds_read_b128 v[240:243], v17 offset:36864
	ds_read_b128 v[244:247], v17 offset:37888
	ds_read_b128 v[248:251], v17 offset:38912
	ds_read_b128 v[174:177], v17 offset:39936
	global_load_lds_dwordx4 v[52:53], off
	v_lshl_add_u64 v[52:53], s[66:67], 0, v[2:3]
	s_mov_b32 m0, s29
	s_nop 0
	global_load_lds_dwordx4 v[52:53], off
	s_waitcnt vmcnt(8)
	s_waitcnt lgkmcnt(0)
	s_barrier
	s_setprio 1
	v_mfma_f32_16x16x32_bf16 v[78:81], v[44:47], v[220:223], v[78:81]
	v_mfma_f32_16x16x32_bf16 v[82:85], v[138:141], v[220:223], v[82:85]
	v_mfma_f32_16x16x32_bf16 v[86:89], v[44:47], v[232:235], v[86:89]
	v_mfma_f32_16x16x32_bf16 v[90:93], v[138:141], v[232:235], v[90:93]
	v_mfma_f32_16x16x32_bf16 v[94:97], v[44:47], v[240:243], v[94:97]
	v_mfma_f32_16x16x32_bf16 v[98:101], v[138:141], v[240:243], v[98:101]
	v_mfma_f32_16x16x32_bf16 v[102:105], v[44:47], v[248:251], v[102:105]
	v_mfma_f32_16x16x32_bf16 v[106:109], v[138:141], v[248:251], v[106:109]
	v_mfma_f32_16x16x32_bf16 v[78:81], v[48:51], v[228:231], v[78:81]
	v_mfma_f32_16x16x32_bf16 v[82:85], v[142:145], v[228:231], v[82:85]
	v_mfma_f32_16x16x32_bf16 v[86:89], v[48:51], v[236:239], v[86:89]
	v_mfma_f32_16x16x32_bf16 v[90:93], v[142:145], v[236:239], v[90:93]
	v_mfma_f32_16x16x32_bf16 v[94:97], v[48:51], v[244:247], v[94:97]
	v_mfma_f32_16x16x32_bf16 v[98:101], v[142:145], v[244:247], v[98:101]
	v_mfma_f32_16x16x32_bf16 v[102:105], v[48:51], v[174:177], v[102:105]
	v_mfma_f32_16x16x32_bf16 v[106:109], v[142:145], v[174:177], v[106:109]
	s_setprio 0
	s_setprio 1
	v_mfma_f32_16x16x32_bf16 v[110:113], v[146:149], v[220:223], v[110:113]
	v_mfma_f32_16x16x32_bf16 v[114:117], v[198:201], v[220:223], v[114:117]
	v_mfma_f32_16x16x32_bf16 v[118:121], v[146:149], v[232:235], v[118:121]
	v_mfma_f32_16x16x32_bf16 v[52:55], v[198:201], v[232:235], v[54:57]
	v_mfma_f32_16x16x32_bf16 v[56:59], v[146:149], v[240:243], v[58:61]
	v_mfma_f32_16x16x32_bf16 v[60:63], v[198:201], v[240:243], v[62:65]
	v_mfma_f32_16x16x32_bf16 v[64:67], v[146:149], v[248:251], v[66:69]
	v_mfma_f32_16x16x32_bf16 v[68:71], v[198:201], v[248:251], v[70:73]
	v_mfma_f32_16x16x32_bf16 v[110:113], v[194:197], v[228:231], v[110:113]
	v_mfma_f32_16x16x32_bf16 v[114:117], v[202:205], v[228:231], v[114:117]
	v_mfma_f32_16x16x32_bf16 v[118:121], v[194:197], v[236:239], v[118:121]
	v_mfma_f32_16x16x32_bf16 v[52:55], v[202:205], v[236:239], v[52:55]
	v_mfma_f32_16x16x32_bf16 v[56:59], v[194:197], v[244:247], v[56:59]
	v_mfma_f32_16x16x32_bf16 v[60:63], v[202:205], v[244:247], v[60:63]
	v_mfma_f32_16x16x32_bf16 v[64:67], v[194:197], v[174:177], v[64:67]
	v_mfma_f32_16x16x32_bf16 v[68:71], v[202:205], v[174:177], v[68:71]
	s_setprio 0
	s_barrier
	s_add_i32 s67, s63, s25
	s_mov_b64 s[70:71], 0x180
	s_add_i32 s63, s67, 0x2000
	v_lshl_add_u64 v[72:73], v[8:9], 0, s[70:71]
	s_mov_b32 m0, s67
	s_add_u32 s68, s52, 0x18180
	ds_read_b128 v[174:177], v17 offset:49152
	ds_read_b128 v[220:223], v17 offset:50176
	ds_read_b128 v[228:231], v17 offset:51200
	ds_read_b128 v[232:235], v17 offset:52224
	ds_read_b128 v[236:239], v17 offset:53248
	ds_read_b128 v[240:243], v17 offset:54272
	ds_read_b128 v[244:247], v17 offset:55296
	ds_read_b128 v[248:251], v17 offset:56320
	global_load_lds_dwordx4 v[72:73], off
	v_lshl_add_u64 v[72:73], v[10:11], 0, s[70:71]
	s_mov_b32 m0, s63
	s_addc_u32 s69, s53, 0
	s_add_i32 s64, s64, s25
	global_load_lds_dwordx4 v[72:73], off
	v_lshl_add_u64 v[72:73], s[68:69], 0, v[4:5]
	s_mov_b32 m0, s64
	s_add_i32 s66, s64, 0x2000
	global_load_lds_dwordx4 v[72:73], off
	v_lshl_add_u64 v[72:73], s[68:69], 0, v[0:1]
	s_mov_b32 m0, s66
	s_nop 0
	global_load_lds_dwordx4 v[72:73], off
	v_lshl_add_u64 v[72:73], v[12:13], 0, s[70:71]
	s_mov_b32 m0, s30
	s_nop 0
	global_load_lds_dwordx4 v[72:73], off
	v_lshl_add_u64 v[72:73], v[14:15], 0, s[70:71]
	s_mov_b32 m0, s31
	s_nop 0
	global_load_lds_dwordx4 v[72:73], off
	s_waitcnt vmcnt(8)
	s_waitcnt lgkmcnt(0)
	s_barrier
	s_setprio 1
	v_mfma_f32_16x16x32_bf16 v[150:153], v[44:47], v[174:177], v[150:153]
	v_mfma_f32_16x16x32_bf16 v[154:157], v[138:141], v[174:177], v[154:157]
	v_mfma_f32_16x16x32_bf16 v[178:181], v[44:47], v[228:231], v[178:181]
	v_mfma_f32_16x16x32_bf16 v[182:185], v[138:141], v[228:231], v[182:185]
	v_mfma_f32_16x16x32_bf16 v[186:189], v[44:47], v[236:239], v[186:189]
	v_mfma_f32_16x16x32_bf16 v[190:193], v[138:141], v[236:239], v[190:193]
	v_mfma_f32_16x16x32_bf16 v[24:27], v[44:47], v[244:247], v[24:27]
	v_mfma_f32_16x16x32_bf16 v[28:31], v[138:141], v[244:247], v[28:31]
	v_mfma_f32_16x16x32_bf16 v[150:153], v[48:51], v[220:223], v[150:153]
	v_mfma_f32_16x16x32_bf16 v[154:157], v[142:145], v[220:223], v[154:157]
	v_mfma_f32_16x16x32_bf16 v[178:181], v[48:51], v[232:235], v[178:181]
	v_mfma_f32_16x16x32_bf16 v[182:185], v[142:145], v[232:235], v[182:185]
	v_mfma_f32_16x16x32_bf16 v[186:189], v[48:51], v[240:243], v[186:189]
	v_mfma_f32_16x16x32_bf16 v[190:193], v[142:145], v[240:243], v[190:193]
	v_mfma_f32_16x16x32_bf16 v[24:27], v[48:51], v[248:251], v[24:27]
	v_mfma_f32_16x16x32_bf16 v[28:31], v[142:145], v[248:251], v[28:31]
	s_setprio 0
	s_setprio 1
	v_mfma_f32_16x16x32_bf16 v[32:35], v[146:149], v[174:177], v[32:35]
	v_mfma_f32_16x16x32_bf16 v[44:47], v[198:201], v[174:177], v[74:77]
	v_mfma_f32_16x16x32_bf16 v[48:51], v[146:149], v[228:231], v[122:125]
	v_mfma_f32_16x16x32_bf16 v[72:75], v[198:201], v[228:231], v[126:129]
	v_mfma_f32_16x16x32_bf16 v[122:125], v[146:149], v[236:239], v[130:133]
	v_mfma_f32_16x16x32_bf16 v[126:129], v[198:201], v[236:239], v[134:137]
	v_mfma_f32_16x16x32_bf16 v[36:39], v[146:149], v[244:247], v[36:39]
	v_mfma_f32_16x16x32_bf16 v[40:43], v[198:201], v[244:247], v[40:43]
	v_mfma_f32_16x16x32_bf16 v[32:35], v[194:197], v[220:223], v[32:35]
	v_mfma_f32_16x16x32_bf16 v[44:47], v[202:205], v[220:223], v[44:47]
	v_mfma_f32_16x16x32_bf16 v[48:51], v[194:197], v[232:235], v[48:51]
	v_mfma_f32_16x16x32_bf16 v[72:75], v[202:205], v[232:235], v[72:75]
	v_mfma_f32_16x16x32_bf16 v[122:125], v[194:197], v[240:243], v[122:125]
	v_mfma_f32_16x16x32_bf16 v[126:129], v[202:205], v[240:243], v[126:129]
	v_mfma_f32_16x16x32_bf16 v[36:39], v[194:197], v[248:251], v[36:39]
	v_mfma_f32_16x16x32_bf16 v[40:43], v[202:205], v[248:251], v[40:43]
	s_setprio 0
	s_barrier
	ds_read_b128 v[130:133], v19
	ds_read_b128 v[134:137], v19 offset:1024
	ds_read_b128 v[138:141], v19 offset:2048
	ds_read_b128 v[142:145], v19 offset:3072
	ds_read_b128 v[146:149], v20
	ds_read_b128 v[174:177], v20 offset:1024
	ds_read_b128 v[194:197], v20 offset:2048
	ds_read_b128 v[198:201], v20 offset:3072
	s_add_u32 s68, s50, 0x18180
	s_addc_u32 s69, s51, 0
	s_mov_b32 m0, s65
	v_lshl_add_u64 v[76:77], s[68:69], 0, v[6:7]
	ds_read_b128 v[202:205], v17
	ds_read_b128 v[220:223], v17 offset:1024
	ds_read_b128 v[228:231], v17 offset:2048
	ds_read_b128 v[232:235], v17 offset:3072
	ds_read_b128 v[236:239], v17 offset:4096
	ds_read_b128 v[240:243], v17 offset:5120
	ds_read_b128 v[244:247], v17 offset:6144
	ds_read_b128 v[248:251], v17 offset:7168
	global_load_lds_dwordx4 v[76:77], off
	v_lshl_add_u64 v[76:77], s[68:69], 0, v[2:3]
	s_mov_b32 m0, s57
	s_nop 0
	global_load_lds_dwordx4 v[76:77], off
	s_waitcnt vmcnt(8)
	s_waitcnt lgkmcnt(0)
	s_barrier
	s_setprio 1
	v_mfma_f32_16x16x32_bf16 v[76:79], v[130:133], v[202:205], v[78:81]
	v_mfma_f32_16x16x32_bf16 v[80:83], v[138:141], v[202:205], v[82:85]
	v_mfma_f32_16x16x32_bf16 v[84:87], v[130:133], v[228:231], v[86:89]
	v_mfma_f32_16x16x32_bf16 v[88:91], v[138:141], v[228:231], v[90:93]
	v_mfma_f32_16x16x32_bf16 v[92:95], v[130:133], v[236:239], v[94:97]
	v_mfma_f32_16x16x32_bf16 v[96:99], v[138:141], v[236:239], v[98:101]
	v_mfma_f32_16x16x32_bf16 v[100:103], v[130:133], v[244:247], v[102:105]
	v_mfma_f32_16x16x32_bf16 v[104:107], v[138:141], v[244:247], v[106:109]
	v_mfma_f32_16x16x32_bf16 v[76:79], v[134:137], v[220:223], v[76:79]
	v_mfma_f32_16x16x32_bf16 v[80:83], v[142:145], v[220:223], v[80:83]
	v_mfma_f32_16x16x32_bf16 v[84:87], v[134:137], v[232:235], v[84:87]
	v_mfma_f32_16x16x32_bf16 v[88:91], v[142:145], v[232:235], v[88:91]
	v_mfma_f32_16x16x32_bf16 v[92:95], v[134:137], v[240:243], v[92:95]
	v_mfma_f32_16x16x32_bf16 v[96:99], v[142:145], v[240:243], v[96:99]
	v_mfma_f32_16x16x32_bf16 v[100:103], v[134:137], v[248:251], v[100:103]
	v_mfma_f32_16x16x32_bf16 v[104:107], v[142:145], v[248:251], v[104:107]
	s_setprio 0
	s_setprio 1
	v_mfma_f32_16x16x32_bf16 v[108:111], v[146:149], v[202:205], v[110:113]
	v_mfma_f32_16x16x32_bf16 v[112:115], v[194:197], v[202:205], v[114:117]
	v_mfma_f32_16x16x32_bf16 v[116:119], v[146:149], v[228:231], v[118:121]
	v_mfma_f32_16x16x32_bf16 v[52:55], v[194:197], v[228:231], v[52:55]
	v_mfma_f32_16x16x32_bf16 v[56:59], v[146:149], v[236:239], v[56:59]
	v_mfma_f32_16x16x32_bf16 v[60:63], v[194:197], v[236:239], v[60:63]
	v_mfma_f32_16x16x32_bf16 v[64:67], v[146:149], v[244:247], v[64:67]
	v_mfma_f32_16x16x32_bf16 v[68:71], v[194:197], v[244:247], v[68:71]
	v_mfma_f32_16x16x32_bf16 v[108:111], v[174:177], v[220:223], v[108:111]
	v_mfma_f32_16x16x32_bf16 v[112:115], v[198:201], v[220:223], v[112:115]
	v_mfma_f32_16x16x32_bf16 v[116:119], v[174:177], v[232:235], v[116:119]
	v_mfma_f32_16x16x32_bf16 v[52:55], v[198:201], v[232:235], v[52:55]
	v_mfma_f32_16x16x32_bf16 v[56:59], v[174:177], v[240:243], v[56:59]
	v_mfma_f32_16x16x32_bf16 v[60:63], v[198:201], v[240:243], v[60:63]
	v_mfma_f32_16x16x32_bf16 v[64:67], v[174:177], v[248:251], v[64:67]
	v_mfma_f32_16x16x32_bf16 v[68:71], v[198:201], v[248:251], v[68:71]
	s_setprio 0
	s_barrier
	s_mov_b64 s[70:71], 0x200
	s_mov_b32 m0, s62
	v_lshl_add_u64 v[120:121], v[8:9], 0, s[70:71]
	s_add_u32 s68, s52, 0x18200
	ds_read_b128 v[202:205], v17 offset:16384
	ds_read_b128 v[220:223], v17 offset:17408
	ds_read_b128 v[228:231], v17 offset:18432
	ds_read_b128 v[232:235], v17 offset:19456
	ds_read_b128 v[236:239], v17 offset:20480
	ds_read_b128 v[240:243], v17 offset:21504
	ds_read_b128 v[244:247], v17 offset:22528
	ds_read_b128 v[248:251], v17 offset:23552
	global_load_lds_dwordx4 v[120:121], off
	v_lshl_add_u64 v[120:121], v[10:11], 0, s[70:71]
	s_mov_b32 m0, s58
	s_addc_u32 s69, s53, 0
	global_load_lds_dwordx4 v[120:121], off
	v_lshl_add_u64 v[120:121], s[68:69], 0, v[4:5]
	s_mov_b32 m0, s59
	s_nop 0
	global_load_lds_dwordx4 v[120:121], off
	v_lshl_add_u64 v[120:121], s[68:69], 0, v[0:1]
	s_mov_b32 m0, s61
	s_nop 0
	global_load_lds_dwordx4 v[120:121], off
	v_lshl_add_u64 v[120:121], v[12:13], 0, s[70:71]
	s_mov_b32 m0, s26
	s_nop 0
	global_load_lds_dwordx4 v[120:121], off
	v_lshl_add_u64 v[120:121], v[14:15], 0, s[70:71]
	s_mov_b32 m0, s27
	s_nop 0
	global_load_lds_dwordx4 v[120:121], off
	s_waitcnt vmcnt(8)
	s_waitcnt lgkmcnt(0)
	s_barrier
	s_setprio 1
	v_mfma_f32_16x16x32_bf16 v[150:153], v[130:133], v[202:205], v[150:153]
	v_mfma_f32_16x16x32_bf16 v[154:157], v[138:141], v[202:205], v[154:157]
	v_mfma_f32_16x16x32_bf16 v[178:181], v[130:133], v[228:231], v[178:181]
	v_mfma_f32_16x16x32_bf16 v[182:185], v[138:141], v[228:231], v[182:185]
	v_mfma_f32_16x16x32_bf16 v[186:189], v[130:133], v[236:239], v[186:189]
	v_mfma_f32_16x16x32_bf16 v[190:193], v[138:141], v[236:239], v[190:193]
	v_mfma_f32_16x16x32_bf16 v[24:27], v[130:133], v[244:247], v[24:27]
	v_mfma_f32_16x16x32_bf16 v[28:31], v[138:141], v[244:247], v[28:31]
	v_mfma_f32_16x16x32_bf16 v[150:153], v[134:137], v[220:223], v[150:153]
	v_mfma_f32_16x16x32_bf16 v[154:157], v[142:145], v[220:223], v[154:157]
	v_mfma_f32_16x16x32_bf16 v[178:181], v[134:137], v[232:235], v[178:181]
	v_mfma_f32_16x16x32_bf16 v[182:185], v[142:145], v[232:235], v[182:185]
	v_mfma_f32_16x16x32_bf16 v[186:189], v[134:137], v[240:243], v[186:189]
	v_mfma_f32_16x16x32_bf16 v[190:193], v[142:145], v[240:243], v[190:193]
	v_mfma_f32_16x16x32_bf16 v[24:27], v[134:137], v[248:251], v[24:27]
	v_mfma_f32_16x16x32_bf16 v[28:31], v[142:145], v[248:251], v[28:31]
	s_setprio 0
	s_setprio 1
	v_mfma_f32_16x16x32_bf16 v[32:35], v[146:149], v[202:205], v[32:35]
	v_mfma_f32_16x16x32_bf16 v[44:47], v[194:197], v[202:205], v[44:47]
	v_mfma_f32_16x16x32_bf16 v[48:51], v[146:149], v[228:231], v[48:51]
	v_mfma_f32_16x16x32_bf16 v[72:75], v[194:197], v[228:231], v[72:75]
	v_mfma_f32_16x16x32_bf16 v[120:123], v[146:149], v[236:239], v[122:125]
	v_mfma_f32_16x16x32_bf16 v[124:127], v[194:197], v[236:239], v[126:129]
	v_mfma_f32_16x16x32_bf16 v[36:39], v[146:149], v[244:247], v[36:39]
	v_mfma_f32_16x16x32_bf16 v[40:43], v[194:197], v[244:247], v[40:43]
	v_mfma_f32_16x16x32_bf16 v[32:35], v[174:177], v[220:223], v[32:35]
	v_mfma_f32_16x16x32_bf16 v[44:47], v[198:201], v[220:223], v[44:47]
	v_mfma_f32_16x16x32_bf16 v[48:51], v[174:177], v[232:235], v[48:51]
	v_mfma_f32_16x16x32_bf16 v[72:75], v[198:201], v[232:235], v[72:75]
	v_mfma_f32_16x16x32_bf16 v[120:123], v[174:177], v[240:243], v[120:123]
	v_mfma_f32_16x16x32_bf16 v[124:127], v[198:201], v[240:243], v[124:127]
	v_mfma_f32_16x16x32_bf16 v[36:39], v[174:177], v[248:251], v[36:39]
	v_mfma_f32_16x16x32_bf16 v[40:43], v[198:201], v[248:251], v[40:43]
	s_setprio 0
	s_barrier
	ds_read_b128 v[128:131], v21
	ds_read_b128 v[132:135], v21 offset:1024
	ds_read_b128 v[136:139], v21 offset:2048
	ds_read_b128 v[140:143], v21 offset:3072
	ds_read_b128 v[144:147], v22
	ds_read_b128 v[174:177], v22 offset:1024
	ds_read_b128 v[194:197], v22 offset:2048
	ds_read_b128 v[198:201], v22 offset:3072
	s_add_u32 s68, s50, 0x18200
	s_addc_u32 s69, s51, 0
	s_mov_b32 m0, s28
	v_lshl_add_u64 v[148:149], s[68:69], 0, v[6:7]
	ds_read_b128 v[202:205], v17 offset:32768
	ds_read_b128 v[220:223], v17 offset:33792
	ds_read_b128 v[228:231], v17 offset:34816
	ds_read_b128 v[232:235], v17 offset:35840
	ds_read_b128 v[236:239], v17 offset:36864
	ds_read_b128 v[240:243], v17 offset:37888
	ds_read_b128 v[244:247], v17 offset:38912
	ds_read_b128 v[248:251], v17 offset:39936
	global_load_lds_dwordx4 v[148:149], off
	v_lshl_add_u64 v[148:149], s[68:69], 0, v[2:3]
	s_mov_b32 m0, s29
	s_nop 0
	global_load_lds_dwordx4 v[148:149], off
	s_waitcnt vmcnt(8)
	s_waitcnt lgkmcnt(0)
	s_barrier
	s_setprio 1
	v_mfma_f32_16x16x32_bf16 v[76:79], v[128:131], v[202:205], v[76:79]
	v_mfma_f32_16x16x32_bf16 v[80:83], v[136:139], v[202:205], v[80:83]
	v_mfma_f32_16x16x32_bf16 v[84:87], v[128:131], v[228:231], v[84:87]
	v_mfma_f32_16x16x32_bf16 v[88:91], v[136:139], v[228:231], v[88:91]
	v_mfma_f32_16x16x32_bf16 v[92:95], v[128:131], v[236:239], v[92:95]
	v_mfma_f32_16x16x32_bf16 v[96:99], v[136:139], v[236:239], v[96:99]
	v_mfma_f32_16x16x32_bf16 v[100:103], v[128:131], v[244:247], v[100:103]
	v_mfma_f32_16x16x32_bf16 v[104:107], v[136:139], v[244:247], v[104:107]
	v_mfma_f32_16x16x32_bf16 v[76:79], v[132:135], v[220:223], v[76:79]
	v_mfma_f32_16x16x32_bf16 v[80:83], v[140:143], v[220:223], v[80:83]
	v_mfma_f32_16x16x32_bf16 v[84:87], v[132:135], v[232:235], v[84:87]
	v_mfma_f32_16x16x32_bf16 v[88:91], v[140:143], v[232:235], v[88:91]
	v_mfma_f32_16x16x32_bf16 v[92:95], v[132:135], v[240:243], v[92:95]
	v_mfma_f32_16x16x32_bf16 v[96:99], v[140:143], v[240:243], v[96:99]
	v_mfma_f32_16x16x32_bf16 v[100:103], v[132:135], v[248:251], v[100:103]
	v_mfma_f32_16x16x32_bf16 v[104:107], v[140:143], v[248:251], v[104:107]
	s_setprio 0
	s_setprio 1
	v_mfma_f32_16x16x32_bf16 v[108:111], v[144:147], v[202:205], v[108:111]
	v_mfma_f32_16x16x32_bf16 v[112:115], v[194:197], v[202:205], v[112:115]
	v_mfma_f32_16x16x32_bf16 v[116:119], v[144:147], v[228:231], v[116:119]
	v_mfma_f32_16x16x32_bf16 v[52:55], v[194:197], v[228:231], v[52:55]
	v_mfma_f32_16x16x32_bf16 v[56:59], v[144:147], v[236:239], v[56:59]
	v_mfma_f32_16x16x32_bf16 v[60:63], v[194:197], v[236:239], v[60:63]
	v_mfma_f32_16x16x32_bf16 v[64:67], v[144:147], v[244:247], v[64:67]
	v_mfma_f32_16x16x32_bf16 v[68:71], v[194:197], v[244:247], v[68:71]
	v_mfma_f32_16x16x32_bf16 v[108:111], v[174:177], v[220:223], v[108:111]
	v_mfma_f32_16x16x32_bf16 v[112:115], v[198:201], v[220:223], v[112:115]
	v_mfma_f32_16x16x32_bf16 v[116:119], v[174:177], v[232:235], v[116:119]
	v_mfma_f32_16x16x32_bf16 v[52:55], v[198:201], v[232:235], v[52:55]
	v_mfma_f32_16x16x32_bf16 v[56:59], v[174:177], v[240:243], v[56:59]
	v_mfma_f32_16x16x32_bf16 v[60:63], v[198:201], v[240:243], v[60:63]
	v_mfma_f32_16x16x32_bf16 v[64:67], v[174:177], v[248:251], v[64:67]
	v_mfma_f32_16x16x32_bf16 v[68:71], v[198:201], v[248:251], v[68:71]
	s_setprio 0
	s_barrier
	s_mov_b64 s[68:69], 0x280
	s_mov_b32 m0, s67
	v_lshl_add_u64 v[8:9], v[8:9], 0, s[68:69]
	s_add_u32 s52, s52, 0x18280
	ds_read_b128 v[202:205], v17 offset:49152
	ds_read_b128 v[220:223], v17 offset:50176
	ds_read_b128 v[228:231], v17 offset:51200
	ds_read_b128 v[232:235], v17 offset:52224
	ds_read_b128 v[236:239], v17 offset:53248
	ds_read_b128 v[240:243], v17 offset:54272
	ds_read_b128 v[244:247], v17 offset:55296
	ds_read_b128 v[248:251], v17 offset:56320
	global_load_lds_dwordx4 v[8:9], off
	v_lshl_add_u64 v[8:9], v[10:11], 0, s[68:69]
	s_mov_b32 m0, s63
	s_addc_u32 s53, s53, 0
	global_load_lds_dwordx4 v[8:9], off
	v_lshl_add_u64 v[8:9], s[52:53], 0, v[4:5]
	s_mov_b32 m0, s64
	s_nop 0
	global_load_lds_dwordx4 v[8:9], off
	v_lshl_add_u64 v[8:9], s[52:53], 0, v[0:1]
	s_mov_b32 m0, s66
	s_nop 0
	global_load_lds_dwordx4 v[8:9], off
	v_lshl_add_u64 v[8:9], v[12:13], 0, s[68:69]
	s_mov_b32 m0, s30
	s_nop 0
	global_load_lds_dwordx4 v[8:9], off
	v_lshl_add_u64 v[8:9], v[14:15], 0, s[68:69]
	s_mov_b32 m0, s31
	s_nop 0
	global_load_lds_dwordx4 v[8:9], off
	s_waitcnt vmcnt(8)
	s_waitcnt lgkmcnt(0)
	s_barrier
	s_setprio 1
	v_mfma_f32_16x16x32_bf16 v[8:11], v[128:131], v[202:205], v[150:153]
	v_mfma_f32_16x16x32_bf16 v[12:15], v[136:139], v[202:205], v[154:157]
	v_mfma_f32_16x16x32_bf16 v[148:151], v[128:131], v[228:231], v[178:181]
	v_mfma_f32_16x16x32_bf16 v[152:155], v[136:139], v[228:231], v[182:185]
	v_mfma_f32_16x16x32_bf16 v[156:159], v[128:131], v[236:239], v[186:189]
	v_mfma_f32_16x16x32_bf16 v[178:181], v[136:139], v[236:239], v[190:193]
	v_mfma_f32_16x16x32_bf16 v[24:27], v[128:131], v[244:247], v[24:27]
	v_mfma_f32_16x16x32_bf16 v[28:31], v[136:139], v[244:247], v[28:31]
	v_mfma_f32_16x16x32_bf16 v[8:11], v[132:135], v[220:223], v[8:11]
	v_mfma_f32_16x16x32_bf16 v[12:15], v[140:143], v[220:223], v[12:15]
	v_mfma_f32_16x16x32_bf16 v[148:151], v[132:135], v[232:235], v[148:151]
	v_mfma_f32_16x16x32_bf16 v[152:155], v[140:143], v[232:235], v[152:155]
	v_mfma_f32_16x16x32_bf16 v[156:159], v[132:135], v[240:243], v[156:159]
	v_mfma_f32_16x16x32_bf16 v[178:181], v[140:143], v[240:243], v[178:181]
	v_mfma_f32_16x16x32_bf16 v[24:27], v[132:135], v[248:251], v[24:27]
	v_mfma_f32_16x16x32_bf16 v[28:31], v[140:143], v[248:251], v[28:31]
	s_setprio 0
	s_setprio 1
	v_mfma_f32_16x16x32_bf16 v[32:35], v[144:147], v[202:205], v[32:35]
	v_mfma_f32_16x16x32_bf16 v[44:47], v[194:197], v[202:205], v[44:47]
	v_mfma_f32_16x16x32_bf16 v[48:51], v[144:147], v[228:231], v[48:51]
	v_mfma_f32_16x16x32_bf16 v[72:75], v[194:197], v[228:231], v[72:75]
	v_mfma_f32_16x16x32_bf16 v[120:123], v[144:147], v[236:239], v[120:123]
	v_mfma_f32_16x16x32_bf16 v[124:127], v[194:197], v[236:239], v[124:127]
	v_mfma_f32_16x16x32_bf16 v[36:39], v[144:147], v[244:247], v[36:39]
	v_mfma_f32_16x16x32_bf16 v[40:43], v[194:197], v[244:247], v[40:43]
	v_mfma_f32_16x16x32_bf16 v[32:35], v[174:177], v[220:223], v[32:35]
	v_mfma_f32_16x16x32_bf16 v[44:47], v[198:201], v[220:223], v[44:47]
	v_mfma_f32_16x16x32_bf16 v[48:51], v[174:177], v[232:235], v[48:51]
	v_mfma_f32_16x16x32_bf16 v[72:75], v[198:201], v[232:235], v[72:75]
	v_mfma_f32_16x16x32_bf16 v[120:123], v[174:177], v[240:243], v[120:123]
	v_mfma_f32_16x16x32_bf16 v[124:127], v[198:201], v[240:243], v[124:127]
	v_mfma_f32_16x16x32_bf16 v[36:39], v[174:177], v[248:251], v[36:39]
	v_mfma_f32_16x16x32_bf16 v[40:43], v[198:201], v[248:251], v[40:43]
	s_setprio 0
	s_barrier
	ds_read_b128 v[128:131], v19
	ds_read_b128 v[132:135], v19 offset:1024
	ds_read_b128 v[136:139], v19 offset:2048
	ds_read_b128 v[140:143], v19 offset:3072
	ds_read_b128 v[144:147], v20
	ds_read_b128 v[174:177], v20 offset:1024
	ds_read_b128 v[182:185], v20 offset:2048
	ds_read_b128 v[186:189], v20 offset:3072
	s_add_u32 s50, s50, 0x18280
	s_addc_u32 s51, s51, 0
	s_mov_b32 m0, s65
	v_lshl_add_u64 v[240:241], s[50:51], 0, v[6:7]
	ds_read_b128 v[190:193], v17
	ds_read_b128 v[194:197], v17 offset:1024
	ds_read_b128 v[198:201], v17 offset:2048
	ds_read_b128 v[202:205], v17 offset:3072
	ds_read_b128 v[220:223], v17 offset:4096
	ds_read_b128 v[228:231], v17 offset:5120
	ds_read_b128 v[232:235], v17 offset:6144
	ds_read_b128 v[236:239], v17 offset:7168
	global_load_lds_dwordx4 v[240:241], off
	v_lshl_add_u64 v[240:241], s[50:51], 0, v[2:3]
	s_mov_b32 m0, s57
	s_nop 0
	global_load_lds_dwordx4 v[240:241], off
	s_waitcnt vmcnt(8)
	s_waitcnt lgkmcnt(0)
	s_barrier
	s_setprio 1
	v_mfma_f32_16x16x32_bf16 v[76:79], v[128:131], v[190:193], v[76:79]
	v_mfma_f32_16x16x32_bf16 v[80:83], v[136:139], v[190:193], v[80:83]
	v_mfma_f32_16x16x32_bf16 v[84:87], v[128:131], v[198:201], v[84:87]
	v_mfma_f32_16x16x32_bf16 v[88:91], v[136:139], v[198:201], v[88:91]
	v_mfma_f32_16x16x32_bf16 v[92:95], v[128:131], v[220:223], v[92:95]
	v_mfma_f32_16x16x32_bf16 v[96:99], v[136:139], v[220:223], v[96:99]
	v_mfma_f32_16x16x32_bf16 v[100:103], v[128:131], v[232:235], v[100:103]
	v_mfma_f32_16x16x32_bf16 v[104:107], v[136:139], v[232:235], v[104:107]
	v_mfma_f32_16x16x32_bf16 v[76:79], v[132:135], v[194:197], v[76:79]
	v_mfma_f32_16x16x32_bf16 v[80:83], v[140:143], v[194:197], v[80:83]
	v_mfma_f32_16x16x32_bf16 v[84:87], v[132:135], v[202:205], v[84:87]
	v_mfma_f32_16x16x32_bf16 v[88:91], v[140:143], v[202:205], v[88:91]
	v_mfma_f32_16x16x32_bf16 v[92:95], v[132:135], v[228:231], v[92:95]
	v_mfma_f32_16x16x32_bf16 v[96:99], v[140:143], v[228:231], v[96:99]
	v_mfma_f32_16x16x32_bf16 v[100:103], v[132:135], v[236:239], v[100:103]
	v_mfma_f32_16x16x32_bf16 v[104:107], v[140:143], v[236:239], v[104:107]
	s_setprio 0
	s_setprio 1
	v_mfma_f32_16x16x32_bf16 v[108:111], v[144:147], v[190:193], v[108:111]
	v_mfma_f32_16x16x32_bf16 v[112:115], v[182:185], v[190:193], v[112:115]
	v_mfma_f32_16x16x32_bf16 v[116:119], v[144:147], v[198:201], v[116:119]
	v_mfma_f32_16x16x32_bf16 v[52:55], v[182:185], v[198:201], v[52:55]
	v_mfma_f32_16x16x32_bf16 v[56:59], v[144:147], v[220:223], v[56:59]
	v_mfma_f32_16x16x32_bf16 v[60:63], v[182:185], v[220:223], v[60:63]
	v_mfma_f32_16x16x32_bf16 v[64:67], v[144:147], v[232:235], v[64:67]
	v_mfma_f32_16x16x32_bf16 v[68:71], v[182:185], v[232:235], v[68:71]
	v_mfma_f32_16x16x32_bf16 v[108:111], v[174:177], v[194:197], v[108:111]
	v_mfma_f32_16x16x32_bf16 v[112:115], v[186:189], v[194:197], v[112:115]
	v_mfma_f32_16x16x32_bf16 v[116:119], v[174:177], v[202:205], v[116:119]
	v_mfma_f32_16x16x32_bf16 v[52:55], v[186:189], v[202:205], v[52:55]
	v_mfma_f32_16x16x32_bf16 v[56:59], v[174:177], v[228:231], v[56:59]
	v_mfma_f32_16x16x32_bf16 v[60:63], v[186:189], v[228:231], v[60:63]
	v_mfma_f32_16x16x32_bf16 v[64:67], v[174:177], v[236:239], v[64:67]
	v_mfma_f32_16x16x32_bf16 v[68:71], v[186:189], v[236:239], v[68:71]
	s_setprio 0
	s_barrier
	s_mov_b32 m0, s62
	v_lshl_add_u64 v[240:241], s[44:45], 0, v[4:5]
	s_add_u32 s50, s44, 0x18000
	ds_read_b128 v[190:193], v17 offset:16384
	ds_read_b128 v[194:197], v17 offset:17408
	ds_read_b128 v[198:201], v17 offset:18432
	ds_read_b128 v[202:205], v17 offset:19456
	ds_read_b128 v[220:223], v17 offset:20480
	ds_read_b128 v[228:231], v17 offset:21504
	ds_read_b128 v[232:235], v17 offset:22528
	ds_read_b128 v[236:239], v17 offset:23552
	global_load_lds_dwordx4 v[240:241], off
	v_lshl_add_u64 v[242:243], s[44:45], 0, v[0:1]
	s_mov_b32 m0, s58
	s_addc_u32 s51, s45, 0
	global_load_lds_dwordx4 v[242:243], off
	v_lshl_add_u64 v[244:245], s[50:51], 0, v[4:5]
	s_mov_b32 m0, s59
	v_lshl_add_u64 v[246:247], s[42:43], 0, v[2:3]
	global_load_lds_dwordx4 v[244:245], off
	v_lshl_add_u64 v[244:245], s[50:51], 0, v[0:1]
	s_mov_b32 m0, s61
	s_nop 0
	global_load_lds_dwordx4 v[244:245], off
	v_lshl_add_u64 v[244:245], s[42:43], 0, v[6:7]
	s_mov_b32 m0, s26
	s_nop 0
	global_load_lds_dwordx4 v[244:245], off
	s_mov_b32 m0, s27
	s_nop 0
	global_load_lds_dwordx4 v[246:247], off
	s_waitcnt vmcnt(8)
	s_waitcnt lgkmcnt(0)
	s_barrier
	s_setprio 1
	v_mfma_f32_16x16x32_bf16 v[8:11], v[128:131], v[190:193], v[8:11]
	v_mfma_f32_16x16x32_bf16 v[12:15], v[136:139], v[190:193], v[12:15]
	v_mfma_f32_16x16x32_bf16 v[148:151], v[128:131], v[198:201], v[148:151]
	v_mfma_f32_16x16x32_bf16 v[152:155], v[136:139], v[198:201], v[152:155]
	v_mfma_f32_16x16x32_bf16 v[156:159], v[128:131], v[220:223], v[156:159]
	v_mfma_f32_16x16x32_bf16 v[178:181], v[136:139], v[220:223], v[178:181]
	v_mfma_f32_16x16x32_bf16 v[24:27], v[128:131], v[232:235], v[24:27]
	v_mfma_f32_16x16x32_bf16 v[28:31], v[136:139], v[232:235], v[28:31]
	v_mfma_f32_16x16x32_bf16 v[8:11], v[132:135], v[194:197], v[8:11]
	v_mfma_f32_16x16x32_bf16 v[12:15], v[140:143], v[194:197], v[12:15]
	v_mfma_f32_16x16x32_bf16 v[148:151], v[132:135], v[202:205], v[148:151]
	v_mfma_f32_16x16x32_bf16 v[152:155], v[140:143], v[202:205], v[152:155]
	v_mfma_f32_16x16x32_bf16 v[156:159], v[132:135], v[228:231], v[156:159]
	v_mfma_f32_16x16x32_bf16 v[178:181], v[140:143], v[228:231], v[178:181]
	v_mfma_f32_16x16x32_bf16 v[24:27], v[132:135], v[236:239], v[24:27]
	v_mfma_f32_16x16x32_bf16 v[28:31], v[140:143], v[236:239], v[28:31]
	s_setprio 0
	s_setprio 1
	v_mfma_f32_16x16x32_bf16 v[32:35], v[144:147], v[190:193], v[32:35]
	v_mfma_f32_16x16x32_bf16 v[44:47], v[182:185], v[190:193], v[44:47]
	v_mfma_f32_16x16x32_bf16 v[48:51], v[144:147], v[198:201], v[48:51]
	v_mfma_f32_16x16x32_bf16 v[72:75], v[182:185], v[198:201], v[72:75]
	v_mfma_f32_16x16x32_bf16 v[120:123], v[144:147], v[220:223], v[120:123]
	v_mfma_f32_16x16x32_bf16 v[124:127], v[182:185], v[220:223], v[124:127]
	v_mfma_f32_16x16x32_bf16 v[36:39], v[144:147], v[232:235], v[36:39]
	v_mfma_f32_16x16x32_bf16 v[40:43], v[182:185], v[232:235], v[40:43]
	v_mfma_f32_16x16x32_bf16 v[32:35], v[174:177], v[194:197], v[32:35]
	v_mfma_f32_16x16x32_bf16 v[44:47], v[186:189], v[194:197], v[44:47]
	v_mfma_f32_16x16x32_bf16 v[48:51], v[174:177], v[202:205], v[48:51]
	v_mfma_f32_16x16x32_bf16 v[72:75], v[186:189], v[202:205], v[72:75]
	v_mfma_f32_16x16x32_bf16 v[120:123], v[174:177], v[228:231], v[120:123]
	v_mfma_f32_16x16x32_bf16 v[124:127], v[186:189], v[228:231], v[124:127]
	v_mfma_f32_16x16x32_bf16 v[36:39], v[174:177], v[236:239], v[36:39]
	v_mfma_f32_16x16x32_bf16 v[40:43], v[186:189], v[236:239], v[40:43]
	s_setprio 0
	s_barrier
	ds_read_b128 v[128:131], v21
	ds_read_b128 v[132:135], v21 offset:1024
	ds_read_b128 v[136:139], v21 offset:2048
	ds_read_b128 v[140:143], v21 offset:3072
	ds_read_b128 v[144:147], v22
	ds_read_b128 v[174:177], v22 offset:1024
	ds_read_b128 v[182:185], v22 offset:2048
	ds_read_b128 v[20:23], v22 offset:3072
	s_add_u32 s50, s42, 0x18000
	s_addc_u32 s51, s43, 0
	s_mov_b32 m0, s28
	v_lshl_add_u64 v[236:237], s[50:51], 0, v[6:7]
	ds_read_b128 v[186:189], v17 offset:32768
	ds_read_b128 v[190:193], v17 offset:33792
	ds_read_b128 v[194:197], v17 offset:34816
	ds_read_b128 v[198:201], v17 offset:35840
	ds_read_b128 v[202:205], v17 offset:36864
	ds_read_b128 v[220:223], v17 offset:37888
	ds_read_b128 v[228:231], v17 offset:38912
	ds_read_b128 v[232:235], v17 offset:39936
	global_load_lds_dwordx4 v[236:237], off
	v_lshl_add_u64 v[236:237], s[50:51], 0, v[2:3]
	s_mov_b32 m0, s29
	s_nop 0
	global_load_lds_dwordx4 v[236:237], off
	s_waitcnt vmcnt(8)
	s_waitcnt lgkmcnt(0)
	s_barrier
	s_setprio 1
	v_mfma_f32_16x16x32_bf16 v[76:79], v[128:131], v[186:189], v[76:79]
	v_mfma_f32_16x16x32_bf16 v[80:83], v[136:139], v[186:189], v[80:83]
	v_mfma_f32_16x16x32_bf16 v[84:87], v[128:131], v[194:197], v[84:87]
	v_mfma_f32_16x16x32_bf16 v[88:91], v[136:139], v[194:197], v[88:91]
	v_mfma_f32_16x16x32_bf16 v[92:95], v[128:131], v[202:205], v[92:95]
	v_mfma_f32_16x16x32_bf16 v[96:99], v[136:139], v[202:205], v[96:99]
	v_mfma_f32_16x16x32_bf16 v[100:103], v[128:131], v[228:231], v[100:103]
	v_mfma_f32_16x16x32_bf16 v[104:107], v[136:139], v[228:231], v[104:107]
	v_mfma_f32_16x16x32_bf16 v[76:79], v[132:135], v[190:193], v[76:79]
	v_mfma_f32_16x16x32_bf16 v[80:83], v[140:143], v[190:193], v[80:83]
	v_mfma_f32_16x16x32_bf16 v[84:87], v[132:135], v[198:201], v[84:87]
	v_mfma_f32_16x16x32_bf16 v[88:91], v[140:143], v[198:201], v[88:91]
	v_mfma_f32_16x16x32_bf16 v[92:95], v[132:135], v[220:223], v[92:95]
	v_mfma_f32_16x16x32_bf16 v[96:99], v[140:143], v[220:223], v[96:99]
	v_mfma_f32_16x16x32_bf16 v[100:103], v[132:135], v[232:235], v[100:103]
	v_mfma_f32_16x16x32_bf16 v[104:107], v[140:143], v[232:235], v[104:107]
	s_setprio 0
	s_setprio 1
	v_mfma_f32_16x16x32_bf16 v[108:111], v[144:147], v[186:189], v[108:111]
	v_mfma_f32_16x16x32_bf16 v[112:115], v[182:185], v[186:189], v[112:115]
	v_mfma_f32_16x16x32_bf16 v[116:119], v[144:147], v[194:197], v[116:119]
	v_mfma_f32_16x16x32_bf16 v[52:55], v[182:185], v[194:197], v[52:55]
	v_mfma_f32_16x16x32_bf16 v[56:59], v[144:147], v[202:205], v[56:59]
	v_mfma_f32_16x16x32_bf16 v[60:63], v[182:185], v[202:205], v[60:63]
	v_mfma_f32_16x16x32_bf16 v[64:67], v[144:147], v[228:231], v[64:67]
	v_mfma_f32_16x16x32_bf16 v[68:71], v[182:185], v[228:231], v[68:71]
	v_mfma_f32_16x16x32_bf16 v[108:111], v[174:177], v[190:193], v[108:111]
	v_mfma_f32_16x16x32_bf16 v[112:115], v[20:23], v[190:193], v[112:115]
	v_mfma_f32_16x16x32_bf16 v[116:119], v[174:177], v[198:201], v[116:119]
	v_mfma_f32_16x16x32_bf16 v[52:55], v[20:23], v[198:201], v[52:55]
	v_mfma_f32_16x16x32_bf16 v[56:59], v[174:177], v[220:223], v[56:59]
	v_mfma_f32_16x16x32_bf16 v[60:63], v[20:23], v[220:223], v[60:63]
	v_mfma_f32_16x16x32_bf16 v[64:67], v[174:177], v[232:235], v[64:67]
	v_mfma_f32_16x16x32_bf16 v[68:71], v[20:23], v[232:235], v[68:71]
	s_setprio 0
	s_barrier
	s_mov_b32 m0, s67
	v_lshl_add_u64 v[236:237], v[240:241], 0, s[4:5]
	s_add_u32 s50, s44, 0x18080
	ds_read_b128 v[186:189], v17 offset:49152
	ds_read_b128 v[190:193], v17 offset:50176
	ds_read_b128 v[194:197], v17 offset:51200
	ds_read_b128 v[198:201], v17 offset:52224
	ds_read_b128 v[202:205], v17 offset:53248
	ds_read_b128 v[220:223], v17 offset:54272
	ds_read_b128 v[228:231], v17 offset:55296
	ds_read_b128 v[232:235], v17 offset:56320
	global_load_lds_dwordx4 v[236:237], off
	v_lshl_add_u64 v[236:237], v[242:243], 0, s[4:5]
	s_mov_b32 m0, s63
	s_addc_u32 s51, s45, 0
	global_load_lds_dwordx4 v[236:237], off
	v_lshl_add_u64 v[236:237], s[50:51], 0, v[4:5]
	s_mov_b32 m0, s64
	s_nop 0
	global_load_lds_dwordx4 v[236:237], off
	v_lshl_add_u64 v[236:237], s[50:51], 0, v[0:1]
	s_mov_b32 m0, s66
	s_nop 0
	global_load_lds_dwordx4 v[236:237], off
	v_lshl_add_u64 v[236:237], v[244:245], 0, s[4:5]
	s_mov_b32 m0, s30
	s_nop 0
	global_load_lds_dwordx4 v[236:237], off
	v_lshl_add_u64 v[236:237], v[246:247], 0, s[4:5]
	s_mov_b32 m0, s31
	s_nop 0
	global_load_lds_dwordx4 v[236:237], off
	s_waitcnt vmcnt(8)
	s_waitcnt lgkmcnt(0)
	s_barrier
	s_setprio 1
	v_mfma_f32_16x16x32_bf16 v[8:11], v[128:131], v[186:189], v[8:11]
	v_mfma_f32_16x16x32_bf16 v[12:15], v[136:139], v[186:189], v[12:15]
	v_mfma_f32_16x16x32_bf16 v[148:151], v[128:131], v[194:197], v[148:151]
	v_mfma_f32_16x16x32_bf16 v[152:155], v[136:139], v[194:197], v[152:155]
	v_mfma_f32_16x16x32_bf16 v[156:159], v[128:131], v[202:205], v[156:159]
	v_mfma_f32_16x16x32_bf16 v[178:181], v[136:139], v[202:205], v[178:181]
	v_mfma_f32_16x16x32_bf16 v[24:27], v[128:131], v[228:231], v[24:27]
	v_mfma_f32_16x16x32_bf16 v[28:31], v[136:139], v[228:231], v[28:31]
	v_mfma_f32_16x16x32_bf16 v[8:11], v[132:135], v[190:193], v[8:11]
	v_mfma_f32_16x16x32_bf16 v[12:15], v[140:143], v[190:193], v[12:15]
	v_mfma_f32_16x16x32_bf16 v[148:151], v[132:135], v[198:201], v[148:151]
	v_mfma_f32_16x16x32_bf16 v[152:155], v[140:143], v[198:201], v[152:155]
	v_mfma_f32_16x16x32_bf16 v[156:159], v[132:135], v[220:223], v[156:159]
	v_mfma_f32_16x16x32_bf16 v[178:181], v[140:143], v[220:223], v[178:181]
	v_mfma_f32_16x16x32_bf16 v[24:27], v[132:135], v[232:235], v[24:27]
	v_mfma_f32_16x16x32_bf16 v[28:31], v[140:143], v[232:235], v[28:31]
	s_setprio 0
	s_setprio 1
	v_mfma_f32_16x16x32_bf16 v[32:35], v[144:147], v[186:189], v[32:35]
	v_mfma_f32_16x16x32_bf16 v[44:47], v[182:185], v[186:189], v[44:47]
	v_mfma_f32_16x16x32_bf16 v[48:51], v[144:147], v[194:197], v[48:51]
	v_mfma_f32_16x16x32_bf16 v[72:75], v[182:185], v[194:197], v[72:75]
	v_mfma_f32_16x16x32_bf16 v[120:123], v[144:147], v[202:205], v[120:123]
	v_mfma_f32_16x16x32_bf16 v[124:127], v[182:185], v[202:205], v[124:127]
	v_mfma_f32_16x16x32_bf16 v[36:39], v[144:147], v[228:231], v[36:39]
	v_mfma_f32_16x16x32_bf16 v[40:43], v[182:185], v[228:231], v[40:43]
	v_mfma_f32_16x16x32_bf16 v[32:35], v[174:177], v[190:193], v[32:35]
	v_mfma_f32_16x16x32_bf16 v[44:47], v[20:23], v[190:193], v[44:47]
	v_mfma_f32_16x16x32_bf16 v[48:51], v[174:177], v[198:201], v[48:51]
	v_mfma_f32_16x16x32_bf16 v[72:75], v[20:23], v[198:201], v[72:75]
	v_mfma_f32_16x16x32_bf16 v[120:123], v[174:177], v[220:223], v[120:123]
	v_mfma_f32_16x16x32_bf16 v[124:127], v[20:23], v[220:223], v[124:127]
	v_mfma_f32_16x16x32_bf16 v[36:39], v[174:177], v[232:235], v[36:39]
	v_mfma_f32_16x16x32_bf16 v[20:23], v[20:23], v[232:235], v[40:43]
	s_setprio 0
	s_barrier
	s_lshl_b32 s50, s55, 8
	s_lshl_b32 s51, s56, 19
	s_add_i32 s50, s50, s51
	v_add_u32_e32 v162, s50, v18
	v_lshl_add_u64 v[128:129], v[162:163], 1, s[46:47]
	v_cvt_pk_bf16_f32 v40, v76, v77
	v_cvt_pk_bf16_f32 v41, v78, v79
	v_cvt_pk_bf16_f32 v42, v80, v81
	v_cvt_pk_bf16_f32 v43, v82, v83
	global_store_dwordx4 v[128:129], v[40:43], off
	v_cvt_pk_bf16_f32 v8, v8, v9
	v_cvt_pk_bf16_f32 v9, v10, v11
	v_cvt_pk_bf16_f32 v40, v108, v109
	v_cvt_pk_bf16_f32 v41, v110, v111
	v_cvt_pk_bf16_f32 v42, v112, v113
	v_cvt_pk_bf16_f32 v43, v114, v115
	global_store_dwordx4 v[128:129], v[40:43], off offset:256
	v_cvt_pk_bf16_f32 v10, v12, v13
	v_cvt_pk_bf16_f32 v11, v14, v15
	v_add_u32_e32 v40, 0x8000, v162
	v_mov_b32_e32 v41, v163
	v_lshl_add_u64 v[76:77], v[40:41], 1, s[46:47]
	v_cvt_pk_bf16_f32 v40, v84, v85
	v_cvt_pk_bf16_f32 v41, v86, v87
	v_cvt_pk_bf16_f32 v42, v88, v89
	v_cvt_pk_bf16_f32 v43, v90, v91
	global_store_dwordx4 v[76:77], v[40:43], off
	s_add_i32 s54, s54, s82
	s_andn2_b64 vcc, exec, s[40:41]
	v_cvt_pk_bf16_f32 v40, v116, v117
	v_cvt_pk_bf16_f32 v41, v118, v119
	v_cvt_pk_bf16_f32 v42, v52, v53
	v_cvt_pk_bf16_f32 v43, v54, v55
	global_store_dwordx4 v[76:77], v[40:43], off offset:256
	s_mov_b32 s55, s6
	s_mov_b32 s56, s7
	v_add_u32_e32 v40, 0x10000, v162
	v_mov_b32_e32 v41, v163
	v_lshl_add_u64 v[52:53], v[40:41], 1, s[46:47]
	v_cvt_pk_bf16_f32 v40, v92, v93
	v_cvt_pk_bf16_f32 v41, v94, v95
	v_cvt_pk_bf16_f32 v42, v96, v97
	v_cvt_pk_bf16_f32 v43, v98, v99
	global_store_dwordx4 v[52:53], v[40:43], off
	s_mov_b64 s[52:53], s[44:45]
	s_mov_b64 s[50:51], s[42:43]
	v_cvt_pk_bf16_f32 v40, v56, v57
	v_cvt_pk_bf16_f32 v41, v58, v59
	v_cvt_pk_bf16_f32 v42, v60, v61
	v_cvt_pk_bf16_f32 v43, v62, v63
	global_store_dwordx4 v[52:53], v[40:43], off offset:256
	s_nop 1
	v_add_u32_e32 v40, 0x18000, v162
	v_mov_b32_e32 v41, v163
	v_lshl_add_u64 v[52:53], v[40:41], 1, s[46:47]
	v_cvt_pk_bf16_f32 v40, v100, v101
	v_cvt_pk_bf16_f32 v41, v102, v103
	v_cvt_pk_bf16_f32 v42, v104, v105
	v_cvt_pk_bf16_f32 v43, v106, v107
	global_store_dwordx4 v[52:53], v[40:43], off
	s_nop 1
	v_cvt_pk_bf16_f32 v40, v64, v65
	v_cvt_pk_bf16_f32 v41, v66, v67
	v_cvt_pk_bf16_f32 v42, v68, v69
	v_cvt_pk_bf16_f32 v43, v70, v71
	global_store_dwordx4 v[52:53], v[40:43], off offset:256
	s_nop 1
	v_add_u32_e32 v40, 0x40000, v162
	v_mov_b32_e32 v41, v163
	v_lshl_add_u64 v[40:41], v[40:41], 1, s[46:47]
	global_store_dwordx4 v[40:41], v[8:11], off
	s_nop 1
	v_cvt_pk_bf16_f32 v8, v32, v33
	v_cvt_pk_bf16_f32 v9, v34, v35
	v_cvt_pk_bf16_f32 v10, v44, v45
	v_cvt_pk_bf16_f32 v11, v46, v47
	global_store_dwordx4 v[40:41], v[8:11], off offset:256
	s_nop 1
	v_add_u32_e32 v8, 0x48000, v162
	v_mov_b32_e32 v9, v163
	v_lshl_add_u64 v[12:13], v[8:9], 1, s[46:47]
	v_cvt_pk_bf16_f32 v8, v148, v149
	v_cvt_pk_bf16_f32 v9, v150, v151
	v_cvt_pk_bf16_f32 v10, v152, v153
	v_cvt_pk_bf16_f32 v11, v154, v155
	global_store_dwordx4 v[12:13], v[8:11], off
	s_nop 1
	v_cvt_pk_bf16_f32 v8, v48, v49
	v_cvt_pk_bf16_f32 v9, v50, v51
	v_cvt_pk_bf16_f32 v10, v72, v73
	v_cvt_pk_bf16_f32 v11, v74, v75
	global_store_dwordx4 v[12:13], v[8:11], off offset:256
	s_nop 1
	v_add_u32_e32 v8, 0x50000, v162
	v_mov_b32_e32 v9, v163
	v_lshl_add_u64 v[12:13], v[8:9], 1, s[46:47]
	v_cvt_pk_bf16_f32 v8, v156, v157
	v_cvt_pk_bf16_f32 v9, v158, v159
	v_cvt_pk_bf16_f32 v10, v178, v179
	v_cvt_pk_bf16_f32 v11, v180, v181
	global_store_dwordx4 v[12:13], v[8:11], off
	v_add_u32_e32 v162, 0x58000, v162
	s_nop 0
	v_cvt_pk_bf16_f32 v8, v120, v121
	v_cvt_pk_bf16_f32 v9, v122, v123
	v_cvt_pk_bf16_f32 v10, v124, v125
	v_cvt_pk_bf16_f32 v11, v126, v127
	global_store_dwordx4 v[12:13], v[8:11], off offset:256
	v_lshl_add_u64 v[12:13], v[162:163], 1, s[46:47]
	s_nop 0
	v_cvt_pk_bf16_f32 v8, v24, v25
	v_cvt_pk_bf16_f32 v9, v26, v27
	v_cvt_pk_bf16_f32 v10, v28, v29
	v_cvt_pk_bf16_f32 v11, v30, v31
	global_store_dwordx4 v[12:13], v[8:11], off
	s_nop 1
	v_cvt_pk_bf16_f32 v8, v36, v37
	v_cvt_pk_bf16_f32 v9, v38, v39
	v_cvt_pk_bf16_f32 v10, v20, v21
	v_cvt_pk_bf16_f32 v11, v22, v23
	global_store_dwordx4 v[12:13], v[8:11], off offset:256
	s_cbranch_vccz .LBB0_513

.LBB0_771:
	s_add_u32 s55, s60, 0xfffc0080
	s_addc_u32 s62, s61, -1
	s_add_i32 s72, 0, 0x10000
	s_cmp_eq_u32 s53, 12
	s_cselect_b32 s65, s6, s62
	s_cselect_b32 s64, s7, s55
	s_cselect_b32 s63, s28, s31
	s_cselect_b32 s62, s29, s30
	s_add_i32 s55, 0, 0x14000
	v_add_u32_e32 v156, s72, v145
	v_add_u32_e32 v162, s55, v145
	ds_read_b128 v[140:143], v156
	ds_read_b128 v[148:151], v156 offset:1024
	ds_read_b128 v[152:155], v156 offset:2048
	ds_read_b128 v[156:159], v156 offset:3072
	ds_read_b128 v[174:177], v162
	ds_read_b128 v[178:181], v162 offset:1024
	ds_read_b128 v[182:185], v162 offset:2048
	ds_read_b128 v[186:189], v162 offset:3072
	v_lshl_add_u64 v[240:241], s[60:61], 0, v[136:137]
	s_add_i32 m0, s25, 0xc000
	ds_read_b128 v[190:193], v147
	ds_read_b128 v[194:197], v147 offset:1024
	ds_read_b128 v[198:201], v147 offset:2048
	ds_read_b128 v[202:205], v147 offset:3072
	ds_read_b128 v[220:223], v147 offset:4096
	ds_read_b128 v[228:231], v147 offset:5120
	ds_read_b128 v[232:235], v147 offset:6144
	ds_read_b128 v[236:239], v147 offset:7168
	global_load_lds_dwordx4 v[240:241], off
	v_lshl_add_u64 v[240:241], s[60:61], 0, v[138:139]
	s_add_i32 m0, s25, 0xe000
	s_nop 0
	global_load_lds_dwordx4 v[240:241], off
	s_waitcnt vmcnt(8)
	s_waitcnt lgkmcnt(0)
	s_barrier
	s_setprio 1
	v_mfma_f32_16x16x32_bf16 v[124:127], v[140:143], v[190:193], v[124:127]
	v_mfma_f32_16x16x32_bf16 v[120:123], v[152:155], v[190:193], v[120:123]
	v_mfma_f32_16x16x32_bf16 v[108:111], v[140:143], v[198:201], v[108:111]
	v_mfma_f32_16x16x32_bf16 v[104:107], v[152:155], v[198:201], v[104:107]
	v_mfma_f32_16x16x32_bf16 v[92:95], v[140:143], v[220:223], v[92:95]
	v_mfma_f32_16x16x32_bf16 v[88:91], v[152:155], v[220:223], v[88:91]
	v_mfma_f32_16x16x32_bf16 v[76:79], v[140:143], v[232:235], v[76:79]
	v_mfma_f32_16x16x32_bf16 v[72:75], v[152:155], v[232:235], v[72:75]
	v_mfma_f32_16x16x32_bf16 v[124:127], v[148:151], v[194:197], v[124:127]
	v_mfma_f32_16x16x32_bf16 v[120:123], v[156:159], v[194:197], v[120:123]
	v_mfma_f32_16x16x32_bf16 v[108:111], v[148:151], v[202:205], v[108:111]
	v_mfma_f32_16x16x32_bf16 v[104:107], v[156:159], v[202:205], v[104:107]
	v_mfma_f32_16x16x32_bf16 v[92:95], v[148:151], v[228:231], v[92:95]
	v_mfma_f32_16x16x32_bf16 v[88:91], v[156:159], v[228:231], v[88:91]
	v_mfma_f32_16x16x32_bf16 v[76:79], v[148:151], v[236:239], v[76:79]
	v_mfma_f32_16x16x32_bf16 v[72:75], v[156:159], v[236:239], v[72:75]
	s_setprio 0
	s_setprio 1
	v_mfma_f32_16x16x32_bf16 v[116:119], v[174:177], v[190:193], v[116:119]
	v_mfma_f32_16x16x32_bf16 v[112:115], v[182:185], v[190:193], v[112:115]
	v_mfma_f32_16x16x32_bf16 v[100:103], v[174:177], v[198:201], v[100:103]
	v_mfma_f32_16x16x32_bf16 v[96:99], v[182:185], v[198:201], v[96:99]
	v_mfma_f32_16x16x32_bf16 v[84:87], v[174:177], v[220:223], v[84:87]
	v_mfma_f32_16x16x32_bf16 v[80:83], v[182:185], v[220:223], v[80:83]
	v_mfma_f32_16x16x32_bf16 v[68:71], v[174:177], v[232:235], v[68:71]
	v_mfma_f32_16x16x32_bf16 v[64:67], v[182:185], v[232:235], v[64:67]
	v_mfma_f32_16x16x32_bf16 v[116:119], v[178:181], v[194:197], v[116:119]
	v_mfma_f32_16x16x32_bf16 v[112:115], v[186:189], v[194:197], v[112:115]
	v_mfma_f32_16x16x32_bf16 v[100:103], v[178:181], v[202:205], v[100:103]
	v_mfma_f32_16x16x32_bf16 v[96:99], v[186:189], v[202:205], v[96:99]
	v_mfma_f32_16x16x32_bf16 v[84:87], v[178:181], v[228:231], v[84:87]
	v_mfma_f32_16x16x32_bf16 v[80:83], v[186:189], v[228:231], v[80:83]
	v_mfma_f32_16x16x32_bf16 v[68:71], v[178:181], v[236:239], v[68:71]
	v_mfma_f32_16x16x32_bf16 v[64:67], v[186:189], v[236:239], v[64:67]
	s_setprio 0
	s_barrier
	s_add_i32 s72, s72, s24
	v_lshl_add_u64 v[240:241], s[62:63], 0, v[132:133]
	s_mov_b32 m0, s72
	ds_read_b128 v[190:193], v147 offset:16384
	ds_read_b128 v[194:197], v147 offset:17408
	ds_read_b128 v[198:201], v147 offset:18432
	ds_read_b128 v[202:205], v147 offset:19456
	ds_read_b128 v[220:223], v147 offset:20480
	ds_read_b128 v[228:231], v147 offset:21504
	ds_read_b128 v[232:235], v147 offset:22528
	ds_read_b128 v[236:239], v147 offset:23552
	global_load_lds_dwordx4 v[240:241], off
	s_add_i32 m0, s72, 0x2000
	s_add_u32 s72, s62, 0x40000
	v_lshl_add_u64 v[242:243], s[62:63], 0, v[128:129]
	s_addc_u32 s73, s63, 0
	s_add_i32 s55, s55, s24
	global_load_lds_dwordx4 v[242:243], off
	v_lshl_add_u64 v[244:245], s[72:73], 0, v[132:133]
	s_mov_b32 m0, s55
	v_lshl_add_u64 v[246:247], s[64:65], 0, v[130:131]
	global_load_lds_dwordx4 v[244:245], off
	v_lshl_add_u64 v[244:245], s[72:73], 0, v[128:129]
	s_add_i32 m0, s55, 0x2000
	s_nop 0
	global_load_lds_dwordx4 v[244:245], off
	v_lshl_add_u64 v[244:245], s[64:65], 0, v[134:135]
	s_mov_b32 m0, s25
	s_nop 0
	global_load_lds_dwordx4 v[244:245], off
	s_mov_b32 m0, s66
	s_nop 0
	global_load_lds_dwordx4 v[246:247], off
	s_waitcnt vmcnt(8)
	s_waitcnt lgkmcnt(0)
	s_barrier
	s_setprio 1
	v_mfma_f32_16x16x32_bf16 v[60:63], v[140:143], v[190:193], v[60:63]
	v_mfma_f32_16x16x32_bf16 v[56:59], v[152:155], v[190:193], v[56:59]
	v_mfma_f32_16x16x32_bf16 v[44:47], v[140:143], v[198:201], v[44:47]
	v_mfma_f32_16x16x32_bf16 v[40:43], v[152:155], v[198:201], v[40:43]
	v_mfma_f32_16x16x32_bf16 v[28:31], v[140:143], v[220:223], v[28:31]
	v_mfma_f32_16x16x32_bf16 v[24:27], v[152:155], v[220:223], v[24:27]
	v_mfma_f32_16x16x32_bf16 v[12:15], v[140:143], v[232:235], v[12:15]
	v_mfma_f32_16x16x32_bf16 v[8:11], v[152:155], v[232:235], v[8:11]
	v_mfma_f32_16x16x32_bf16 v[60:63], v[148:151], v[194:197], v[60:63]
	v_mfma_f32_16x16x32_bf16 v[56:59], v[156:159], v[194:197], v[56:59]
	v_mfma_f32_16x16x32_bf16 v[44:47], v[148:151], v[202:205], v[44:47]
	v_mfma_f32_16x16x32_bf16 v[40:43], v[156:159], v[202:205], v[40:43]
	v_mfma_f32_16x16x32_bf16 v[28:31], v[148:151], v[228:231], v[28:31]
	v_mfma_f32_16x16x32_bf16 v[24:27], v[156:159], v[228:231], v[24:27]
	v_mfma_f32_16x16x32_bf16 v[12:15], v[148:151], v[236:239], v[12:15]
	v_mfma_f32_16x16x32_bf16 v[8:11], v[156:159], v[236:239], v[8:11]
	s_setprio 0
	s_setprio 1
	v_mfma_f32_16x16x32_bf16 v[52:55], v[174:177], v[190:193], v[52:55]
	v_mfma_f32_16x16x32_bf16 v[48:51], v[182:185], v[190:193], v[48:51]
	v_mfma_f32_16x16x32_bf16 v[36:39], v[174:177], v[198:201], v[36:39]
	v_mfma_f32_16x16x32_bf16 v[32:35], v[182:185], v[198:201], v[32:35]
	v_mfma_f32_16x16x32_bf16 v[20:23], v[174:177], v[220:223], v[20:23]
	v_mfma_f32_16x16x32_bf16 v[16:19], v[182:185], v[220:223], v[16:19]
	v_mfma_f32_16x16x32_bf16 v[4:7], v[174:177], v[232:235], v[4:7]
	v_mfma_f32_16x16x32_bf16 v[0:3], v[182:185], v[232:235], v[0:3]
	v_mfma_f32_16x16x32_bf16 v[52:55], v[178:181], v[194:197], v[52:55]
	v_mfma_f32_16x16x32_bf16 v[48:51], v[186:189], v[194:197], v[48:51]
	v_mfma_f32_16x16x32_bf16 v[36:39], v[178:181], v[202:205], v[36:39]
	v_mfma_f32_16x16x32_bf16 v[32:35], v[186:189], v[202:205], v[32:35]
	v_mfma_f32_16x16x32_bf16 v[20:23], v[178:181], v[228:231], v[20:23]
	v_mfma_f32_16x16x32_bf16 v[16:19], v[186:189], v[228:231], v[16:19]
	v_mfma_f32_16x16x32_bf16 v[4:7], v[178:181], v[236:239], v[4:7]
	v_mfma_f32_16x16x32_bf16 v[0:3], v[186:189], v[236:239], v[0:3]
	s_setprio 0
	s_barrier
	s_add_i32 s55, 0, 0x18000
	s_add_i32 s72, 0, 0x1c000
	v_add_u32_e32 v156, s55, v145
	v_add_u32_e32 v162, s72, v145
	ds_read_b128 v[140:143], v156
	ds_read_b128 v[148:151], v156 offset:1024
	ds_read_b128 v[152:155], v156 offset:2048
	ds_read_b128 v[156:159], v156 offset:3072
	ds_read_b128 v[174:177], v162
	ds_read_b128 v[178:181], v162 offset:1024
	ds_read_b128 v[182:185], v162 offset:2048
	ds_read_b128 v[186:189], v162 offset:3072
	s_add_u32 s64, s64, 0x40000
	s_addc_u32 s65, s65, 0
	s_mov_b32 m0, s67
	v_lshl_add_u64 v[248:249], s[64:65], 0, v[134:135]
	ds_read_b128 v[190:193], v147 offset:32768
	ds_read_b128 v[194:197], v147 offset:33792
	ds_read_b128 v[198:201], v147 offset:34816
	ds_read_b128 v[202:205], v147 offset:35840
	ds_read_b128 v[220:223], v147 offset:36864
	ds_read_b128 v[228:231], v147 offset:37888
	ds_read_b128 v[232:235], v147 offset:38912
	ds_read_b128 v[236:239], v147 offset:39936
	global_load_lds_dwordx4 v[248:249], off
	v_lshl_add_u64 v[248:249], s[64:65], 0, v[130:131]
	s_mov_b32 m0, s68
	s_nop 0
	global_load_lds_dwordx4 v[248:249], off
	s_waitcnt vmcnt(8)
	s_waitcnt lgkmcnt(0)
	s_barrier
	s_setprio 1
	v_mfma_f32_16x16x32_bf16 v[124:127], v[140:143], v[190:193], v[124:127]
	v_mfma_f32_16x16x32_bf16 v[120:123], v[152:155], v[190:193], v[120:123]
	v_mfma_f32_16x16x32_bf16 v[108:111], v[140:143], v[198:201], v[108:111]
	v_mfma_f32_16x16x32_bf16 v[104:107], v[152:155], v[198:201], v[104:107]
	v_mfma_f32_16x16x32_bf16 v[92:95], v[140:143], v[220:223], v[92:95]
	v_mfma_f32_16x16x32_bf16 v[88:91], v[152:155], v[220:223], v[88:91]
	v_mfma_f32_16x16x32_bf16 v[76:79], v[140:143], v[232:235], v[76:79]
	v_mfma_f32_16x16x32_bf16 v[72:75], v[152:155], v[232:235], v[72:75]
	v_mfma_f32_16x16x32_bf16 v[124:127], v[148:151], v[194:197], v[124:127]
	v_mfma_f32_16x16x32_bf16 v[120:123], v[156:159], v[194:197], v[120:123]
	v_mfma_f32_16x16x32_bf16 v[108:111], v[148:151], v[202:205], v[108:111]
	v_mfma_f32_16x16x32_bf16 v[104:107], v[156:159], v[202:205], v[104:107]
	v_mfma_f32_16x16x32_bf16 v[92:95], v[148:151], v[228:231], v[92:95]
	v_mfma_f32_16x16x32_bf16 v[88:91], v[156:159], v[228:231], v[88:91]
	v_mfma_f32_16x16x32_bf16 v[76:79], v[148:151], v[236:239], v[76:79]
	v_mfma_f32_16x16x32_bf16 v[72:75], v[156:159], v[236:239], v[72:75]
	s_setprio 0
	s_setprio 1
	v_mfma_f32_16x16x32_bf16 v[116:119], v[174:177], v[190:193], v[116:119]
	v_mfma_f32_16x16x32_bf16 v[112:115], v[182:185], v[190:193], v[112:115]
	v_mfma_f32_16x16x32_bf16 v[100:103], v[174:177], v[198:201], v[100:103]
	v_mfma_f32_16x16x32_bf16 v[96:99], v[182:185], v[198:201], v[96:99]
	v_mfma_f32_16x16x32_bf16 v[84:87], v[174:177], v[220:223], v[84:87]
	v_mfma_f32_16x16x32_bf16 v[80:83], v[182:185], v[220:223], v[80:83]
	v_mfma_f32_16x16x32_bf16 v[68:71], v[174:177], v[232:235], v[68:71]
	v_mfma_f32_16x16x32_bf16 v[64:67], v[182:185], v[232:235], v[64:67]
	v_mfma_f32_16x16x32_bf16 v[116:119], v[178:181], v[194:197], v[116:119]
	v_mfma_f32_16x16x32_bf16 v[112:115], v[186:189], v[194:197], v[112:115]
	v_mfma_f32_16x16x32_bf16 v[100:103], v[178:181], v[202:205], v[100:103]
	v_mfma_f32_16x16x32_bf16 v[96:99], v[186:189], v[202:205], v[96:99]
	v_mfma_f32_16x16x32_bf16 v[84:87], v[178:181], v[228:231], v[84:87]
	v_mfma_f32_16x16x32_bf16 v[80:83], v[186:189], v[228:231], v[80:83]
	v_mfma_f32_16x16x32_bf16 v[68:71], v[178:181], v[236:239], v[68:71]
	v_mfma_f32_16x16x32_bf16 v[64:67], v[186:189], v[236:239], v[64:67]
	s_setprio 0
	s_barrier
	s_add_i32 s55, s55, s24
	v_lshl_add_u64 v[240:241], v[240:241], 0, s[4:5]
	s_mov_b32 m0, s55
	ds_read_b128 v[190:193], v147 offset:49152
	ds_read_b128 v[194:197], v147 offset:50176
	ds_read_b128 v[198:201], v147 offset:51200
	ds_read_b128 v[202:205], v147 offset:52224
	ds_read_b128 v[220:223], v147 offset:53248
	ds_read_b128 v[228:231], v147 offset:54272
	ds_read_b128 v[232:235], v147 offset:55296
	ds_read_b128 v[236:239], v147 offset:56320
	global_load_lds_dwordx4 v[240:241], off
	s_add_i32 m0, s55, 0x2000
	s_add_u32 s62, s62, 0x40080
	v_lshl_add_u64 v[240:241], v[242:243], 0, s[4:5]
	s_addc_u32 s63, s63, 0
	s_add_i32 s55, s72, s24
	global_load_lds_dwordx4 v[240:241], off
	v_lshl_add_u64 v[240:241], s[62:63], 0, v[132:133]
	s_mov_b32 m0, s55
	s_nop 0
	global_load_lds_dwordx4 v[240:241], off
	v_lshl_add_u64 v[240:241], s[62:63], 0, v[128:129]
	s_add_i32 m0, s55, 0x2000
	s_nop 0
	global_load_lds_dwordx4 v[240:241], off
	v_lshl_add_u64 v[240:241], v[244:245], 0, s[4:5]
	s_mov_b32 m0, s69
	s_nop 0
	global_load_lds_dwordx4 v[240:241], off
	v_lshl_add_u64 v[240:241], v[246:247], 0, s[4:5]
	s_mov_b32 m0, s70
	s_nop 0
	global_load_lds_dwordx4 v[240:241], off
	s_waitcnt vmcnt(8)
	s_waitcnt lgkmcnt(0)
	s_barrier
	s_setprio 1
	v_mfma_f32_16x16x32_bf16 v[60:63], v[140:143], v[190:193], v[60:63]
	v_mfma_f32_16x16x32_bf16 v[56:59], v[152:155], v[190:193], v[56:59]
	v_mfma_f32_16x16x32_bf16 v[44:47], v[140:143], v[198:201], v[44:47]
	v_mfma_f32_16x16x32_bf16 v[40:43], v[152:155], v[198:201], v[40:43]
	v_mfma_f32_16x16x32_bf16 v[28:31], v[140:143], v[220:223], v[28:31]
	v_mfma_f32_16x16x32_bf16 v[24:27], v[152:155], v[220:223], v[24:27]
	v_mfma_f32_16x16x32_bf16 v[12:15], v[140:143], v[232:235], v[12:15]
	v_mfma_f32_16x16x32_bf16 v[8:11], v[152:155], v[232:235], v[8:11]
	v_mfma_f32_16x16x32_bf16 v[60:63], v[148:151], v[194:197], v[60:63]
	v_mfma_f32_16x16x32_bf16 v[56:59], v[156:159], v[194:197], v[56:59]
	v_mfma_f32_16x16x32_bf16 v[44:47], v[148:151], v[202:205], v[44:47]
	v_mfma_f32_16x16x32_bf16 v[40:43], v[156:159], v[202:205], v[40:43]
	v_mfma_f32_16x16x32_bf16 v[28:31], v[148:151], v[228:231], v[28:31]
	v_mfma_f32_16x16x32_bf16 v[24:27], v[156:159], v[228:231], v[24:27]
	v_mfma_f32_16x16x32_bf16 v[12:15], v[148:151], v[236:239], v[12:15]
	v_mfma_f32_16x16x32_bf16 v[8:11], v[156:159], v[236:239], v[8:11]
	s_setprio 0
	s_setprio 1
	v_mfma_f32_16x16x32_bf16 v[52:55], v[174:177], v[190:193], v[52:55]
	v_mfma_f32_16x16x32_bf16 v[48:51], v[182:185], v[190:193], v[48:51]
	v_mfma_f32_16x16x32_bf16 v[36:39], v[174:177], v[198:201], v[36:39]
	v_mfma_f32_16x16x32_bf16 v[32:35], v[182:185], v[198:201], v[32:35]
	v_mfma_f32_16x16x32_bf16 v[20:23], v[174:177], v[220:223], v[20:23]
	v_mfma_f32_16x16x32_bf16 v[16:19], v[182:185], v[220:223], v[16:19]
	v_mfma_f32_16x16x32_bf16 v[4:7], v[174:177], v[232:235], v[4:7]
	v_mfma_f32_16x16x32_bf16 v[0:3], v[182:185], v[232:235], v[0:3]
	v_mfma_f32_16x16x32_bf16 v[52:55], v[178:181], v[194:197], v[52:55]
	v_mfma_f32_16x16x32_bf16 v[48:51], v[186:189], v[194:197], v[48:51]
	v_mfma_f32_16x16x32_bf16 v[36:39], v[178:181], v[202:205], v[36:39]
	v_mfma_f32_16x16x32_bf16 v[32:35], v[186:189], v[202:205], v[32:35]
	v_mfma_f32_16x16x32_bf16 v[20:23], v[178:181], v[228:231], v[20:23]
	v_mfma_f32_16x16x32_bf16 v[16:19], v[186:189], v[228:231], v[16:19]
	v_mfma_f32_16x16x32_bf16 v[4:7], v[178:181], v[236:239], v[4:7]
	v_mfma_f32_16x16x32_bf16 v[0:3], v[186:189], v[236:239], v[0:3]
	s_setprio 0
	s_barrier
	s_add_i32 s53, s53, 2
	s_add_u32 s60, s60, 0x100
	s_addc_u32 s61, s61, 0
	s_add_u32 s30, s30, 0x100
	s_addc_u32 s31, s31, 0
	s_cmp_gt_u32 s53, 13
	s_cbranch_scc0 .LBB0_771
	s_and_b64 vcc, exec, s[48:49]
	s_mov_b64 s[30:31], s[34:35]
	s_cbranch_vccz .LBB0_774
	s_barrier

.LBB0_858:
	s_add_u32 s61, s66, 0xfffe0080
	s_addc_u32 s68, s67, -1
	s_add_i32 s83, 0, 0x10000
	s_cmp_eq_u32 s59, 4
	s_cselect_b32 s71, s6, s68
	s_cselect_b32 s70, s7, s61
	v_add_u32_e32 v136, s83, v157
	s_cselect_b32 s69, s28, s31
	s_cselect_b32 s68, s29, s30
	s_add_i32 s61, 0, 0x14000
	ds_read_b128 v[128:131], v136
	ds_read_b128 v[132:135], v136 offset:1024
	ds_read_b128 v[148:151], v136 offset:2048
	ds_read_b128 v[152:155], v136 offset:3072
	v_add_u32_e32 v136, s61, v157
	ds_read_b128 v[174:177], v136
	ds_read_b128 v[178:181], v136 offset:1024
	ds_read_b128 v[182:185], v136 offset:2048
	ds_read_b128 v[186:189], v136 offset:3072
	v_lshl_add_u64 v[136:137], s[66:67], 0, v[144:145]
	s_add_i32 m0, s25, 0xc000
	ds_read_b128 v[190:193], v159
	ds_read_b128 v[194:197], v159 offset:1024
	ds_read_b128 v[198:201], v159 offset:2048
	ds_read_b128 v[202:205], v159 offset:3072
	ds_read_b128 v[220:223], v159 offset:4096
	ds_read_b128 v[228:231], v159 offset:5120
	ds_read_b128 v[232:235], v159 offset:6144
	ds_read_b128 v[236:239], v159 offset:7168
	global_load_lds_dwordx4 v[136:137], off
	v_lshl_add_u64 v[136:137], s[66:67], 0, v[146:147]
	s_add_i32 m0, s25, 0xe000
	s_nop 0
	global_load_lds_dwordx4 v[136:137], off
	s_waitcnt vmcnt(8)
	s_waitcnt lgkmcnt(0)
	s_barrier
	s_setprio 1
	v_mfma_f32_16x16x32_bf16 v[124:127], v[128:131], v[190:193], v[124:127]
	v_mfma_f32_16x16x32_bf16 v[120:123], v[148:151], v[190:193], v[120:123]
	v_mfma_f32_16x16x32_bf16 v[108:111], v[128:131], v[198:201], v[108:111]
	v_mfma_f32_16x16x32_bf16 v[104:107], v[148:151], v[198:201], v[104:107]
	v_mfma_f32_16x16x32_bf16 v[92:95], v[128:131], v[220:223], v[92:95]
	v_mfma_f32_16x16x32_bf16 v[88:91], v[148:151], v[220:223], v[88:91]
	v_mfma_f32_16x16x32_bf16 v[76:79], v[128:131], v[232:235], v[76:79]
	v_mfma_f32_16x16x32_bf16 v[72:75], v[148:151], v[232:235], v[72:75]
	v_mfma_f32_16x16x32_bf16 v[124:127], v[132:135], v[194:197], v[124:127]
	v_mfma_f32_16x16x32_bf16 v[120:123], v[152:155], v[194:197], v[120:123]
	v_mfma_f32_16x16x32_bf16 v[108:111], v[132:135], v[202:205], v[108:111]
	v_mfma_f32_16x16x32_bf16 v[104:107], v[152:155], v[202:205], v[104:107]
	v_mfma_f32_16x16x32_bf16 v[92:95], v[132:135], v[228:231], v[92:95]
	v_mfma_f32_16x16x32_bf16 v[88:91], v[152:155], v[228:231], v[88:91]
	v_mfma_f32_16x16x32_bf16 v[76:79], v[132:135], v[236:239], v[76:79]
	v_mfma_f32_16x16x32_bf16 v[72:75], v[152:155], v[236:239], v[72:75]
	s_setprio 0
	s_setprio 1
	v_mfma_f32_16x16x32_bf16 v[116:119], v[174:177], v[190:193], v[116:119]
	v_mfma_f32_16x16x32_bf16 v[112:115], v[182:185], v[190:193], v[112:115]
	v_mfma_f32_16x16x32_bf16 v[100:103], v[174:177], v[198:201], v[100:103]
	v_mfma_f32_16x16x32_bf16 v[96:99], v[182:185], v[198:201], v[96:99]
	v_mfma_f32_16x16x32_bf16 v[84:87], v[174:177], v[220:223], v[84:87]
	v_mfma_f32_16x16x32_bf16 v[80:83], v[182:185], v[220:223], v[80:83]
	v_mfma_f32_16x16x32_bf16 v[68:71], v[174:177], v[232:235], v[68:71]
	v_mfma_f32_16x16x32_bf16 v[64:67], v[182:185], v[232:235], v[64:67]
	v_mfma_f32_16x16x32_bf16 v[116:119], v[178:181], v[194:197], v[116:119]
	v_mfma_f32_16x16x32_bf16 v[112:115], v[186:189], v[194:197], v[112:115]
	v_mfma_f32_16x16x32_bf16 v[100:103], v[178:181], v[202:205], v[100:103]
	v_mfma_f32_16x16x32_bf16 v[96:99], v[186:189], v[202:205], v[96:99]
	v_mfma_f32_16x16x32_bf16 v[84:87], v[178:181], v[228:231], v[84:87]
	v_mfma_f32_16x16x32_bf16 v[80:83], v[186:189], v[228:231], v[80:83]
	v_mfma_f32_16x16x32_bf16 v[68:71], v[178:181], v[236:239], v[68:71]
	v_mfma_f32_16x16x32_bf16 v[64:67], v[186:189], v[236:239], v[64:67]
	s_setprio 0
	s_barrier
	s_add_i32 s83, s83, s22
	v_lshl_add_u64 v[136:137], s[68:69], 0, v[162:163]
	s_mov_b32 m0, s83
	ds_read_b128 v[190:193], v159 offset:16384
	ds_read_b128 v[194:197], v159 offset:17408
	ds_read_b128 v[198:201], v159 offset:18432
	ds_read_b128 v[202:205], v159 offset:19456
	ds_read_b128 v[220:223], v159 offset:20480
	ds_read_b128 v[228:231], v159 offset:21504
	ds_read_b128 v[232:235], v159 offset:22528
	ds_read_b128 v[236:239], v159 offset:23552
	global_load_lds_dwordx4 v[136:137], off
	s_add_i32 m0, s83, 0x2000
	s_add_u32 s84, s68, 0x20000
	v_lshl_add_u64 v[240:241], s[68:69], 0, v[138:139]
	s_addc_u32 s85, s69, 0
	s_add_i32 s61, s61, s22
	global_load_lds_dwordx4 v[240:241], off
	v_lshl_add_u64 v[242:243], s[84:85], 0, v[162:163]
	s_mov_b32 m0, s61
	v_lshl_add_u64 v[244:245], s[70:71], 0, v[140:141]
	global_load_lds_dwordx4 v[242:243], off
	v_lshl_add_u64 v[242:243], s[84:85], 0, v[138:139]
	s_add_i32 m0, s61, 0x2000
	s_nop 0
	global_load_lds_dwordx4 v[242:243], off
	v_lshl_add_u64 v[242:243], s[70:71], 0, v[142:143]
	s_mov_b32 m0, s25
	s_nop 0
	global_load_lds_dwordx4 v[242:243], off
	s_mov_b32 m0, s72
	s_nop 0
	global_load_lds_dwordx4 v[244:245], off
	s_waitcnt vmcnt(8)
	s_waitcnt lgkmcnt(0)
	s_barrier
	s_setprio 1
	v_mfma_f32_16x16x32_bf16 v[60:63], v[128:131], v[190:193], v[60:63]
	v_mfma_f32_16x16x32_bf16 v[56:59], v[148:151], v[190:193], v[56:59]
	v_mfma_f32_16x16x32_bf16 v[44:47], v[128:131], v[198:201], v[44:47]
	v_mfma_f32_16x16x32_bf16 v[40:43], v[148:151], v[198:201], v[40:43]
	v_mfma_f32_16x16x32_bf16 v[28:31], v[128:131], v[220:223], v[28:31]
	v_mfma_f32_16x16x32_bf16 v[24:27], v[148:151], v[220:223], v[24:27]
	v_mfma_f32_16x16x32_bf16 v[12:15], v[128:131], v[232:235], v[12:15]
	v_mfma_f32_16x16x32_bf16 v[8:11], v[148:151], v[232:235], v[8:11]
	v_mfma_f32_16x16x32_bf16 v[60:63], v[132:135], v[194:197], v[60:63]
	v_mfma_f32_16x16x32_bf16 v[56:59], v[152:155], v[194:197], v[56:59]
	v_mfma_f32_16x16x32_bf16 v[44:47], v[132:135], v[202:205], v[44:47]
	v_mfma_f32_16x16x32_bf16 v[40:43], v[152:155], v[202:205], v[40:43]
	v_mfma_f32_16x16x32_bf16 v[28:31], v[132:135], v[228:231], v[28:31]
	v_mfma_f32_16x16x32_bf16 v[24:27], v[152:155], v[228:231], v[24:27]
	v_mfma_f32_16x16x32_bf16 v[12:15], v[132:135], v[236:239], v[12:15]
	v_mfma_f32_16x16x32_bf16 v[8:11], v[152:155], v[236:239], v[8:11]
	s_setprio 0
	s_setprio 1
	v_mfma_f32_16x16x32_bf16 v[52:55], v[174:177], v[190:193], v[52:55]
	v_mfma_f32_16x16x32_bf16 v[48:51], v[182:185], v[190:193], v[48:51]
	v_mfma_f32_16x16x32_bf16 v[36:39], v[174:177], v[198:201], v[36:39]
	v_mfma_f32_16x16x32_bf16 v[32:35], v[182:185], v[198:201], v[32:35]
	v_mfma_f32_16x16x32_bf16 v[20:23], v[174:177], v[220:223], v[20:23]
	v_mfma_f32_16x16x32_bf16 v[16:19], v[182:185], v[220:223], v[16:19]
	v_mfma_f32_16x16x32_bf16 v[4:7], v[174:177], v[232:235], v[4:7]
	v_mfma_f32_16x16x32_bf16 v[0:3], v[182:185], v[232:235], v[0:3]
	v_mfma_f32_16x16x32_bf16 v[52:55], v[178:181], v[194:197], v[52:55]
	v_mfma_f32_16x16x32_bf16 v[48:51], v[186:189], v[194:197], v[48:51]
	v_mfma_f32_16x16x32_bf16 v[36:39], v[178:181], v[202:205], v[36:39]
	v_mfma_f32_16x16x32_bf16 v[32:35], v[186:189], v[202:205], v[32:35]
	v_mfma_f32_16x16x32_bf16 v[20:23], v[178:181], v[228:231], v[20:23]
	v_mfma_f32_16x16x32_bf16 v[16:19], v[186:189], v[228:231], v[16:19]
	v_mfma_f32_16x16x32_bf16 v[4:7], v[178:181], v[236:239], v[4:7]
	v_mfma_f32_16x16x32_bf16 v[0:3], v[186:189], v[236:239], v[0:3]
	s_setprio 0
	s_barrier
	s_add_i32 s61, 0, 0x18000
	s_add_i32 s83, 0, 0x1c000
	v_add_u32_e32 v152, s61, v157
	v_add_u32_e32 v186, s83, v157
	ds_read_b128 v[128:131], v152
	ds_read_b128 v[132:135], v152 offset:1024
	ds_read_b128 v[148:151], v152 offset:2048
	ds_read_b128 v[152:155], v152 offset:3072
	ds_read_b128 v[174:177], v186
	ds_read_b128 v[178:181], v186 offset:1024
	ds_read_b128 v[182:185], v186 offset:2048
	ds_read_b128 v[186:189], v186 offset:3072
	s_add_u32 s70, s70, 0x20000
	s_addc_u32 s71, s71, 0
	s_mov_b32 m0, s73
	v_lshl_add_u64 v[246:247], s[70:71], 0, v[142:143]
	ds_read_b128 v[190:193], v159 offset:32768
	ds_read_b128 v[194:197], v159 offset:33792
	ds_read_b128 v[198:201], v159 offset:34816
	ds_read_b128 v[202:205], v159 offset:35840
	ds_read_b128 v[220:223], v159 offset:36864
	ds_read_b128 v[228:231], v159 offset:37888
	ds_read_b128 v[232:235], v159 offset:38912
	ds_read_b128 v[236:239], v159 offset:39936
	global_load_lds_dwordx4 v[246:247], off
	v_lshl_add_u64 v[246:247], s[70:71], 0, v[140:141]
	s_mov_b32 m0, s74
	s_nop 0
	global_load_lds_dwordx4 v[246:247], off
	s_waitcnt vmcnt(8)
	s_waitcnt lgkmcnt(0)
	s_barrier
	s_setprio 1
	v_mfma_f32_16x16x32_bf16 v[124:127], v[128:131], v[190:193], v[124:127]
	v_mfma_f32_16x16x32_bf16 v[120:123], v[148:151], v[190:193], v[120:123]
	v_mfma_f32_16x16x32_bf16 v[108:111], v[128:131], v[198:201], v[108:111]
	v_mfma_f32_16x16x32_bf16 v[104:107], v[148:151], v[198:201], v[104:107]
	v_mfma_f32_16x16x32_bf16 v[92:95], v[128:131], v[220:223], v[92:95]
	v_mfma_f32_16x16x32_bf16 v[88:91], v[148:151], v[220:223], v[88:91]
	v_mfma_f32_16x16x32_bf16 v[76:79], v[128:131], v[232:235], v[76:79]
	v_mfma_f32_16x16x32_bf16 v[72:75], v[148:151], v[232:235], v[72:75]
	v_mfma_f32_16x16x32_bf16 v[124:127], v[132:135], v[194:197], v[124:127]
	v_mfma_f32_16x16x32_bf16 v[120:123], v[152:155], v[194:197], v[120:123]
	v_mfma_f32_16x16x32_bf16 v[108:111], v[132:135], v[202:205], v[108:111]
	v_mfma_f32_16x16x32_bf16 v[104:107], v[152:155], v[202:205], v[104:107]
	v_mfma_f32_16x16x32_bf16 v[92:95], v[132:135], v[228:231], v[92:95]
	v_mfma_f32_16x16x32_bf16 v[88:91], v[152:155], v[228:231], v[88:91]
	v_mfma_f32_16x16x32_bf16 v[76:79], v[132:135], v[236:239], v[76:79]
	v_mfma_f32_16x16x32_bf16 v[72:75], v[152:155], v[236:239], v[72:75]
	s_setprio 0
	s_setprio 1
	v_mfma_f32_16x16x32_bf16 v[116:119], v[174:177], v[190:193], v[116:119]
	v_mfma_f32_16x16x32_bf16 v[112:115], v[182:185], v[190:193], v[112:115]
	v_mfma_f32_16x16x32_bf16 v[100:103], v[174:177], v[198:201], v[100:103]
	v_mfma_f32_16x16x32_bf16 v[96:99], v[182:185], v[198:201], v[96:99]
	v_mfma_f32_16x16x32_bf16 v[84:87], v[174:177], v[220:223], v[84:87]
	v_mfma_f32_16x16x32_bf16 v[80:83], v[182:185], v[220:223], v[80:83]
	v_mfma_f32_16x16x32_bf16 v[68:71], v[174:177], v[232:235], v[68:71]
	v_mfma_f32_16x16x32_bf16 v[64:67], v[182:185], v[232:235], v[64:67]
	v_mfma_f32_16x16x32_bf16 v[116:119], v[178:181], v[194:197], v[116:119]
	v_mfma_f32_16x16x32_bf16 v[112:115], v[186:189], v[194:197], v[112:115]
	v_mfma_f32_16x16x32_bf16 v[100:103], v[178:181], v[202:205], v[100:103]
	v_mfma_f32_16x16x32_bf16 v[96:99], v[186:189], v[202:205], v[96:99]
	v_mfma_f32_16x16x32_bf16 v[84:87], v[178:181], v[228:231], v[84:87]
	v_mfma_f32_16x16x32_bf16 v[80:83], v[186:189], v[228:231], v[80:83]
	v_mfma_f32_16x16x32_bf16 v[68:71], v[178:181], v[236:239], v[68:71]
	v_mfma_f32_16x16x32_bf16 v[64:67], v[186:189], v[236:239], v[64:67]
	s_setprio 0
	s_barrier
	s_add_i32 s61, s61, s22
	v_lshl_add_u64 v[136:137], v[136:137], 0, s[4:5]
	s_mov_b32 m0, s61
	ds_read_b128 v[190:193], v159 offset:49152
	ds_read_b128 v[194:197], v159 offset:50176
	ds_read_b128 v[198:201], v159 offset:51200
	ds_read_b128 v[202:205], v159 offset:52224
	ds_read_b128 v[220:223], v159 offset:53248
	ds_read_b128 v[228:231], v159 offset:54272
	ds_read_b128 v[232:235], v159 offset:55296
	ds_read_b128 v[236:239], v159 offset:56320
	global_load_lds_dwordx4 v[136:137], off
	s_add_i32 m0, s61, 0x2000
	s_add_u32 s68, s68, 0x20080
	v_lshl_add_u64 v[136:137], v[240:241], 0, s[4:5]
	s_addc_u32 s69, s69, 0
	s_add_i32 s61, s83, s22
	global_load_lds_dwordx4 v[136:137], off
	v_lshl_add_u64 v[136:137], s[68:69], 0, v[162:163]
	s_mov_b32 m0, s61
	s_nop 0
	global_load_lds_dwordx4 v[136:137], off
	v_lshl_add_u64 v[136:137], s[68:69], 0, v[138:139]
	s_add_i32 m0, s61, 0x2000
	s_nop 0
	global_load_lds_dwordx4 v[136:137], off
	v_lshl_add_u64 v[136:137], v[242:243], 0, s[4:5]
	s_mov_b32 m0, s75
	s_nop 0
	global_load_lds_dwordx4 v[136:137], off
	v_lshl_add_u64 v[136:137], v[244:245], 0, s[4:5]
	s_mov_b32 m0, s76
	s_nop 0
	global_load_lds_dwordx4 v[136:137], off
	s_waitcnt vmcnt(8)
	s_waitcnt lgkmcnt(0)
	s_barrier
	s_setprio 1
	v_mfma_f32_16x16x32_bf16 v[60:63], v[128:131], v[190:193], v[60:63]
	v_mfma_f32_16x16x32_bf16 v[56:59], v[148:151], v[190:193], v[56:59]
	v_mfma_f32_16x16x32_bf16 v[44:47], v[128:131], v[198:201], v[44:47]
	v_mfma_f32_16x16x32_bf16 v[40:43], v[148:151], v[198:201], v[40:43]
	v_mfma_f32_16x16x32_bf16 v[28:31], v[128:131], v[220:223], v[28:31]
	v_mfma_f32_16x16x32_bf16 v[24:27], v[148:151], v[220:223], v[24:27]
	v_mfma_f32_16x16x32_bf16 v[12:15], v[128:131], v[232:235], v[12:15]
	v_mfma_f32_16x16x32_bf16 v[8:11], v[148:151], v[232:235], v[8:11]
	v_mfma_f32_16x16x32_bf16 v[60:63], v[132:135], v[194:197], v[60:63]
	v_mfma_f32_16x16x32_bf16 v[56:59], v[152:155], v[194:197], v[56:59]
	v_mfma_f32_16x16x32_bf16 v[44:47], v[132:135], v[202:205], v[44:47]
	v_mfma_f32_16x16x32_bf16 v[40:43], v[152:155], v[202:205], v[40:43]
	v_mfma_f32_16x16x32_bf16 v[28:31], v[132:135], v[228:231], v[28:31]
	v_mfma_f32_16x16x32_bf16 v[24:27], v[152:155], v[228:231], v[24:27]
	v_mfma_f32_16x16x32_bf16 v[12:15], v[132:135], v[236:239], v[12:15]
	v_mfma_f32_16x16x32_bf16 v[8:11], v[152:155], v[236:239], v[8:11]
	s_setprio 0
	s_setprio 1
	v_mfma_f32_16x16x32_bf16 v[52:55], v[174:177], v[190:193], v[52:55]
	v_mfma_f32_16x16x32_bf16 v[48:51], v[182:185], v[190:193], v[48:51]
	v_mfma_f32_16x16x32_bf16 v[36:39], v[174:177], v[198:201], v[36:39]
	v_mfma_f32_16x16x32_bf16 v[32:35], v[182:185], v[198:201], v[32:35]
	v_mfma_f32_16x16x32_bf16 v[20:23], v[174:177], v[220:223], v[20:23]
	v_mfma_f32_16x16x32_bf16 v[16:19], v[182:185], v[220:223], v[16:19]
	v_mfma_f32_16x16x32_bf16 v[4:7], v[174:177], v[232:235], v[4:7]
	v_mfma_f32_16x16x32_bf16 v[0:3], v[182:185], v[232:235], v[0:3]
	v_mfma_f32_16x16x32_bf16 v[52:55], v[178:181], v[194:197], v[52:55]
	v_mfma_f32_16x16x32_bf16 v[48:51], v[186:189], v[194:197], v[48:51]
	v_mfma_f32_16x16x32_bf16 v[36:39], v[178:181], v[202:205], v[36:39]
	v_mfma_f32_16x16x32_bf16 v[32:35], v[186:189], v[202:205], v[32:35]
	v_mfma_f32_16x16x32_bf16 v[20:23], v[178:181], v[228:231], v[20:23]
	v_mfma_f32_16x16x32_bf16 v[16:19], v[186:189], v[228:231], v[16:19]
	v_mfma_f32_16x16x32_bf16 v[4:7], v[178:181], v[236:239], v[4:7]
	v_mfma_f32_16x16x32_bf16 v[0:3], v[186:189], v[236:239], v[0:3]
	s_setprio 0
	s_barrier
	s_add_i32 s59, s59, 2
	s_add_u32 s66, s66, 0x100
	s_addc_u32 s67, s67, 0
	s_add_u32 s30, s30, 0x100
	s_addc_u32 s31, s31, 0
	s_cmp_gt_u32 s59, 5
	s_cbranch_scc0 .LBB0_858
	s_and_b64 vcc, exec, s[56:57]
	s_cbranch_vccz .LBB0_861
	s_barrier

.LBB0_975:
	s_add_u32 s29, s60, 0xfffc0080
	s_addc_u32 s30, s61, -1
	s_add_i32 s31, 0, 0x10000
	s_cmp_eq_u32 s28, 12
	s_cselect_b32 s65, s6, s30
	s_cselect_b32 s64, s7, s29
	v_add_u32_e32 v142, s31, v145
	s_cselect_b32 s63, s24, s27
	s_cselect_b32 s62, s25, s26
	s_add_i32 s29, 0, 0x14000
	ds_read_b128 v[138:141], v142
	ds_read_b128 v[148:151], v142 offset:1024
	ds_read_b128 v[152:155], v142 offset:2048
	ds_read_b128 v[156:159], v142 offset:3072
	v_add_u32_e32 v142, s29, v145
	ds_read_b128 v[174:177], v142
	ds_read_b128 v[178:181], v142 offset:1024
	ds_read_b128 v[182:185], v142 offset:2048
	ds_read_b128 v[186:189], v142 offset:3072
	v_lshl_add_u64 v[142:143], s[60:61], 0, v[134:135]
	s_add_i32 m0, s69, 0xc000
	ds_read_b128 v[190:193], v147
	ds_read_b128 v[194:197], v147 offset:1024
	ds_read_b128 v[198:201], v147 offset:2048
	ds_read_b128 v[202:205], v147 offset:3072
	ds_read_b128 v[220:223], v147 offset:4096
	ds_read_b128 v[228:231], v147 offset:5120
	ds_read_b128 v[232:235], v147 offset:6144
	ds_read_b128 v[236:239], v147 offset:7168
	global_load_lds_dwordx4 v[142:143], off
	v_lshl_add_u64 v[142:143], s[60:61], 0, v[136:137]
	s_add_i32 m0, s69, 0xe000
	s_nop 0
	global_load_lds_dwordx4 v[142:143], off
	s_waitcnt vmcnt(8)
	s_waitcnt lgkmcnt(0)
	s_barrier
	s_setprio 1
	v_mfma_f32_16x16x32_bf16 v[124:127], v[138:141], v[190:193], v[124:127]
	v_mfma_f32_16x16x32_bf16 v[120:123], v[152:155], v[190:193], v[120:123]
	v_mfma_f32_16x16x32_bf16 v[108:111], v[138:141], v[198:201], v[108:111]
	v_mfma_f32_16x16x32_bf16 v[104:107], v[152:155], v[198:201], v[104:107]
	v_mfma_f32_16x16x32_bf16 v[92:95], v[138:141], v[220:223], v[92:95]
	v_mfma_f32_16x16x32_bf16 v[88:91], v[152:155], v[220:223], v[88:91]
	v_mfma_f32_16x16x32_bf16 v[76:79], v[138:141], v[232:235], v[76:79]
	v_mfma_f32_16x16x32_bf16 v[72:75], v[152:155], v[232:235], v[72:75]
	v_mfma_f32_16x16x32_bf16 v[124:127], v[148:151], v[194:197], v[124:127]
	v_mfma_f32_16x16x32_bf16 v[120:123], v[156:159], v[194:197], v[120:123]
	v_mfma_f32_16x16x32_bf16 v[108:111], v[148:151], v[202:205], v[108:111]
	v_mfma_f32_16x16x32_bf16 v[104:107], v[156:159], v[202:205], v[104:107]
	v_mfma_f32_16x16x32_bf16 v[92:95], v[148:151], v[228:231], v[92:95]
	v_mfma_f32_16x16x32_bf16 v[88:91], v[156:159], v[228:231], v[88:91]
	v_mfma_f32_16x16x32_bf16 v[76:79], v[148:151], v[236:239], v[76:79]
	v_mfma_f32_16x16x32_bf16 v[72:75], v[156:159], v[236:239], v[72:75]
	s_setprio 0
	s_setprio 1
	v_mfma_f32_16x16x32_bf16 v[116:119], v[174:177], v[190:193], v[116:119]
	v_mfma_f32_16x16x32_bf16 v[112:115], v[182:185], v[190:193], v[112:115]
	v_mfma_f32_16x16x32_bf16 v[100:103], v[174:177], v[198:201], v[100:103]
	v_mfma_f32_16x16x32_bf16 v[96:99], v[182:185], v[198:201], v[96:99]
	v_mfma_f32_16x16x32_bf16 v[84:87], v[174:177], v[220:223], v[84:87]
	v_mfma_f32_16x16x32_bf16 v[80:83], v[182:185], v[220:223], v[80:83]
	v_mfma_f32_16x16x32_bf16 v[68:71], v[174:177], v[232:235], v[68:71]
	v_mfma_f32_16x16x32_bf16 v[64:67], v[182:185], v[232:235], v[64:67]
	v_mfma_f32_16x16x32_bf16 v[116:119], v[178:181], v[194:197], v[116:119]
	v_mfma_f32_16x16x32_bf16 v[112:115], v[186:189], v[194:197], v[112:115]
	v_mfma_f32_16x16x32_bf16 v[100:103], v[178:181], v[202:205], v[100:103]
	v_mfma_f32_16x16x32_bf16 v[96:99], v[186:189], v[202:205], v[96:99]
	v_mfma_f32_16x16x32_bf16 v[84:87], v[178:181], v[228:231], v[84:87]
	v_mfma_f32_16x16x32_bf16 v[80:83], v[186:189], v[228:231], v[80:83]
	v_mfma_f32_16x16x32_bf16 v[68:71], v[178:181], v[236:239], v[68:71]
	v_mfma_f32_16x16x32_bf16 v[64:67], v[186:189], v[236:239], v[64:67]
	s_setprio 0
	s_barrier
	s_add_i32 s30, s31, s68
	v_lshl_add_u64 v[142:143], s[62:63], 0, v[162:163]
	s_mov_b32 m0, s30
	ds_read_b128 v[190:193], v147 offset:16384
	ds_read_b128 v[194:197], v147 offset:17408
	ds_read_b128 v[198:201], v147 offset:18432
	ds_read_b128 v[202:205], v147 offset:19456
	ds_read_b128 v[220:223], v147 offset:20480
	ds_read_b128 v[228:231], v147 offset:21504
	ds_read_b128 v[232:235], v147 offset:22528
	ds_read_b128 v[236:239], v147 offset:23552
	global_load_lds_dwordx4 v[142:143], off
	s_add_i32 m0, s30, 0x2000
	s_add_u32 s30, s62, 0x40000
	v_lshl_add_u64 v[240:241], s[62:63], 0, v[128:129]
	s_addc_u32 s31, s63, 0
	s_add_i32 s29, s29, s68
	global_load_lds_dwordx4 v[240:241], off
	v_lshl_add_u64 v[242:243], s[30:31], 0, v[162:163]
	s_mov_b32 m0, s29
	v_lshl_add_u64 v[244:245], s[64:65], 0, v[130:131]
	global_load_lds_dwordx4 v[242:243], off
	v_lshl_add_u64 v[242:243], s[30:31], 0, v[128:129]
	s_add_i32 m0, s29, 0x2000
	s_nop 0
	global_load_lds_dwordx4 v[242:243], off
	v_lshl_add_u64 v[242:243], s[64:65], 0, v[132:133]
	s_mov_b32 m0, s69
	s_nop 0
	global_load_lds_dwordx4 v[242:243], off
	s_mov_b32 m0, s70
	s_nop 0
	global_load_lds_dwordx4 v[244:245], off
	s_waitcnt vmcnt(8)
	s_waitcnt lgkmcnt(0)
	s_barrier
	s_setprio 1
	v_mfma_f32_16x16x32_bf16 v[60:63], v[138:141], v[190:193], v[60:63]
	v_mfma_f32_16x16x32_bf16 v[56:59], v[152:155], v[190:193], v[56:59]
	v_mfma_f32_16x16x32_bf16 v[44:47], v[138:141], v[198:201], v[44:47]
	v_mfma_f32_16x16x32_bf16 v[40:43], v[152:155], v[198:201], v[40:43]
	v_mfma_f32_16x16x32_bf16 v[28:31], v[138:141], v[220:223], v[28:31]
	v_mfma_f32_16x16x32_bf16 v[24:27], v[152:155], v[220:223], v[24:27]
	v_mfma_f32_16x16x32_bf16 v[12:15], v[138:141], v[232:235], v[12:15]
	v_mfma_f32_16x16x32_bf16 v[8:11], v[152:155], v[232:235], v[8:11]
	v_mfma_f32_16x16x32_bf16 v[60:63], v[148:151], v[194:197], v[60:63]
	v_mfma_f32_16x16x32_bf16 v[56:59], v[156:159], v[194:197], v[56:59]
	v_mfma_f32_16x16x32_bf16 v[44:47], v[148:151], v[202:205], v[44:47]
	v_mfma_f32_16x16x32_bf16 v[40:43], v[156:159], v[202:205], v[40:43]
	v_mfma_f32_16x16x32_bf16 v[28:31], v[148:151], v[228:231], v[28:31]
	v_mfma_f32_16x16x32_bf16 v[24:27], v[156:159], v[228:231], v[24:27]
	v_mfma_f32_16x16x32_bf16 v[12:15], v[148:151], v[236:239], v[12:15]
	v_mfma_f32_16x16x32_bf16 v[8:11], v[156:159], v[236:239], v[8:11]
	s_setprio 0
	s_setprio 1
	v_mfma_f32_16x16x32_bf16 v[52:55], v[174:177], v[190:193], v[52:55]
	v_mfma_f32_16x16x32_bf16 v[48:51], v[182:185], v[190:193], v[48:51]
	v_mfma_f32_16x16x32_bf16 v[36:39], v[174:177], v[198:201], v[36:39]
	v_mfma_f32_16x16x32_bf16 v[32:35], v[182:185], v[198:201], v[32:35]
	v_mfma_f32_16x16x32_bf16 v[20:23], v[174:177], v[220:223], v[20:23]
	v_mfma_f32_16x16x32_bf16 v[16:19], v[182:185], v[220:223], v[16:19]
	v_mfma_f32_16x16x32_bf16 v[4:7], v[174:177], v[232:235], v[4:7]
	v_mfma_f32_16x16x32_bf16 v[0:3], v[182:185], v[232:235], v[0:3]
	v_mfma_f32_16x16x32_bf16 v[52:55], v[178:181], v[194:197], v[52:55]
	v_mfma_f32_16x16x32_bf16 v[48:51], v[186:189], v[194:197], v[48:51]
	v_mfma_f32_16x16x32_bf16 v[36:39], v[178:181], v[202:205], v[36:39]
	v_mfma_f32_16x16x32_bf16 v[32:35], v[186:189], v[202:205], v[32:35]
	v_mfma_f32_16x16x32_bf16 v[20:23], v[178:181], v[228:231], v[20:23]
	v_mfma_f32_16x16x32_bf16 v[16:19], v[186:189], v[228:231], v[16:19]
	v_mfma_f32_16x16x32_bf16 v[4:7], v[178:181], v[236:239], v[4:7]
	v_mfma_f32_16x16x32_bf16 v[0:3], v[186:189], v[236:239], v[0:3]
	s_setprio 0
	s_barrier
	s_add_i32 s29, 0, 0x18000
	s_add_i32 s53, 0, 0x1c000
	v_add_u32_e32 v156, s29, v145
	v_add_u32_e32 v186, s53, v145
	ds_read_b128 v[138:141], v156
	ds_read_b128 v[148:151], v156 offset:1024
	ds_read_b128 v[152:155], v156 offset:2048
	ds_read_b128 v[156:159], v156 offset:3072
	ds_read_b128 v[174:177], v186
	ds_read_b128 v[178:181], v186 offset:1024
	ds_read_b128 v[182:185], v186 offset:2048
	ds_read_b128 v[186:189], v186 offset:3072
	s_add_u32 s30, s64, 0x40000
	s_addc_u32 s31, s65, 0
	s_mov_b32 m0, s71
	v_lshl_add_u64 v[246:247], s[30:31], 0, v[132:133]
	ds_read_b128 v[190:193], v147 offset:32768
	ds_read_b128 v[194:197], v147 offset:33792
	ds_read_b128 v[198:201], v147 offset:34816
	ds_read_b128 v[202:205], v147 offset:35840
	ds_read_b128 v[220:223], v147 offset:36864
	ds_read_b128 v[228:231], v147 offset:37888
	ds_read_b128 v[232:235], v147 offset:38912
	ds_read_b128 v[236:239], v147 offset:39936
	global_load_lds_dwordx4 v[246:247], off
	v_lshl_add_u64 v[246:247], s[30:31], 0, v[130:131]
	s_mov_b32 m0, s72
	s_nop 0
	global_load_lds_dwordx4 v[246:247], off
	s_waitcnt vmcnt(8)
	s_waitcnt lgkmcnt(0)
	s_barrier
	s_setprio 1
	v_mfma_f32_16x16x32_bf16 v[124:127], v[138:141], v[190:193], v[124:127]
	v_mfma_f32_16x16x32_bf16 v[120:123], v[152:155], v[190:193], v[120:123]
	v_mfma_f32_16x16x32_bf16 v[108:111], v[138:141], v[198:201], v[108:111]
	v_mfma_f32_16x16x32_bf16 v[104:107], v[152:155], v[198:201], v[104:107]
	v_mfma_f32_16x16x32_bf16 v[92:95], v[138:141], v[220:223], v[92:95]
	v_mfma_f32_16x16x32_bf16 v[88:91], v[152:155], v[220:223], v[88:91]
	v_mfma_f32_16x16x32_bf16 v[76:79], v[138:141], v[232:235], v[76:79]
	v_mfma_f32_16x16x32_bf16 v[72:75], v[152:155], v[232:235], v[72:75]
	v_mfma_f32_16x16x32_bf16 v[124:127], v[148:151], v[194:197], v[124:127]
	v_mfma_f32_16x16x32_bf16 v[120:123], v[156:159], v[194:197], v[120:123]
	v_mfma_f32_16x16x32_bf16 v[108:111], v[148:151], v[202:205], v[108:111]
	v_mfma_f32_16x16x32_bf16 v[104:107], v[156:159], v[202:205], v[104:107]
	v_mfma_f32_16x16x32_bf16 v[92:95], v[148:151], v[228:231], v[92:95]
	v_mfma_f32_16x16x32_bf16 v[88:91], v[156:159], v[228:231], v[88:91]
	v_mfma_f32_16x16x32_bf16 v[76:79], v[148:151], v[236:239], v[76:79]
	v_mfma_f32_16x16x32_bf16 v[72:75], v[156:159], v[236:239], v[72:75]
	s_setprio 0
	s_setprio 1
	v_mfma_f32_16x16x32_bf16 v[116:119], v[174:177], v[190:193], v[116:119]
	v_mfma_f32_16x16x32_bf16 v[112:115], v[182:185], v[190:193], v[112:115]
	v_mfma_f32_16x16x32_bf16 v[100:103], v[174:177], v[198:201], v[100:103]
	v_mfma_f32_16x16x32_bf16 v[96:99], v[182:185], v[198:201], v[96:99]
	v_mfma_f32_16x16x32_bf16 v[84:87], v[174:177], v[220:223], v[84:87]
	v_mfma_f32_16x16x32_bf16 v[80:83], v[182:185], v[220:223], v[80:83]
	v_mfma_f32_16x16x32_bf16 v[68:71], v[174:177], v[232:235], v[68:71]
	v_mfma_f32_16x16x32_bf16 v[64:67], v[182:185], v[232:235], v[64:67]
	v_mfma_f32_16x16x32_bf16 v[116:119], v[178:181], v[194:197], v[116:119]
	v_mfma_f32_16x16x32_bf16 v[112:115], v[186:189], v[194:197], v[112:115]
	v_mfma_f32_16x16x32_bf16 v[100:103], v[178:181], v[202:205], v[100:103]
	v_mfma_f32_16x16x32_bf16 v[96:99], v[186:189], v[202:205], v[96:99]
	v_mfma_f32_16x16x32_bf16 v[84:87], v[178:181], v[228:231], v[84:87]
	v_mfma_f32_16x16x32_bf16 v[80:83], v[186:189], v[228:231], v[80:83]
	v_mfma_f32_16x16x32_bf16 v[68:71], v[178:181], v[236:239], v[68:71]
	v_mfma_f32_16x16x32_bf16 v[64:67], v[186:189], v[236:239], v[64:67]
	s_setprio 0
	s_barrier
	s_add_i32 s29, s29, s68
	v_lshl_add_u64 v[142:143], v[142:143], 0, s[4:5]
	s_mov_b32 m0, s29
	ds_read_b128 v[190:193], v147 offset:49152
	ds_read_b128 v[194:197], v147 offset:50176
	ds_read_b128 v[198:201], v147 offset:51200
	ds_read_b128 v[202:205], v147 offset:52224
	ds_read_b128 v[220:223], v147 offset:53248
	ds_read_b128 v[228:231], v147 offset:54272
	ds_read_b128 v[232:235], v147 offset:55296
	ds_read_b128 v[236:239], v147 offset:56320
	global_load_lds_dwordx4 v[142:143], off
	s_add_i32 m0, s29, 0x2000
	s_add_u32 s30, s62, 0x40080
	v_lshl_add_u64 v[142:143], v[240:241], 0, s[4:5]
	s_addc_u32 s31, s63, 0
	s_add_i32 s29, s53, s68
	global_load_lds_dwordx4 v[142:143], off
	v_lshl_add_u64 v[142:143], s[30:31], 0, v[162:163]
	s_mov_b32 m0, s29
	s_nop 0
	global_load_lds_dwordx4 v[142:143], off
	v_lshl_add_u64 v[142:143], s[30:31], 0, v[128:129]
	s_add_i32 m0, s29, 0x2000
	s_nop 0
	global_load_lds_dwordx4 v[142:143], off
	v_lshl_add_u64 v[142:143], v[242:243], 0, s[4:5]
	s_mov_b32 m0, s74
	s_nop 0
	global_load_lds_dwordx4 v[142:143], off
	v_lshl_add_u64 v[142:143], v[244:245], 0, s[4:5]
	s_mov_b32 m0, s75
	s_nop 0
	global_load_lds_dwordx4 v[142:143], off
	s_waitcnt vmcnt(8)
	s_waitcnt lgkmcnt(0)
	s_barrier
	s_setprio 1
	v_mfma_f32_16x16x32_bf16 v[60:63], v[138:141], v[190:193], v[60:63]
	v_mfma_f32_16x16x32_bf16 v[56:59], v[152:155], v[190:193], v[56:59]
	v_mfma_f32_16x16x32_bf16 v[44:47], v[138:141], v[198:201], v[44:47]
	v_mfma_f32_16x16x32_bf16 v[40:43], v[152:155], v[198:201], v[40:43]
	v_mfma_f32_16x16x32_bf16 v[28:31], v[138:141], v[220:223], v[28:31]
	v_mfma_f32_16x16x32_bf16 v[24:27], v[152:155], v[220:223], v[24:27]
	v_mfma_f32_16x16x32_bf16 v[12:15], v[138:141], v[232:235], v[12:15]
	v_mfma_f32_16x16x32_bf16 v[8:11], v[152:155], v[232:235], v[8:11]
	v_mfma_f32_16x16x32_bf16 v[60:63], v[148:151], v[194:197], v[60:63]
	v_mfma_f32_16x16x32_bf16 v[56:59], v[156:159], v[194:197], v[56:59]
	v_mfma_f32_16x16x32_bf16 v[44:47], v[148:151], v[202:205], v[44:47]
	v_mfma_f32_16x16x32_bf16 v[40:43], v[156:159], v[202:205], v[40:43]
	v_mfma_f32_16x16x32_bf16 v[28:31], v[148:151], v[228:231], v[28:31]
	v_mfma_f32_16x16x32_bf16 v[24:27], v[156:159], v[228:231], v[24:27]
	v_mfma_f32_16x16x32_bf16 v[12:15], v[148:151], v[236:239], v[12:15]
	v_mfma_f32_16x16x32_bf16 v[8:11], v[156:159], v[236:239], v[8:11]
	s_setprio 0
	s_setprio 1
	v_mfma_f32_16x16x32_bf16 v[52:55], v[174:177], v[190:193], v[52:55]
	v_mfma_f32_16x16x32_bf16 v[48:51], v[182:185], v[190:193], v[48:51]
	v_mfma_f32_16x16x32_bf16 v[36:39], v[174:177], v[198:201], v[36:39]
	v_mfma_f32_16x16x32_bf16 v[32:35], v[182:185], v[198:201], v[32:35]
	v_mfma_f32_16x16x32_bf16 v[20:23], v[174:177], v[220:223], v[20:23]
	v_mfma_f32_16x16x32_bf16 v[16:19], v[182:185], v[220:223], v[16:19]
	v_mfma_f32_16x16x32_bf16 v[4:7], v[174:177], v[232:235], v[4:7]
	v_mfma_f32_16x16x32_bf16 v[0:3], v[182:185], v[232:235], v[0:3]
	v_mfma_f32_16x16x32_bf16 v[52:55], v[178:181], v[194:197], v[52:55]
	v_mfma_f32_16x16x32_bf16 v[48:51], v[186:189], v[194:197], v[48:51]
	v_mfma_f32_16x16x32_bf16 v[36:39], v[178:181], v[202:205], v[36:39]
	v_mfma_f32_16x16x32_bf16 v[32:35], v[186:189], v[202:205], v[32:35]
	v_mfma_f32_16x16x32_bf16 v[20:23], v[178:181], v[228:231], v[20:23]
	v_mfma_f32_16x16x32_bf16 v[16:19], v[186:189], v[228:231], v[16:19]
	v_mfma_f32_16x16x32_bf16 v[4:7], v[178:181], v[236:239], v[4:7]
	v_mfma_f32_16x16x32_bf16 v[0:3], v[186:189], v[236:239], v[0:3]
	s_setprio 0
	s_barrier
	s_add_i32 s28, s28, 2
	s_add_u32 s60, s60, 0x100
	s_addc_u32 s61, s61, 0
	s_add_u32 s26, s26, 0x100
	s_addc_u32 s27, s27, 0
	s_cmp_gt_u32 s28, 13
	s_cbranch_scc0 .LBB0_975
	s_and_b64 vcc, exec, s[50:51]
	s_cbranch_vccz .LBB0_978
	s_barrier

.LBB0_1066:
	s_add_u32 s29, s58, 0xfffc0080
	s_addc_u32 s30, s59, -1
	s_add_i32 s31, 0, 0x10000
	s_cmp_eq_u32 s28, 12
	s_cselect_b32 s63, s6, s30
	s_cselect_b32 s62, s7, s29
	v_add_u32_e32 v142, s31, v144
	s_cselect_b32 s61, s24, s27
	s_cselect_b32 s60, s25, s26
	s_add_i32 s29, 0, 0x14000
	ds_read_b128 v[138:141], v142
	ds_read_b128 v[148:151], v142 offset:1024
	ds_read_b128 v[152:155], v142 offset:2048
	ds_read_b128 v[156:159], v142 offset:3072
	v_add_u32_e32 v142, s29, v144
	ds_read_b128 v[174:177], v142
	ds_read_b128 v[178:181], v142 offset:1024
	ds_read_b128 v[182:185], v142 offset:2048
	ds_read_b128 v[186:189], v142 offset:3072
	v_lshl_add_u64 v[240:241], s[58:59], 0, v[134:135]
	s_add_i32 m0, s67, 0xc000
	ds_read_b128 v[190:193], v146
	ds_read_b128 v[194:197], v146 offset:1024
	ds_read_b128 v[198:201], v146 offset:2048
	ds_read_b128 v[202:205], v146 offset:3072
	ds_read_b128 v[220:223], v146 offset:4096
	ds_read_b128 v[228:231], v146 offset:5120
	ds_read_b128 v[232:235], v146 offset:6144
	ds_read_b128 v[236:239], v146 offset:7168
	global_load_lds_dwordx4 v[240:241], off
	v_lshl_add_u64 v[240:241], s[58:59], 0, v[136:137]
	s_add_i32 m0, s67, 0xe000
	s_nop 0
	global_load_lds_dwordx4 v[240:241], off
	s_waitcnt vmcnt(8)
	s_waitcnt lgkmcnt(0)
	s_barrier
	s_setprio 1
	v_mfma_f32_16x16x32_bf16 v[124:127], v[138:141], v[190:193], v[124:127]
	v_mfma_f32_16x16x32_bf16 v[120:123], v[152:155], v[190:193], v[120:123]
	v_mfma_f32_16x16x32_bf16 v[108:111], v[138:141], v[198:201], v[108:111]
	v_mfma_f32_16x16x32_bf16 v[104:107], v[152:155], v[198:201], v[104:107]
	v_mfma_f32_16x16x32_bf16 v[92:95], v[138:141], v[220:223], v[92:95]
	v_mfma_f32_16x16x32_bf16 v[88:91], v[152:155], v[220:223], v[88:91]
	v_mfma_f32_16x16x32_bf16 v[76:79], v[138:141], v[232:235], v[76:79]
	v_mfma_f32_16x16x32_bf16 v[72:75], v[152:155], v[232:235], v[72:75]
	v_mfma_f32_16x16x32_bf16 v[124:127], v[148:151], v[194:197], v[124:127]
	v_mfma_f32_16x16x32_bf16 v[120:123], v[156:159], v[194:197], v[120:123]
	v_mfma_f32_16x16x32_bf16 v[108:111], v[148:151], v[202:205], v[108:111]
	v_mfma_f32_16x16x32_bf16 v[104:107], v[156:159], v[202:205], v[104:107]
	v_mfma_f32_16x16x32_bf16 v[92:95], v[148:151], v[228:231], v[92:95]
	v_mfma_f32_16x16x32_bf16 v[88:91], v[156:159], v[228:231], v[88:91]
	v_mfma_f32_16x16x32_bf16 v[76:79], v[148:151], v[236:239], v[76:79]
	v_mfma_f32_16x16x32_bf16 v[72:75], v[156:159], v[236:239], v[72:75]
	s_setprio 0
	s_setprio 1
	v_mfma_f32_16x16x32_bf16 v[116:119], v[174:177], v[190:193], v[116:119]
	v_mfma_f32_16x16x32_bf16 v[112:115], v[182:185], v[190:193], v[112:115]
	v_mfma_f32_16x16x32_bf16 v[100:103], v[174:177], v[198:201], v[100:103]
	v_mfma_f32_16x16x32_bf16 v[96:99], v[182:185], v[198:201], v[96:99]
	v_mfma_f32_16x16x32_bf16 v[84:87], v[174:177], v[220:223], v[84:87]
	v_mfma_f32_16x16x32_bf16 v[80:83], v[182:185], v[220:223], v[80:83]
	v_mfma_f32_16x16x32_bf16 v[68:71], v[174:177], v[232:235], v[68:71]
	v_mfma_f32_16x16x32_bf16 v[64:67], v[182:185], v[232:235], v[64:67]
	v_mfma_f32_16x16x32_bf16 v[116:119], v[178:181], v[194:197], v[116:119]
	v_mfma_f32_16x16x32_bf16 v[112:115], v[186:189], v[194:197], v[112:115]
	v_mfma_f32_16x16x32_bf16 v[100:103], v[178:181], v[202:205], v[100:103]
	v_mfma_f32_16x16x32_bf16 v[96:99], v[186:189], v[202:205], v[96:99]
	v_mfma_f32_16x16x32_bf16 v[84:87], v[178:181], v[228:231], v[84:87]
	v_mfma_f32_16x16x32_bf16 v[80:83], v[186:189], v[228:231], v[80:83]
	v_mfma_f32_16x16x32_bf16 v[68:71], v[178:181], v[236:239], v[68:71]
	v_mfma_f32_16x16x32_bf16 v[64:67], v[186:189], v[236:239], v[64:67]
	s_setprio 0
	s_barrier
	s_add_i32 s30, s31, s66
	v_lshl_add_u64 v[240:241], s[60:61], 0, v[162:163]
	s_mov_b32 m0, s30
	ds_read_b128 v[190:193], v146 offset:16384
	ds_read_b128 v[194:197], v146 offset:17408
	ds_read_b128 v[198:201], v146 offset:18432
	ds_read_b128 v[202:205], v146 offset:19456
	ds_read_b128 v[220:223], v146 offset:20480
	ds_read_b128 v[228:231], v146 offset:21504
	ds_read_b128 v[232:235], v146 offset:22528
	ds_read_b128 v[236:239], v146 offset:23552
	global_load_lds_dwordx4 v[240:241], off
	s_add_i32 m0, s30, 0x2000
	s_add_u32 s30, s60, 0x40000
	v_lshl_add_u64 v[242:243], s[60:61], 0, v[128:129]
	s_addc_u32 s31, s61, 0
	s_add_i32 s29, s29, s66
	global_load_lds_dwordx4 v[242:243], off
	v_lshl_add_u64 v[244:245], s[30:31], 0, v[162:163]
	s_mov_b32 m0, s29
	v_lshl_add_u64 v[246:247], s[62:63], 0, v[130:131]
	global_load_lds_dwordx4 v[244:245], off
	v_lshl_add_u64 v[244:245], s[30:31], 0, v[128:129]
	s_add_i32 m0, s29, 0x2000
	s_nop 0
	global_load_lds_dwordx4 v[244:245], off
	v_lshl_add_u64 v[244:245], s[62:63], 0, v[132:133]
	s_mov_b32 m0, s67
	s_nop 0
	global_load_lds_dwordx4 v[244:245], off
	s_mov_b32 m0, s68
	s_nop 0
	global_load_lds_dwordx4 v[246:247], off
	s_waitcnt vmcnt(8)
	s_waitcnt lgkmcnt(0)
	s_barrier
	s_setprio 1
	v_mfma_f32_16x16x32_bf16 v[60:63], v[138:141], v[190:193], v[60:63]
	v_mfma_f32_16x16x32_bf16 v[56:59], v[152:155], v[190:193], v[56:59]
	v_mfma_f32_16x16x32_bf16 v[44:47], v[138:141], v[198:201], v[44:47]
	v_mfma_f32_16x16x32_bf16 v[40:43], v[152:155], v[198:201], v[40:43]
	v_mfma_f32_16x16x32_bf16 v[28:31], v[138:141], v[220:223], v[28:31]
	v_mfma_f32_16x16x32_bf16 v[24:27], v[152:155], v[220:223], v[24:27]
	v_mfma_f32_16x16x32_bf16 v[12:15], v[138:141], v[232:235], v[12:15]
	v_mfma_f32_16x16x32_bf16 v[8:11], v[152:155], v[232:235], v[8:11]
	v_mfma_f32_16x16x32_bf16 v[60:63], v[148:151], v[194:197], v[60:63]
	v_mfma_f32_16x16x32_bf16 v[56:59], v[156:159], v[194:197], v[56:59]
	v_mfma_f32_16x16x32_bf16 v[44:47], v[148:151], v[202:205], v[44:47]
	v_mfma_f32_16x16x32_bf16 v[40:43], v[156:159], v[202:205], v[40:43]
	v_mfma_f32_16x16x32_bf16 v[28:31], v[148:151], v[228:231], v[28:31]
	v_mfma_f32_16x16x32_bf16 v[24:27], v[156:159], v[228:231], v[24:27]
	v_mfma_f32_16x16x32_bf16 v[12:15], v[148:151], v[236:239], v[12:15]
	v_mfma_f32_16x16x32_bf16 v[8:11], v[156:159], v[236:239], v[8:11]
	s_setprio 0
	s_setprio 1
	v_mfma_f32_16x16x32_bf16 v[52:55], v[174:177], v[190:193], v[52:55]
	v_mfma_f32_16x16x32_bf16 v[48:51], v[182:185], v[190:193], v[48:51]
	v_mfma_f32_16x16x32_bf16 v[36:39], v[174:177], v[198:201], v[36:39]
	v_mfma_f32_16x16x32_bf16 v[32:35], v[182:185], v[198:201], v[32:35]
	v_mfma_f32_16x16x32_bf16 v[20:23], v[174:177], v[220:223], v[20:23]
	v_mfma_f32_16x16x32_bf16 v[16:19], v[182:185], v[220:223], v[16:19]
	v_mfma_f32_16x16x32_bf16 v[4:7], v[174:177], v[232:235], v[4:7]
	v_mfma_f32_16x16x32_bf16 v[0:3], v[182:185], v[232:235], v[0:3]
	v_mfma_f32_16x16x32_bf16 v[52:55], v[178:181], v[194:197], v[52:55]
	v_mfma_f32_16x16x32_bf16 v[48:51], v[186:189], v[194:197], v[48:51]
	v_mfma_f32_16x16x32_bf16 v[36:39], v[178:181], v[202:205], v[36:39]
	v_mfma_f32_16x16x32_bf16 v[32:35], v[186:189], v[202:205], v[32:35]
	v_mfma_f32_16x16x32_bf16 v[20:23], v[178:181], v[228:231], v[20:23]
	v_mfma_f32_16x16x32_bf16 v[16:19], v[186:189], v[228:231], v[16:19]
	v_mfma_f32_16x16x32_bf16 v[4:7], v[178:181], v[236:239], v[4:7]
	v_mfma_f32_16x16x32_bf16 v[0:3], v[186:189], v[236:239], v[0:3]
	s_setprio 0
	s_barrier
	s_add_i32 s29, 0, 0x18000
	v_add_u32_e32 v142, s29, v144
	s_add_i32 s51, 0, 0x1c000
	ds_read_b128 v[138:141], v142
	ds_read_b128 v[148:151], v142 offset:1024
	ds_read_b128 v[152:155], v142 offset:2048
	ds_read_b128 v[156:159], v142 offset:3072
	v_add_u32_e32 v142, s51, v144
	ds_read_b128 v[174:177], v142
	ds_read_b128 v[178:181], v142 offset:1024
	ds_read_b128 v[182:185], v142 offset:2048
	ds_read_b128 v[186:189], v142 offset:3072
	s_add_u32 s30, s62, 0x40000
	s_addc_u32 s31, s63, 0
	s_mov_b32 m0, s69
	v_lshl_add_u64 v[248:249], s[30:31], 0, v[132:133]
	ds_read_b128 v[190:193], v146 offset:32768
	ds_read_b128 v[194:197], v146 offset:33792
	ds_read_b128 v[198:201], v146 offset:34816
	ds_read_b128 v[202:205], v146 offset:35840
	ds_read_b128 v[220:223], v146 offset:36864
	ds_read_b128 v[228:231], v146 offset:37888
	ds_read_b128 v[232:235], v146 offset:38912
	ds_read_b128 v[236:239], v146 offset:39936
	global_load_lds_dwordx4 v[248:249], off
	v_lshl_add_u64 v[248:249], s[30:31], 0, v[130:131]
	s_mov_b32 m0, s70
	s_nop 0
	global_load_lds_dwordx4 v[248:249], off
	s_waitcnt vmcnt(8)
	s_waitcnt lgkmcnt(0)
	s_barrier
	s_setprio 1
	v_mfma_f32_16x16x32_bf16 v[124:127], v[138:141], v[190:193], v[124:127]
	v_mfma_f32_16x16x32_bf16 v[120:123], v[152:155], v[190:193], v[120:123]
	v_mfma_f32_16x16x32_bf16 v[108:111], v[138:141], v[198:201], v[108:111]
	v_mfma_f32_16x16x32_bf16 v[104:107], v[152:155], v[198:201], v[104:107]
	v_mfma_f32_16x16x32_bf16 v[92:95], v[138:141], v[220:223], v[92:95]
	v_mfma_f32_16x16x32_bf16 v[88:91], v[152:155], v[220:223], v[88:91]
	v_mfma_f32_16x16x32_bf16 v[76:79], v[138:141], v[232:235], v[76:79]
	v_mfma_f32_16x16x32_bf16 v[72:75], v[152:155], v[232:235], v[72:75]
	v_mfma_f32_16x16x32_bf16 v[124:127], v[148:151], v[194:197], v[124:127]
	v_mfma_f32_16x16x32_bf16 v[120:123], v[156:159], v[194:197], v[120:123]
	v_mfma_f32_16x16x32_bf16 v[108:111], v[148:151], v[202:205], v[108:111]
	v_mfma_f32_16x16x32_bf16 v[104:107], v[156:159], v[202:205], v[104:107]
	v_mfma_f32_16x16x32_bf16 v[92:95], v[148:151], v[228:231], v[92:95]
	v_mfma_f32_16x16x32_bf16 v[88:91], v[156:159], v[228:231], v[88:91]
	v_mfma_f32_16x16x32_bf16 v[76:79], v[148:151], v[236:239], v[76:79]
	v_mfma_f32_16x16x32_bf16 v[72:75], v[156:159], v[236:239], v[72:75]
	s_setprio 0
	s_setprio 1
	v_mfma_f32_16x16x32_bf16 v[116:119], v[174:177], v[190:193], v[116:119]
	v_mfma_f32_16x16x32_bf16 v[112:115], v[182:185], v[190:193], v[112:115]
	v_mfma_f32_16x16x32_bf16 v[100:103], v[174:177], v[198:201], v[100:103]
	v_mfma_f32_16x16x32_bf16 v[96:99], v[182:185], v[198:201], v[96:99]
	v_mfma_f32_16x16x32_bf16 v[84:87], v[174:177], v[220:223], v[84:87]
	v_mfma_f32_16x16x32_bf16 v[80:83], v[182:185], v[220:223], v[80:83]
	v_mfma_f32_16x16x32_bf16 v[68:71], v[174:177], v[232:235], v[68:71]
	v_mfma_f32_16x16x32_bf16 v[64:67], v[182:185], v[232:235], v[64:67]
	v_mfma_f32_16x16x32_bf16 v[116:119], v[178:181], v[194:197], v[116:119]
	v_mfma_f32_16x16x32_bf16 v[112:115], v[186:189], v[194:197], v[112:115]
	v_mfma_f32_16x16x32_bf16 v[100:103], v[178:181], v[202:205], v[100:103]
	v_mfma_f32_16x16x32_bf16 v[96:99], v[186:189], v[202:205], v[96:99]
	v_mfma_f32_16x16x32_bf16 v[84:87], v[178:181], v[228:231], v[84:87]
	v_mfma_f32_16x16x32_bf16 v[80:83], v[186:189], v[228:231], v[80:83]
	v_mfma_f32_16x16x32_bf16 v[68:71], v[178:181], v[236:239], v[68:71]
	v_mfma_f32_16x16x32_bf16 v[64:67], v[186:189], v[236:239], v[64:67]
	s_setprio 0
	s_barrier
	s_add_i32 s29, s29, s66
	v_lshl_add_u64 v[240:241], v[240:241], 0, s[4:5]
	s_mov_b32 m0, s29
	ds_read_b128 v[190:193], v146 offset:49152
	ds_read_b128 v[194:197], v146 offset:50176
	ds_read_b128 v[198:201], v146 offset:51200
	ds_read_b128 v[202:205], v146 offset:52224
	ds_read_b128 v[220:223], v146 offset:53248
	ds_read_b128 v[228:231], v146 offset:54272
	ds_read_b128 v[232:235], v146 offset:55296
	ds_read_b128 v[236:239], v146 offset:56320
	global_load_lds_dwordx4 v[240:241], off
	s_add_i32 m0, s29, 0x2000
	s_add_u32 s30, s60, 0x40080
	v_lshl_add_u64 v[240:241], v[242:243], 0, s[4:5]
	s_addc_u32 s31, s61, 0
	s_add_i32 s29, s51, s66
	global_load_lds_dwordx4 v[240:241], off
	v_lshl_add_u64 v[240:241], s[30:31], 0, v[162:163]
	s_mov_b32 m0, s29
	s_nop 0
	global_load_lds_dwordx4 v[240:241], off
	v_lshl_add_u64 v[240:241], s[30:31], 0, v[128:129]
	s_add_i32 m0, s29, 0x2000
	s_nop 0
	global_load_lds_dwordx4 v[240:241], off
	v_lshl_add_u64 v[240:241], v[244:245], 0, s[4:5]
	s_mov_b32 m0, s71
	s_nop 0
	global_load_lds_dwordx4 v[240:241], off
	v_lshl_add_u64 v[240:241], v[246:247], 0, s[4:5]
	s_mov_b32 m0, s72
	s_nop 0
	global_load_lds_dwordx4 v[240:241], off
	s_waitcnt vmcnt(8)
	s_waitcnt lgkmcnt(0)
	s_barrier
	s_setprio 1
	v_mfma_f32_16x16x32_bf16 v[60:63], v[138:141], v[190:193], v[60:63]
	v_mfma_f32_16x16x32_bf16 v[56:59], v[152:155], v[190:193], v[56:59]
	v_mfma_f32_16x16x32_bf16 v[44:47], v[138:141], v[198:201], v[44:47]
	v_mfma_f32_16x16x32_bf16 v[40:43], v[152:155], v[198:201], v[40:43]
	v_mfma_f32_16x16x32_bf16 v[28:31], v[138:141], v[220:223], v[28:31]
	v_mfma_f32_16x16x32_bf16 v[24:27], v[152:155], v[220:223], v[24:27]
	v_mfma_f32_16x16x32_bf16 v[12:15], v[138:141], v[232:235], v[12:15]
	v_mfma_f32_16x16x32_bf16 v[8:11], v[152:155], v[232:235], v[8:11]
	v_mfma_f32_16x16x32_bf16 v[60:63], v[148:151], v[194:197], v[60:63]
	v_mfma_f32_16x16x32_bf16 v[56:59], v[156:159], v[194:197], v[56:59]
	v_mfma_f32_16x16x32_bf16 v[44:47], v[148:151], v[202:205], v[44:47]
	v_mfma_f32_16x16x32_bf16 v[40:43], v[156:159], v[202:205], v[40:43]
	v_mfma_f32_16x16x32_bf16 v[28:31], v[148:151], v[228:231], v[28:31]
	v_mfma_f32_16x16x32_bf16 v[24:27], v[156:159], v[228:231], v[24:27]
	v_mfma_f32_16x16x32_bf16 v[12:15], v[148:151], v[236:239], v[12:15]
	v_mfma_f32_16x16x32_bf16 v[8:11], v[156:159], v[236:239], v[8:11]
	s_setprio 0
	s_setprio 1
	v_mfma_f32_16x16x32_bf16 v[52:55], v[174:177], v[190:193], v[52:55]
	v_mfma_f32_16x16x32_bf16 v[48:51], v[182:185], v[190:193], v[48:51]
	v_mfma_f32_16x16x32_bf16 v[36:39], v[174:177], v[198:201], v[36:39]
	v_mfma_f32_16x16x32_bf16 v[32:35], v[182:185], v[198:201], v[32:35]
	v_mfma_f32_16x16x32_bf16 v[20:23], v[174:177], v[220:223], v[20:23]
	v_mfma_f32_16x16x32_bf16 v[16:19], v[182:185], v[220:223], v[16:19]
	v_mfma_f32_16x16x32_bf16 v[4:7], v[174:177], v[232:235], v[4:7]
	v_mfma_f32_16x16x32_bf16 v[0:3], v[182:185], v[232:235], v[0:3]
	v_mfma_f32_16x16x32_bf16 v[52:55], v[178:181], v[194:197], v[52:55]
	v_mfma_f32_16x16x32_bf16 v[48:51], v[186:189], v[194:197], v[48:51]
	v_mfma_f32_16x16x32_bf16 v[36:39], v[178:181], v[202:205], v[36:39]
	v_mfma_f32_16x16x32_bf16 v[32:35], v[186:189], v[202:205], v[32:35]
	v_mfma_f32_16x16x32_bf16 v[20:23], v[178:181], v[228:231], v[20:23]
	v_mfma_f32_16x16x32_bf16 v[16:19], v[186:189], v[228:231], v[16:19]
	v_mfma_f32_16x16x32_bf16 v[4:7], v[178:181], v[236:239], v[4:7]
	v_mfma_f32_16x16x32_bf16 v[0:3], v[186:189], v[236:239], v[0:3]
	s_setprio 0
	s_barrier
	s_add_i32 s28, s28, 2
	s_add_u32 s58, s58, 0x100
	s_addc_u32 s59, s59, 0
	s_add_u32 s26, s26, 0x100
	s_addc_u32 s27, s27, 0
	s_cmp_gt_u32 s28, 13
	s_cbranch_scc0 .LBB0_1066
	s_and_b64 vcc, exec, s[48:49]
	s_cbranch_vccz .LBB0_1069
	s_barrier

.LBB0_1280:
	s_add_u32 s60, s58, 0x100
	s_addc_u32 s61, s59, 0
	s_add_i32 s25, 0, 0x10000
	s_cmp_eq_u32 s24, 40
	s_cselect_b32 s65, s45, s61
	s_cselect_b32 s64, s44, s60
	v_add_u32_e32 v142, s25, v145
	s_cselect_b32 s63, s57, s7
	s_cselect_b32 s62, s56, s6
	s_add_i32 s28, 0, 0x14000
	ds_read_b128 v[138:141], v142
	ds_read_b128 v[148:151], v142 offset:1024
	ds_read_b128 v[152:155], v142 offset:2048
	ds_read_b128 v[156:159], v142 offset:3072
	v_add_u32_e32 v142, s28, v145
	ds_read_b128 v[174:177], v142
	ds_read_b128 v[178:181], v142 offset:1024
	ds_read_b128 v[182:185], v142 offset:2048
	ds_read_b128 v[186:189], v142 offset:3072
	v_lshl_add_u64 v[142:143], s[58:59], 0, v[134:135]
	s_add_i32 m0, s68, 0xc000
	ds_read_b128 v[190:193], v147
	ds_read_b128 v[194:197], v147 offset:1024
	ds_read_b128 v[198:201], v147 offset:2048
	ds_read_b128 v[202:205], v147 offset:3072
	ds_read_b128 v[220:223], v147 offset:4096
	ds_read_b128 v[228:231], v147 offset:5120
	ds_read_b128 v[232:235], v147 offset:6144
	ds_read_b128 v[236:239], v147 offset:7168
	global_load_lds_dwordx4 v[142:143], off
	v_lshl_add_u64 v[142:143], s[58:59], 0, v[136:137]
	s_add_i32 m0, s68, 0xe000
	s_nop 0
	global_load_lds_dwordx4 v[142:143], off
	s_waitcnt vmcnt(8)
	s_waitcnt lgkmcnt(0)
	s_barrier
	s_setprio 1
	v_mfma_f32_16x16x32_bf16 v[124:127], v[138:141], v[190:193], v[124:127]
	v_mfma_f32_16x16x32_bf16 v[120:123], v[152:155], v[190:193], v[120:123]
	v_mfma_f32_16x16x32_bf16 v[108:111], v[138:141], v[198:201], v[108:111]
	v_mfma_f32_16x16x32_bf16 v[104:107], v[152:155], v[198:201], v[104:107]
	v_mfma_f32_16x16x32_bf16 v[92:95], v[138:141], v[220:223], v[92:95]
	v_mfma_f32_16x16x32_bf16 v[88:91], v[152:155], v[220:223], v[88:91]
	v_mfma_f32_16x16x32_bf16 v[76:79], v[138:141], v[232:235], v[76:79]
	v_mfma_f32_16x16x32_bf16 v[72:75], v[152:155], v[232:235], v[72:75]
	v_mfma_f32_16x16x32_bf16 v[124:127], v[148:151], v[194:197], v[124:127]
	v_mfma_f32_16x16x32_bf16 v[120:123], v[156:159], v[194:197], v[120:123]
	v_mfma_f32_16x16x32_bf16 v[108:111], v[148:151], v[202:205], v[108:111]
	v_mfma_f32_16x16x32_bf16 v[104:107], v[156:159], v[202:205], v[104:107]
	v_mfma_f32_16x16x32_bf16 v[92:95], v[148:151], v[228:231], v[92:95]
	v_mfma_f32_16x16x32_bf16 v[88:91], v[156:159], v[228:231], v[88:91]
	v_mfma_f32_16x16x32_bf16 v[76:79], v[148:151], v[236:239], v[76:79]
	v_mfma_f32_16x16x32_bf16 v[72:75], v[156:159], v[236:239], v[72:75]
	s_setprio 0
	s_setprio 1
	v_mfma_f32_16x16x32_bf16 v[116:119], v[174:177], v[190:193], v[116:119]
	v_mfma_f32_16x16x32_bf16 v[112:115], v[182:185], v[190:193], v[112:115]
	v_mfma_f32_16x16x32_bf16 v[100:103], v[174:177], v[198:201], v[100:103]
	v_mfma_f32_16x16x32_bf16 v[96:99], v[182:185], v[198:201], v[96:99]
	v_mfma_f32_16x16x32_bf16 v[84:87], v[174:177], v[220:223], v[84:87]
	v_mfma_f32_16x16x32_bf16 v[80:83], v[182:185], v[220:223], v[80:83]
	v_mfma_f32_16x16x32_bf16 v[68:71], v[174:177], v[232:235], v[68:71]
	v_mfma_f32_16x16x32_bf16 v[64:67], v[182:185], v[232:235], v[64:67]
	v_mfma_f32_16x16x32_bf16 v[116:119], v[178:181], v[194:197], v[116:119]
	v_mfma_f32_16x16x32_bf16 v[112:115], v[186:189], v[194:197], v[112:115]
	v_mfma_f32_16x16x32_bf16 v[100:103], v[178:181], v[202:205], v[100:103]
	v_mfma_f32_16x16x32_bf16 v[96:99], v[186:189], v[202:205], v[96:99]
	v_mfma_f32_16x16x32_bf16 v[84:87], v[178:181], v[228:231], v[84:87]
	v_mfma_f32_16x16x32_bf16 v[80:83], v[186:189], v[228:231], v[80:83]
	v_mfma_f32_16x16x32_bf16 v[68:71], v[178:181], v[236:239], v[68:71]
	v_mfma_f32_16x16x32_bf16 v[64:67], v[186:189], v[236:239], v[64:67]
	s_setprio 0
	s_barrier
	s_add_i32 s25, s25, s67
	v_lshl_add_u64 v[142:143], s[62:63], 0, v[162:163]
	s_mov_b32 m0, s25
	ds_read_b128 v[190:193], v147 offset:16384
	ds_read_b128 v[194:197], v147 offset:17408
	ds_read_b128 v[198:201], v147 offset:18432
	ds_read_b128 v[202:205], v147 offset:19456
	ds_read_b128 v[220:223], v147 offset:20480
	ds_read_b128 v[228:231], v147 offset:21504
	ds_read_b128 v[232:235], v147 offset:22528
	ds_read_b128 v[236:239], v147 offset:23552
	global_load_lds_dwordx4 v[142:143], off
	s_add_i32 m0, s25, 0x2000
	s_add_u32 s26, s62, 0xb0000
	v_lshl_add_u64 v[240:241], s[62:63], 0, v[128:129]
	s_addc_u32 s27, s63, 0
	s_add_i32 s25, s28, s67
	global_load_lds_dwordx4 v[240:241], off
	v_lshl_add_u64 v[242:243], s[26:27], 0, v[162:163]
	s_mov_b32 m0, s25
	v_lshl_add_u64 v[244:245], s[64:65], 0, v[130:131]
	global_load_lds_dwordx4 v[242:243], off
	v_lshl_add_u64 v[242:243], s[26:27], 0, v[128:129]
	s_add_i32 m0, s25, 0x2000
	s_nop 0
	global_load_lds_dwordx4 v[242:243], off
	v_lshl_add_u64 v[242:243], s[64:65], 0, v[132:133]
	s_mov_b32 m0, s68
	s_nop 0
	global_load_lds_dwordx4 v[242:243], off
	s_mov_b32 m0, s69
	s_nop 0
	global_load_lds_dwordx4 v[244:245], off
	s_waitcnt vmcnt(8)
	s_waitcnt lgkmcnt(0)
	s_barrier
	s_setprio 1
	v_mfma_f32_16x16x32_bf16 v[60:63], v[138:141], v[190:193], v[60:63]
	v_mfma_f32_16x16x32_bf16 v[56:59], v[152:155], v[190:193], v[56:59]
	v_mfma_f32_16x16x32_bf16 v[44:47], v[138:141], v[198:201], v[44:47]
	v_mfma_f32_16x16x32_bf16 v[40:43], v[152:155], v[198:201], v[40:43]
	v_mfma_f32_16x16x32_bf16 v[28:31], v[138:141], v[220:223], v[28:31]
	v_mfma_f32_16x16x32_bf16 v[24:27], v[152:155], v[220:223], v[24:27]
	v_mfma_f32_16x16x32_bf16 v[12:15], v[138:141], v[232:235], v[12:15]
	v_mfma_f32_16x16x32_bf16 v[8:11], v[152:155], v[232:235], v[8:11]
	v_mfma_f32_16x16x32_bf16 v[60:63], v[148:151], v[194:197], v[60:63]
	v_mfma_f32_16x16x32_bf16 v[56:59], v[156:159], v[194:197], v[56:59]
	v_mfma_f32_16x16x32_bf16 v[44:47], v[148:151], v[202:205], v[44:47]
	v_mfma_f32_16x16x32_bf16 v[40:43], v[156:159], v[202:205], v[40:43]
	v_mfma_f32_16x16x32_bf16 v[28:31], v[148:151], v[228:231], v[28:31]
	v_mfma_f32_16x16x32_bf16 v[24:27], v[156:159], v[228:231], v[24:27]
	v_mfma_f32_16x16x32_bf16 v[12:15], v[148:151], v[236:239], v[12:15]
	v_mfma_f32_16x16x32_bf16 v[8:11], v[156:159], v[236:239], v[8:11]
	s_setprio 0
	s_setprio 1
	v_mfma_f32_16x16x32_bf16 v[52:55], v[174:177], v[190:193], v[52:55]
	v_mfma_f32_16x16x32_bf16 v[48:51], v[182:185], v[190:193], v[48:51]
	v_mfma_f32_16x16x32_bf16 v[36:39], v[174:177], v[198:201], v[36:39]
	v_mfma_f32_16x16x32_bf16 v[32:35], v[182:185], v[198:201], v[32:35]
	v_mfma_f32_16x16x32_bf16 v[20:23], v[174:177], v[220:223], v[20:23]
	v_mfma_f32_16x16x32_bf16 v[16:19], v[182:185], v[220:223], v[16:19]
	v_mfma_f32_16x16x32_bf16 v[4:7], v[174:177], v[232:235], v[4:7]
	v_mfma_f32_16x16x32_bf16 v[0:3], v[182:185], v[232:235], v[0:3]
	v_mfma_f32_16x16x32_bf16 v[52:55], v[178:181], v[194:197], v[52:55]
	v_mfma_f32_16x16x32_bf16 v[48:51], v[186:189], v[194:197], v[48:51]
	v_mfma_f32_16x16x32_bf16 v[36:39], v[178:181], v[202:205], v[36:39]
	v_mfma_f32_16x16x32_bf16 v[32:35], v[186:189], v[202:205], v[32:35]
	v_mfma_f32_16x16x32_bf16 v[20:23], v[178:181], v[228:231], v[20:23]
	v_mfma_f32_16x16x32_bf16 v[16:19], v[186:189], v[228:231], v[16:19]
	v_mfma_f32_16x16x32_bf16 v[4:7], v[178:181], v[236:239], v[4:7]
	v_mfma_f32_16x16x32_bf16 v[0:3], v[186:189], v[236:239], v[0:3]
	s_setprio 0
	s_barrier
	s_add_i32 s25, 0, 0x18000
	s_add_i32 s28, 0, 0x1c000
	v_add_u32_e32 v156, s25, v145
	v_add_u32_e32 v186, s28, v145
	ds_read_b128 v[138:141], v156
	ds_read_b128 v[148:151], v156 offset:1024
	ds_read_b128 v[152:155], v156 offset:2048
	ds_read_b128 v[156:159], v156 offset:3072
	ds_read_b128 v[174:177], v186
	ds_read_b128 v[178:181], v186 offset:1024
	ds_read_b128 v[182:185], v186 offset:2048
	ds_read_b128 v[186:189], v186 offset:3072
	s_add_u32 s26, s64, 0xb0000
	s_addc_u32 s27, s65, 0
	s_mov_b32 m0, s70
	v_lshl_add_u64 v[246:247], s[26:27], 0, v[132:133]
	ds_read_b128 v[190:193], v147 offset:32768
	ds_read_b128 v[194:197], v147 offset:33792
	ds_read_b128 v[198:201], v147 offset:34816
	ds_read_b128 v[202:205], v147 offset:35840
	ds_read_b128 v[220:223], v147 offset:36864
	ds_read_b128 v[228:231], v147 offset:37888
	ds_read_b128 v[232:235], v147 offset:38912
	ds_read_b128 v[236:239], v147 offset:39936
	global_load_lds_dwordx4 v[246:247], off
	v_lshl_add_u64 v[246:247], s[26:27], 0, v[130:131]
	s_mov_b32 m0, s71
	s_nop 0
	global_load_lds_dwordx4 v[246:247], off
	s_waitcnt vmcnt(8)
	s_waitcnt lgkmcnt(0)
	s_barrier
	s_setprio 1
	v_mfma_f32_16x16x32_bf16 v[124:127], v[138:141], v[190:193], v[124:127]
	v_mfma_f32_16x16x32_bf16 v[120:123], v[152:155], v[190:193], v[120:123]
	v_mfma_f32_16x16x32_bf16 v[108:111], v[138:141], v[198:201], v[108:111]
	v_mfma_f32_16x16x32_bf16 v[104:107], v[152:155], v[198:201], v[104:107]
	v_mfma_f32_16x16x32_bf16 v[92:95], v[138:141], v[220:223], v[92:95]
	v_mfma_f32_16x16x32_bf16 v[88:91], v[152:155], v[220:223], v[88:91]
	v_mfma_f32_16x16x32_bf16 v[76:79], v[138:141], v[232:235], v[76:79]
	v_mfma_f32_16x16x32_bf16 v[72:75], v[152:155], v[232:235], v[72:75]
	v_mfma_f32_16x16x32_bf16 v[124:127], v[148:151], v[194:197], v[124:127]
	v_mfma_f32_16x16x32_bf16 v[120:123], v[156:159], v[194:197], v[120:123]
	v_mfma_f32_16x16x32_bf16 v[108:111], v[148:151], v[202:205], v[108:111]
	v_mfma_f32_16x16x32_bf16 v[104:107], v[156:159], v[202:205], v[104:107]
	v_mfma_f32_16x16x32_bf16 v[92:95], v[148:151], v[228:231], v[92:95]
	v_mfma_f32_16x16x32_bf16 v[88:91], v[156:159], v[228:231], v[88:91]
	v_mfma_f32_16x16x32_bf16 v[76:79], v[148:151], v[236:239], v[76:79]
	v_mfma_f32_16x16x32_bf16 v[72:75], v[156:159], v[236:239], v[72:75]
	s_setprio 0
	s_setprio 1
	v_mfma_f32_16x16x32_bf16 v[116:119], v[174:177], v[190:193], v[116:119]
	v_mfma_f32_16x16x32_bf16 v[112:115], v[182:185], v[190:193], v[112:115]
	v_mfma_f32_16x16x32_bf16 v[100:103], v[174:177], v[198:201], v[100:103]
	v_mfma_f32_16x16x32_bf16 v[96:99], v[182:185], v[198:201], v[96:99]
	v_mfma_f32_16x16x32_bf16 v[84:87], v[174:177], v[220:223], v[84:87]
	v_mfma_f32_16x16x32_bf16 v[80:83], v[182:185], v[220:223], v[80:83]
	v_mfma_f32_16x16x32_bf16 v[68:71], v[174:177], v[232:235], v[68:71]
	v_mfma_f32_16x16x32_bf16 v[64:67], v[182:185], v[232:235], v[64:67]
	v_mfma_f32_16x16x32_bf16 v[116:119], v[178:181], v[194:197], v[116:119]
	v_mfma_f32_16x16x32_bf16 v[112:115], v[186:189], v[194:197], v[112:115]
	v_mfma_f32_16x16x32_bf16 v[100:103], v[178:181], v[202:205], v[100:103]
	v_mfma_f32_16x16x32_bf16 v[96:99], v[186:189], v[202:205], v[96:99]
	v_mfma_f32_16x16x32_bf16 v[84:87], v[178:181], v[228:231], v[84:87]
	v_mfma_f32_16x16x32_bf16 v[80:83], v[186:189], v[228:231], v[80:83]
	v_mfma_f32_16x16x32_bf16 v[68:71], v[178:181], v[236:239], v[68:71]
	v_mfma_f32_16x16x32_bf16 v[64:67], v[186:189], v[236:239], v[64:67]
	s_setprio 0
	s_barrier
	s_add_i32 s25, s25, s67
	v_lshl_add_u64 v[142:143], v[142:143], 0, s[4:5]
	s_mov_b32 m0, s25
	ds_read_b128 v[190:193], v147 offset:49152
	ds_read_b128 v[194:197], v147 offset:50176
	ds_read_b128 v[198:201], v147 offset:51200
	ds_read_b128 v[202:205], v147 offset:52224
	ds_read_b128 v[220:223], v147 offset:53248
	ds_read_b128 v[228:231], v147 offset:54272
	ds_read_b128 v[232:235], v147 offset:55296
	ds_read_b128 v[236:239], v147 offset:56320
	global_load_lds_dwordx4 v[142:143], off
	s_add_i32 m0, s25, 0x2000
	s_add_u32 s26, s62, 0xb0080
	v_lshl_add_u64 v[142:143], v[240:241], 0, s[4:5]
	s_addc_u32 s27, s63, 0
	s_add_i32 s25, s28, s67
	global_load_lds_dwordx4 v[142:143], off
	v_lshl_add_u64 v[142:143], s[26:27], 0, v[162:163]
	s_mov_b32 m0, s25
	s_nop 0
	global_load_lds_dwordx4 v[142:143], off
	v_lshl_add_u64 v[142:143], s[26:27], 0, v[128:129]
	s_add_i32 m0, s25, 0x2000
	s_nop 0
	global_load_lds_dwordx4 v[142:143], off
	v_lshl_add_u64 v[142:143], v[242:243], 0, s[4:5]
	s_mov_b32 m0, s73
	s_nop 0
	global_load_lds_dwordx4 v[142:143], off
	v_lshl_add_u64 v[142:143], v[244:245], 0, s[4:5]
	s_mov_b32 m0, s74
	s_nop 0
	global_load_lds_dwordx4 v[142:143], off
	s_waitcnt vmcnt(8)
	s_waitcnt lgkmcnt(0)
	s_barrier
	s_setprio 1
	v_mfma_f32_16x16x32_bf16 v[60:63], v[138:141], v[190:193], v[60:63]
	v_mfma_f32_16x16x32_bf16 v[56:59], v[152:155], v[190:193], v[56:59]
	v_mfma_f32_16x16x32_bf16 v[44:47], v[138:141], v[198:201], v[44:47]
	v_mfma_f32_16x16x32_bf16 v[40:43], v[152:155], v[198:201], v[40:43]
	v_mfma_f32_16x16x32_bf16 v[28:31], v[138:141], v[220:223], v[28:31]
	v_mfma_f32_16x16x32_bf16 v[24:27], v[152:155], v[220:223], v[24:27]
	v_mfma_f32_16x16x32_bf16 v[12:15], v[138:141], v[232:235], v[12:15]
	v_mfma_f32_16x16x32_bf16 v[8:11], v[152:155], v[232:235], v[8:11]
	v_mfma_f32_16x16x32_bf16 v[60:63], v[148:151], v[194:197], v[60:63]
	v_mfma_f32_16x16x32_bf16 v[56:59], v[156:159], v[194:197], v[56:59]
	v_mfma_f32_16x16x32_bf16 v[44:47], v[148:151], v[202:205], v[44:47]
	v_mfma_f32_16x16x32_bf16 v[40:43], v[156:159], v[202:205], v[40:43]
	v_mfma_f32_16x16x32_bf16 v[28:31], v[148:151], v[228:231], v[28:31]
	v_mfma_f32_16x16x32_bf16 v[24:27], v[156:159], v[228:231], v[24:27]
	v_mfma_f32_16x16x32_bf16 v[12:15], v[148:151], v[236:239], v[12:15]
	v_mfma_f32_16x16x32_bf16 v[8:11], v[156:159], v[236:239], v[8:11]
	s_setprio 0
	s_setprio 1
	v_mfma_f32_16x16x32_bf16 v[52:55], v[174:177], v[190:193], v[52:55]
	v_mfma_f32_16x16x32_bf16 v[48:51], v[182:185], v[190:193], v[48:51]
	v_mfma_f32_16x16x32_bf16 v[36:39], v[174:177], v[198:201], v[36:39]
	v_mfma_f32_16x16x32_bf16 v[32:35], v[182:185], v[198:201], v[32:35]
	v_mfma_f32_16x16x32_bf16 v[20:23], v[174:177], v[220:223], v[20:23]
	v_mfma_f32_16x16x32_bf16 v[16:19], v[182:185], v[220:223], v[16:19]
	v_mfma_f32_16x16x32_bf16 v[4:7], v[174:177], v[232:235], v[4:7]
	v_mfma_f32_16x16x32_bf16 v[0:3], v[182:185], v[232:235], v[0:3]
	v_mfma_f32_16x16x32_bf16 v[52:55], v[178:181], v[194:197], v[52:55]
	v_mfma_f32_16x16x32_bf16 v[48:51], v[186:189], v[194:197], v[48:51]
	v_mfma_f32_16x16x32_bf16 v[36:39], v[178:181], v[202:205], v[36:39]
	v_mfma_f32_16x16x32_bf16 v[32:35], v[186:189], v[202:205], v[32:35]
	v_mfma_f32_16x16x32_bf16 v[20:23], v[178:181], v[228:231], v[20:23]
	v_mfma_f32_16x16x32_bf16 v[16:19], v[186:189], v[228:231], v[16:19]
	v_mfma_f32_16x16x32_bf16 v[4:7], v[178:181], v[236:239], v[4:7]
	v_mfma_f32_16x16x32_bf16 v[0:3], v[186:189], v[236:239], v[0:3]
	s_setprio 0
	s_barrier
	s_add_i32 s24, s24, 2
	s_add_u32 s6, s6, 0x100
	s_addc_u32 s7, s7, 0
	s_cmp_gt_u32 s24, 41
	s_mov_b64 s[58:59], s[60:61]
	s_cbranch_scc0 .LBB0_1280
	s_and_b64 vcc, exec, s[54:55]
	s_cbranch_vccz .LBB0_1283
	s_barrier
